# K/V LDS-DMA issue moved from the QK/PV boundary into late VALU-only PV MFMA gaps (VM2: after PV MFMA 9-11, VM1: after 6-7); on top of v18
# baseline (speedup 1.0000x reference)
.LBB0_863:
	v_mfma_f32_32x32x16_bf16 v[112:127], v[100:103], v[218:221], 0
	v_lshl_add_u32 v206, s89, 1, v168
	ds_read_b64_tr_b16 v[194:195], v206 offset:24576
	ds_read_b64_tr_b16 v[196:197], v206 offset:25088
	v_add_f32_e32 v108, v80, v81
	v_add_f32_e32 v108, v82, v108
	v_add_f32_e32 v108, v83, v108
	v_add_f32_e32 v108, v84, v108
	v_add_f32_e32 v108, v85, v108
	v_cvt_pk_bf16_f32 v156, v80, v81
	v_cvt_pk_bf16_f32 v157, v82, v83
	ds_read_b64_tr_b16 v[80:81], v206 offset:28672
	ds_read_b64_tr_b16 v[82:83], v206 offset:29184
	v_add_f32_e32 v104, v86, v108
	v_add_f32_e32 v104, v87, v104
	v_add_f32_e32 v104, v88, v104
	v_add_f32_e32 v144, v89, v104
	v_mfma_f32_32x32x16_bf16 v[96:111], v[96:99], v[218:221], 0
	v_cvt_pk_bf16_f32 v158, v84, v85
	v_cvt_pk_bf16_f32 v159, v86, v87
	ds_read_b64_tr_b16 v[84:85], v206 offset:25600
	ds_read_b64_tr_b16 v[86:87], v206 offset:26112
	v_add_f32_e32 v144, v90, v144
	v_add_f32_e32 v144, v91, v144
	v_add_f32_e32 v144, v92, v144
	v_add_f32_e32 v144, v93, v144
	v_cvt_pk_bf16_f32 v152, v88, v89
	v_cvt_pk_bf16_f32 v153, v90, v91
	v_mfma_f32_32x32x16_bf16 v[112:127], v[164:167], v[222:225], v[112:127]
	ds_read_b64_tr_b16 v[88:89], v206 offset:29696
	ds_read_b64_tr_b16 v[90:91], v206 offset:30208
	v_add_f32_e32 v144, v94, v144
	v_add_f32_e32 v144, v95, v144
	v_add_f32_e32 v144, v64, v144
	v_add_f32_e32 v144, v65, v144
	v_mfma_f32_32x32x16_bf16 v[96:111], v[160:163], v[222:225], v[96:111]
	v_cvt_pk_bf16_f32 v154, v92, v93
	v_cvt_pk_bf16_f32 v155, v94, v95
	ds_read_b64_tr_b16 v[92:93], v206 offset:26624
	ds_read_b64_tr_b16 v[94:95], v206 offset:27136
	v_add_f32_e32 v144, v66, v144
	v_add_f32_e32 v144, v67, v144
	v_add_f32_e32 v144, v68, v144
	v_add_f32_e32 v144, v69, v144
	v_cvt_pk_bf16_f32 v148, v64, v65
	v_cvt_pk_bf16_f32 v149, v66, v67
	v_mfma_f32_32x32x16_bf16 v[112:127], v[140:143], v[226:229], v[112:127]
	ds_read_b64_tr_b16 v[198:199], v206 offset:30720
	ds_read_b64_tr_b16 v[200:201], v206 offset:31232
	v_add_f32_e32 v140, v70, v144
	v_add_f32_e32 v140, v71, v140
	v_add_f32_e32 v140, v72, v140
	v_add_f32_e32 v140, v73, v140
	v_mfma_f32_32x32x16_bf16 v[96:111], v[136:139], v[226:229], v[96:111]
	v_cvt_pk_bf16_f32 v150, v68, v69
	v_cvt_pk_bf16_f32 v151, v70, v71
	ds_read_b64_tr_b16 v[202:203], v206 offset:27648
	ds_read_b64_tr_b16 v[204:205], v206 offset:28160
	v_add_f32_e32 v68, v74, v140
	v_add_f32_e32 v68, v75, v68
	v_add_f32_e32 v68, v76, v68
	v_add_f32_e32 v68, v77, v68
	v_cvt_pk_bf16_f32 v144, v72, v73
	v_cvt_pk_bf16_f32 v145, v74, v75
	v_mfma_f32_32x32x16_bf16 v[112:127], v[132:135], v[230:233], v[112:127]
	ds_read_b64_tr_b16 v[72:73], v206 offset:31744
	ds_read_b64_tr_b16 v[74:75], v206 offset:32256
	v_add_f32_e32 v68, v78, v68
	v_add_f32_e32 v68, v79, v68
	v_add_f32_e32 v68, 0, v68
	v_cvt_pk_bf16_f32 v146, v76, v77
	v_mfma_f32_32x32x16_bf16 v[96:111], v[128:131], v[230:233], v[96:111]
	v_cvt_pk_bf16_f32 v147, v78, v79
	v_add_f32_e32 v193, v193, v68
	s_waitcnt lgkmcnt(12)
	v_mfma_f32_32x32x16_bf16 v[48:63], v[156:159], v[194:197], v[48:63]
	ds_read_b64_tr_b16 v[76:77], v206 offset:32768
	ds_read_b64_tr_b16 v[78:79], v206 offset:33280
	v_exp_f32_e32 v112, v112
	v_exp_f32_e32 v113, v113
	v_mfma_f32_32x32x16_bf16 v[32:47], v[156:159], v[80:83], v[32:47]
	ds_read_b64_tr_b16 v[194:195], v206 offset:36864
	ds_read_b64_tr_b16 v[196:197], v206 offset:37376
	v_exp_f32_e32 v114, v114
	v_exp_f32_e32 v115, v115
	v_add_u32_e32 v242, s86, v234
	v_add_u32_e32 v243, s86, v235
	v_add_u32_e32 v244, s86, v236
	v_add_u32_e32 v245, s86, v237
	ds_read_b128 v[68:71], v242
	ds_read_b128 v[64:67], v242 offset:4096
	s_waitcnt lgkmcnt(14)
	v_mfma_f32_32x32x16_bf16 v[48:63], v[152:155], v[84:87], v[48:63]
	ds_read_b64_tr_b16 v[80:81], v206 offset:33792
	ds_read_b64_tr_b16 v[82:83], v206 offset:34304
	v_exp_f32_e32 v116, v116
	v_exp_f32_e32 v117, v117
	ds_read_b128 v[164:167], v243
	ds_read_b128 v[140:143], v243 offset:4096
	v_mfma_f32_32x32x16_bf16 v[32:47], v[152:155], v[88:91], v[32:47]
	ds_read_b64_tr_b16 v[84:85], v206 offset:37888
	ds_read_b64_tr_b16 v[86:87], v206 offset:38400
	v_exp_f32_e32 v118, v118
	v_exp_f32_e32 v119, v119
	ds_read_b128 v[160:163], v244
	ds_read_b128 v[132:135], v244 offset:4096
	s_waitcnt lgkmcnt(14)
	v_mfma_f32_32x32x16_bf16 v[48:63], v[148:151], v[92:95], v[48:63]
	ds_read_b64_tr_b16 v[88:89], v206 offset:34816
	ds_read_b64_tr_b16 v[90:91], v206 offset:35328
	v_exp_f32_e32 v120, v120
	v_exp_f32_e32 v121, v121
	ds_read_b128 v[136:139], v245
	ds_read_b128 v[128:131], v245 offset:4096
	v_mfma_f32_32x32x16_bf16 v[32:47], v[148:151], v[198:201], v[32:47]
	ds_read_b64_tr_b16 v[92:93], v206 offset:38912
	ds_read_b64_tr_b16 v[94:95], v206 offset:39424
	v_exp_f32_e32 v122, v122
	v_exp_f32_e32 v123, v123
	s_waitcnt lgkmcnt(14)
	v_mfma_f32_32x32x16_bf16 v[48:63], v[144:147], v[202:205], v[48:63]
	ds_read_b64_tr_b16 v[198:199], v206 offset:35840
	ds_read_b64_tr_b16 v[200:201], v206 offset:36352
	v_exp_f32_e32 v124, v124
	v_exp_f32_e32 v125, v125
	v_mfma_f32_32x32x16_bf16 v[32:47], v[144:147], v[72:75], v[32:47]
	ds_read_b64_tr_b16 v[202:203], v206 offset:39936
	ds_read_b64_tr_b16 v[204:205], v206 offset:40448
	v_exp_f32_e32 v126, v126
	v_exp_f32_e32 v127, v127
	s_waitcnt lgkmcnt(14)
	v_mfma_f32_32x32x16_bf16 v[16:31], v[156:159], v[76:79], v[16:31]
	s_add_i32 s88, s87, s35
	v_lshl_add_u64 v[238:239], v[180:181], 0, s[54:55]
	s_mov_b32 s89, m0
	s_mov_b32 m0, s88
	s_nop 0
	global_load_lds_dwordx4 v[238:239], off
	s_mov_b32 m0, s89
	v_exp_f32_e32 v96, v96
	v_exp_f32_e32 v97, v97
	v_mfma_f32_32x32x16_bf16 v[0:15], v[156:159], v[194:197], v[0:15]
	s_lshl_b32 s88, s86, 1
	v_lshl_add_u64 v[238:239], v[178:179], 0, s[54:55]
	s_add_i32 s88, s88, s16
	s_mov_b32 s89, m0
	s_mov_b32 m0, s88
	s_nop 0
	global_load_lds_dwordx4 v[238:239], off
	s_mov_b32 m0, s89
	v_exp_f32_e32 v98, v98
	v_exp_f32_e32 v99, v99
	v_mfma_f32_32x32x16_bf16 v[16:31], v[152:155], v[80:83], v[16:31]
	v_lshl_add_u64 v[238:239], v[176:177], 0, s[54:55]
	s_addk_i32 s88, 0x2000
	s_mov_b32 s89, m0
	s_mov_b32 m0, s88
	s_nop 0
	global_load_lds_dwordx4 v[238:239], off
	s_mov_b32 m0, s89
	v_exp_f32_e32 v100, v100
	v_exp_f32_e32 v101, v101
	s_waitcnt lgkmcnt(12)
	v_mfma_f32_32x32x16_bf16 v[0:15], v[152:155], v[84:87], v[0:15]
	v_exp_f32_e32 v102, v102
	v_exp_f32_e32 v103, v103
	s_waitcnt lgkmcnt(8)
	v_mfma_f32_32x32x16_bf16 v[16:31], v[148:151], v[88:91], v[16:31]
	v_exp_f32_e32 v104, v104
	v_exp_f32_e32 v105, v105
	s_waitcnt lgkmcnt(4)
	v_mfma_f32_32x32x16_bf16 v[0:15], v[148:151], v[92:95], v[0:15]
	v_exp_f32_e32 v106, v106
	v_exp_f32_e32 v107, v107
	s_waitcnt lgkmcnt(2)
	v_mfma_f32_32x32x16_bf16 v[16:31], v[144:147], v[198:201], v[16:31]
	v_exp_f32_e32 v108, v108
	v_exp_f32_e32 v109, v109
	s_waitcnt lgkmcnt(0)
	v_mfma_f32_32x32x16_bf16 v[0:15], v[144:147], v[202:205], v[0:15]
	v_exp_f32_e32 v110, v110
	v_exp_f32_e32 v111, v111
	s_waitcnt vmcnt(3) lgkmcnt(0)
	s_barrier
; #define WAIT_BAR(N) asm volatile("s_waitcnt vmcnt(" #N ") lgkmcnt(0)\n\ts_barrier":::"memory")
;   #define RESC() do{ if(!NOMAX&&resc){ asm volatile("s_waitcnt lgkmcnt(0)":::"memory"); \
;       _Pragma("unroll") for(int d_=0;d_<2*VM;++d_) _Pragma("unroll") for(int r=0;r<16;++r)o[d_][r]*=wsf[crow(r,hi)]; } }while(0)
;   #define ROT() do{sl_prev=sl_cur;sl_cur=sl_next;sl_next=(sl_next==(NSLOT-1)*SLOTB)?0:sl_next+SLOTB;}while(0)
; template<int THRL,int VM,bool NOMAX> __device__ __forceinline__ void attn_unit(const bf16*Qb,const bf16*__restrict__ Kh,const bf16*__restrict__ Vh,bf16*Ob,const int NT,const int sp,float*wscr,char*shm){
;     ...
;   int t=1;
;   for(;t+5<NT;t+=2){
;     STEP(pB0,pB1,pA0,pA1,t,true,true,true);     if constexpr(VM==2){WAIT_BAR(3);}else{WAIT_BAR(2);} RESC(); ROT();
;     STEP(pA0,pA1,pB0,pB1,t+1,true,true,true);   if constexpr(VM==2){WAIT_BAR(3);}else{WAIT_BAR(2);} RESC(); ROT();
;   }
	v_mfma_f32_32x32x16_bf16 v[80:95], v[68:71], v[218:221], 0
	s_add_i32 s88, s86, 0x2000
	s_cmpk_lg_i32 s86, 0x4000
	s_cselect_b32 s88, s88, 0
	v_lshl_add_u32 v206, s87, 1, v168
	ds_read_b64_tr_b16 v[194:195], v206 offset:24576
	ds_read_b64_tr_b16 v[196:197], v206 offset:25088
	v_add_f32_e32 v76, v112, v113
	v_add_f32_e32 v76, v114, v76
	v_add_f32_e32 v76, v115, v76
	v_add_f32_e32 v76, v116, v76
	v_add_f32_e32 v76, v117, v76
	v_cvt_pk_bf16_f32 v156, v112, v113
	v_cvt_pk_bf16_f32 v157, v114, v115
	ds_read_b64_tr_b16 v[112:113], v206 offset:28672
	ds_read_b64_tr_b16 v[114:115], v206 offset:29184
	v_add_f32_e32 v72, v118, v76
	v_add_f32_e32 v72, v119, v72
	v_add_f32_e32 v72, v120, v72
	v_add_f32_e32 v144, v121, v72
	v_mfma_f32_32x32x16_bf16 v[64:79], v[64:67], v[218:221], 0
	v_cvt_pk_bf16_f32 v158, v116, v117
	v_cvt_pk_bf16_f32 v159, v118, v119
	ds_read_b64_tr_b16 v[116:117], v206 offset:25600
	ds_read_b64_tr_b16 v[118:119], v206 offset:26112
	v_add_f32_e32 v144, v122, v144
	v_add_f32_e32 v144, v123, v144
	v_add_f32_e32 v144, v124, v144
	v_add_f32_e32 v144, v125, v144
	v_mfma_f32_32x32x16_bf16 v[80:95], v[164:167], v[222:225], v[80:95]
	v_cvt_pk_bf16_f32 v152, v120, v121
	v_cvt_pk_bf16_f32 v153, v122, v123
	ds_read_b64_tr_b16 v[120:121], v206 offset:29696
	ds_read_b64_tr_b16 v[122:123], v206 offset:30208
	v_add_f32_e32 v144, v126, v144
	v_add_f32_e32 v144, v127, v144
	v_add_f32_e32 v144, v96, v144
	v_add_f32_e32 v144, v97, v144
	v_mfma_f32_32x32x16_bf16 v[64:79], v[140:143], v[222:225], v[64:79]
	v_cvt_pk_bf16_f32 v154, v124, v125
	v_cvt_pk_bf16_f32 v155, v126, v127
	ds_read_b64_tr_b16 v[124:125], v206 offset:26624
	ds_read_b64_tr_b16 v[126:127], v206 offset:27136
	v_add_f32_e32 v144, v98, v144
	v_add_f32_e32 v144, v99, v144
	v_add_f32_e32 v144, v100, v144
	v_add_f32_e32 v144, v101, v144
	v_mfma_f32_32x32x16_bf16 v[80:95], v[160:163], v[226:229], v[80:95]
	v_cvt_pk_bf16_f32 v148, v96, v97
	v_cvt_pk_bf16_f32 v149, v98, v99
	ds_read_b64_tr_b16 v[198:199], v206 offset:30720
	ds_read_b64_tr_b16 v[200:201], v206 offset:31232
	v_add_f32_e32 v140, v102, v144
	v_add_f32_e32 v140, v103, v140
	v_add_f32_e32 v140, v104, v140
	v_add_f32_e32 v140, v105, v140
	v_mfma_f32_32x32x16_bf16 v[64:79], v[132:135], v[226:229], v[64:79]
	v_cvt_pk_bf16_f32 v150, v100, v101
	v_cvt_pk_bf16_f32 v151, v102, v103
	ds_read_b64_tr_b16 v[202:203], v206 offset:27648
	ds_read_b64_tr_b16 v[204:205], v206 offset:28160
	v_add_f32_e32 v100, v106, v140
	v_add_f32_e32 v100, v107, v100
	v_add_f32_e32 v100, v108, v100
	v_add_f32_e32 v100, v109, v100
	v_mfma_f32_32x32x16_bf16 v[80:95], v[136:139], v[230:233], v[80:95]
	v_cvt_pk_bf16_f32 v144, v104, v105
	v_cvt_pk_bf16_f32 v145, v106, v107
	ds_read_b64_tr_b16 v[104:105], v206 offset:31744
	ds_read_b64_tr_b16 v[106:107], v206 offset:32256
	v_add_f32_e32 v100, v110, v100
	v_add_f32_e32 v100, v111, v100
	v_add_f32_e32 v100, 0, v100
	v_cvt_pk_bf16_f32 v146, v108, v109
	v_mfma_f32_32x32x16_bf16 v[64:79], v[128:131], v[230:233], v[64:79]
	v_cvt_pk_bf16_f32 v147, v110, v111
	v_add_f32_e32 v193, v193, v100
	s_waitcnt lgkmcnt(12)
	v_mfma_f32_32x32x16_bf16 v[48:63], v[156:159], v[194:197], v[48:63]
	ds_read_b64_tr_b16 v[108:109], v206 offset:32768
	ds_read_b64_tr_b16 v[110:111], v206 offset:33280
	v_exp_f32_e32 v80, v80
	v_exp_f32_e32 v81, v81
	v_mfma_f32_32x32x16_bf16 v[32:47], v[156:159], v[112:115], v[32:47]
	ds_read_b64_tr_b16 v[194:195], v206 offset:36864
	ds_read_b64_tr_b16 v[196:197], v206 offset:37376
	v_exp_f32_e32 v82, v82
	v_exp_f32_e32 v83, v83
	v_add_u32_e32 v242, s88, v234
	v_add_u32_e32 v243, s88, v235
	v_add_u32_e32 v244, s88, v236
	v_add_u32_e32 v245, s88, v237
	ds_read_b128 v[100:103], v242
	ds_read_b128 v[96:99], v242 offset:4096
	s_waitcnt lgkmcnt(14)
	v_mfma_f32_32x32x16_bf16 v[48:63], v[152:155], v[116:119], v[48:63]
	ds_read_b64_tr_b16 v[112:113], v206 offset:33792
	ds_read_b64_tr_b16 v[114:115], v206 offset:34304
	v_exp_f32_e32 v84, v84
	v_exp_f32_e32 v85, v85
	ds_read_b128 v[164:167], v243
	ds_read_b128 v[160:163], v243 offset:4096
	v_mfma_f32_32x32x16_bf16 v[32:47], v[152:155], v[120:123], v[32:47]
	ds_read_b64_tr_b16 v[116:117], v206 offset:37888
	ds_read_b64_tr_b16 v[118:119], v206 offset:38400
	v_exp_f32_e32 v86, v86
	v_exp_f32_e32 v87, v87
	ds_read_b128 v[140:143], v244
	ds_read_b128 v[136:139], v244 offset:4096
	s_waitcnt lgkmcnt(14)
	v_mfma_f32_32x32x16_bf16 v[48:63], v[148:151], v[124:127], v[48:63]
	ds_read_b64_tr_b16 v[120:121], v206 offset:34816
	ds_read_b64_tr_b16 v[122:123], v206 offset:35328
	v_exp_f32_e32 v88, v88
	v_exp_f32_e32 v89, v89
	ds_read_b128 v[132:135], v245
	ds_read_b128 v[128:131], v245 offset:4096
	v_mfma_f32_32x32x16_bf16 v[32:47], v[148:151], v[198:201], v[32:47]
	ds_read_b64_tr_b16 v[124:125], v206 offset:38912
	ds_read_b64_tr_b16 v[126:127], v206 offset:39424
	v_exp_f32_e32 v90, v90
	v_exp_f32_e32 v91, v91
	s_waitcnt lgkmcnt(14)
	v_mfma_f32_32x32x16_bf16 v[48:63], v[144:147], v[202:205], v[48:63]
	ds_read_b64_tr_b16 v[198:199], v206 offset:35840
	ds_read_b64_tr_b16 v[200:201], v206 offset:36352
	v_exp_f32_e32 v92, v92
	v_exp_f32_e32 v93, v93
	v_mfma_f32_32x32x16_bf16 v[32:47], v[144:147], v[104:107], v[32:47]
	ds_read_b64_tr_b16 v[202:203], v206 offset:39936
	ds_read_b64_tr_b16 v[204:205], v206 offset:40448
	v_exp_f32_e32 v94, v94
	v_exp_f32_e32 v95, v95
	s_waitcnt lgkmcnt(14)
	v_mfma_f32_32x32x16_bf16 v[16:31], v[156:159], v[108:111], v[16:31]
	s_add_i32 s87, s86, s35
	s_mov_b32 s89, m0
	s_mov_b32 m0, s87
	s_nop 0
	global_load_lds_dwordx4 v[180:181], off
	s_mov_b32 m0, s89
	v_exp_f32_e32 v64, v64
	v_exp_f32_e32 v65, v65
	v_mfma_f32_32x32x16_bf16 v[0:15], v[156:159], v[194:197], v[0:15]
	s_lshl_b32 s87, s88, 1
	s_add_i32 s87, s87, s16
	s_mov_b32 s89, m0
	s_mov_b32 m0, s87
	s_nop 0
	global_load_lds_dwordx4 v[178:179], off
	s_mov_b32 m0, s89
	v_exp_f32_e32 v66, v66
	v_exp_f32_e32 v67, v67
	v_mfma_f32_32x32x16_bf16 v[16:31], v[152:155], v[112:115], v[16:31]
	s_addk_i32 s87, 0x2000
	s_mov_b32 s89, m0
	s_mov_b32 m0, s87
	s_nop 0
	global_load_lds_dwordx4 v[176:177], off
	s_mov_b32 m0, s89
	v_exp_f32_e32 v68, v68
	v_exp_f32_e32 v69, v69
	s_waitcnt lgkmcnt(12)
	v_mfma_f32_32x32x16_bf16 v[0:15], v[152:155], v[116:119], v[0:15]
	v_exp_f32_e32 v70, v70
	v_exp_f32_e32 v71, v71
	s_waitcnt lgkmcnt(8)
	v_mfma_f32_32x32x16_bf16 v[16:31], v[148:151], v[120:123], v[16:31]
	v_exp_f32_e32 v72, v72
	v_exp_f32_e32 v73, v73
	s_waitcnt lgkmcnt(4)
	v_mfma_f32_32x32x16_bf16 v[0:15], v[148:151], v[124:127], v[0:15]
	v_exp_f32_e32 v74, v74
	v_exp_f32_e32 v75, v75
	s_waitcnt lgkmcnt(2)
	v_mfma_f32_32x32x16_bf16 v[16:31], v[144:147], v[198:201], v[16:31]
	v_exp_f32_e32 v76, v76
	v_exp_f32_e32 v77, v77
	s_waitcnt lgkmcnt(0)
	v_mfma_f32_32x32x16_bf16 v[0:15], v[144:147], v[202:205], v[0:15]
	v_exp_f32_e32 v78, v78
	v_exp_f32_e32 v79, v79
	s_add_i32 s90, s88, 0x2000
	s_waitcnt vmcnt(3) lgkmcnt(0)
	s_barrier
; #define WAIT_BAR(N) asm volatile("s_waitcnt vmcnt(" #N ") lgkmcnt(0)\n\ts_barrier":::"memory")
;   #define RESC() do{ if(!NOMAX&&resc){ asm volatile("s_waitcnt lgkmcnt(0)":::"memory"); \
;       _Pragma("unroll") for(int d_=0;d_<2*VM;++d_) _Pragma("unroll") for(int r=0;r<16;++r)o[d_][r]*=wsf[crow(r,hi)]; } }while(0)
;   #define ROT() do{sl_prev=sl_cur;sl_cur=sl_next;sl_next=(sl_next==(NSLOT-1)*SLOTB)?0:sl_next+SLOTB;}while(0)
;   #define ENDW(tt) do{ if((tt)+3<NT){ if constexpr(VM==2){WAIT_BAR(3);}else{WAIT_BAR(2);} } else if((tt)+2<NT){ if constexpr(VM==2){WAIT_BAR(2);}else{WAIT_BAR(1);} } else {WAIT_BAR(0);} }while(0)
; template<int THRL,int VM,bool NOMAX> __device__ __forceinline__ void attn_unit(const bf16*Qb,const bf16*__restrict__ Kh,const bf16*__restrict__ Vh,bf16*Ob,const int NT,const int sp,float*wscr,char*shm){
;     ...
;   int t=1;
;   for(;t+5<NT;t+=2){
;     STEP(pB0,pB1,pA0,pA1,t,true,true,true);     if constexpr(VM==2){WAIT_BAR(3);}else{WAIT_BAR(2);} RESC(); ROT();
;     STEP(pA0,pA1,pB0,pB1,t+1,true,true,true);   if constexpr(VM==2){WAIT_BAR(3);}else{WAIT_BAR(2);} RESC(); ROT();
;   }
;     ...
;   for(;t+1<NT;t+=2){
;     STEP(pB0,pB1,pA0,pA1,t,(t+3<NT),(t+1<NT),(t+1<NT));       ENDW(t);   RESC(); ROT();
;     STEP(pA0,pA1,pB0,pB1,t+1,(t+4<NT),(t+2<NT),(t+2<NT));     ENDW(t+1); RESC(); ROT();
	s_cmpk_lg_i32 s88, 0x4000
	s_mov_b32 s89, s86
	s_cselect_b32 s86, s90, 0
	s_add_i32 s85, s85, 2
	v_lshl_add_u64 v[176:177], v[176:177], 0, s[56:57]
	v_lshl_add_u64 v[178:179], v[178:179], 0, s[56:57]
	v_lshl_add_u64 v[180:181], v[180:181], 0, s[56:57]
	s_mov_b32 s87, s88
	s_cmpk_lt_u32 s85, 0x79
	s_cbranch_scc1 .LBB0_863
	s_and_b32 s34, s34, 0x3fffffc0
	s_lshl_b32 s34, s34, 2
	s_add_i32 s34, s34, 0
	s_add_i32 s34, s34, 0x12000
	s_cmp_lg_u32 0, -1
	s_cselect_b32 s85, 0, 0
	s_add_i32 s86, s85, 0x6000
	v_add_u32_e32 v104, s86, v191
	v_add3_u32 v176, v104, v190, v192
	v_add_u32_e32 v177, 0x6000, v168
	ds_read_b64_tr_b16 v[178:179], v168 offset:57344
	ds_read_b64_tr_b16 v[180:181], v168 offset:57856
	v_add_f32_e32 v108, v80, v81
	ds_read_b128 v[104:107], v188
	v_add_f32_e32 v108, v82, v108
	v_add_f32_e32 v108, v83, v108
	v_add_f32_e32 v108, v84, v108
	v_add_f32_e32 v108, v85, v108
	v_cvt_pk_bf16_f32 v156, v80, v81
	v_cvt_pk_bf16_f32 v157, v82, v83
	s_waitcnt lgkmcnt(0)
	v_mfma_f32_32x32x16_bf16 v[112:127], v[100:103], v[104:107], 0
	ds_read_b64_tr_b16 v[80:81], v168 offset:61440
	ds_read_b64_tr_b16 v[82:83], v168 offset:61952
	ds_read_b128 v[100:103], v188
	v_add_f32_e32 v104, v86, v108
	v_add_f32_e32 v104, v87, v104
	v_add_f32_e32 v104, v88, v104
	v_add_f32_e32 v144, v89, v104
	v_cvt_pk_bf16_f32 v158, v84, v85
	v_cvt_pk_bf16_f32 v159, v86, v87
	s_waitcnt lgkmcnt(0)
	v_mfma_f32_32x32x16_bf16 v[96:111], v[96:99], v[100:103], 0
	ds_read_b64_tr_b16 v[84:85], v168 offset:58368
	ds_read_b64_tr_b16 v[86:87], v168 offset:58880
	ds_read_b128 v[194:197], v188 offset:1024
	v_add_f32_e32 v144, v90, v144
	v_add_f32_e32 v144, v91, v144
	v_add_f32_e32 v144, v92, v144
	v_add_f32_e32 v144, v93, v144
	v_cvt_pk_bf16_f32 v152, v88, v89
	v_cvt_pk_bf16_f32 v153, v90, v91
	s_waitcnt lgkmcnt(0)
	v_mfma_f32_32x32x16_bf16 v[112:127], v[164:167], v[194:197], v[112:127]
	ds_read_b64_tr_b16 v[88:89], v168 offset:62464
	ds_read_b64_tr_b16 v[90:91], v168 offset:62976
	ds_read_b128 v[164:167], v188 offset:1024
	v_add_f32_e32 v144, v94, v144
	v_add_f32_e32 v144, v95, v144
	v_add_f32_e32 v144, v64, v144
	v_add_f32_e32 v144, v65, v144
	v_cvt_pk_bf16_f32 v154, v92, v93
	v_cvt_pk_bf16_f32 v155, v94, v95
	s_waitcnt lgkmcnt(0)
	v_mfma_f32_32x32x16_bf16 v[96:111], v[160:163], v[164:167], v[96:111]
	ds_read_b64_tr_b16 v[194:195], v168 offset:59392
	ds_read_b64_tr_b16 v[196:197], v168 offset:59904
	ds_read_b128 v[92:95], v188 offset:2048
	v_add_f32_e32 v144, v66, v144
	v_add_f32_e32 v144, v67, v144
	v_add_f32_e32 v144, v68, v144
	v_add_f32_e32 v144, v69, v144
	v_cvt_pk_bf16_f32 v148, v64, v65
	v_cvt_pk_bf16_f32 v149, v66, v67
	s_waitcnt lgkmcnt(0)
	v_mfma_f32_32x32x16_bf16 v[112:127], v[140:143], v[92:95], v[112:127]
	ds_read_b64_tr_b16 v[140:141], v168 offset:63488
	ds_read_b64_tr_b16 v[142:143], v168 offset:64000
	ds_read_b128 v[64:67], v188 offset:2048
	v_add_f32_e32 v92, v70, v144
	v_add_f32_e32 v92, v71, v92
	v_add_f32_e32 v92, v72, v92
	v_add_f32_e32 v92, v73, v92
	v_cvt_pk_bf16_f32 v150, v68, v69
	v_cvt_pk_bf16_f32 v151, v70, v71
	s_waitcnt lgkmcnt(0)
	v_mfma_f32_32x32x16_bf16 v[96:111], v[136:139], v[64:67], v[96:111]
	ds_read_b64_tr_b16 v[136:137], v168 offset:60416
	ds_read_b64_tr_b16 v[138:139], v168 offset:60928
	ds_read_b128 v[64:67], v188 offset:3072
	v_add_f32_e32 v68, v74, v92
	v_add_f32_e32 v68, v75, v68
	v_add_f32_e32 v68, v76, v68
	v_add_f32_e32 v68, v77, v68
	v_cvt_pk_bf16_f32 v144, v72, v73
	v_cvt_pk_bf16_f32 v145, v74, v75
	s_waitcnt lgkmcnt(0)
	v_mfma_f32_32x32x16_bf16 v[112:127], v[132:135], v[64:67], v[112:127]
	ds_read_b64_tr_b16 v[72:73], v168 offset:64512
	ds_read_b64_tr_b16 v[74:75], v168 offset:65024
	ds_read_b128 v[64:67], v188 offset:3072
	v_add_f32_e32 v68, v78, v68
	v_add_f32_e32 v68, v79, v68
	v_add_f32_e32 v68, 0, v68
	v_cvt_pk_bf16_f32 v146, v76, v77
	v_cvt_pk_bf16_f32 v147, v78, v79
	s_waitcnt lgkmcnt(0)
	v_mfma_f32_32x32x16_bf16 v[96:111], v[128:131], v[64:67], v[96:111]
	v_lshl_add_u64 v[64:65], v[174:175], 0, s[58:59]
	s_mov_b32 s86, m0
	s_mov_b32 m0, s35
	s_nop 0
	global_load_lds_dwordx4 v[64:65], off
	s_mov_b32 m0, s86
	s_add_i32 s85, s85, s17
	v_lshl_add_u64 v[64:65], v[170:171], 0, s[60:61]
	s_add_i32 s17, s85, 0xa000
	s_mov_b32 s35, m0
	s_mov_b32 m0, s17
	s_nop 0
	global_load_lds_dwordx4 v[64:65], off
	s_mov_b32 m0, s35
	v_lshl_add_u64 v[64:65], v[172:173], 0, s[60:61]
	s_add_i32 s35, s17, 0x2000
	s_mov_b32 s86, m0
	s_mov_b32 m0, s35
	s_nop 0
	global_load_lds_dwordx4 v[64:65], off
	s_mov_b32 m0, s86
	v_add_f32_e32 v198, v193, v68
	v_mfma_f32_32x32x16_bf16 v[48:63], v[156:159], v[178:181], v[48:63]
	ds_read_b64_tr_b16 v[76:77], v177 offset:40960
	ds_read_b64_tr_b16 v[78:79], v177 offset:41472
	v_exp_f32_e32 v112, v112
	v_exp_f32_e32 v113, v113
	v_mfma_f32_32x32x16_bf16 v[32:47], v[156:159], v[80:83], v[32:47]
	ds_read_b64_tr_b16 v[128:129], v177 offset:45056
	ds_read_b64_tr_b16 v[130:131], v177 offset:45568
	v_exp_f32_e32 v114, v114
	v_exp_f32_e32 v115, v115
	ds_read_b128 v[68:71], v234 offset:8192
	ds_read_b128 v[64:67], v234 offset:12288
	v_mfma_f32_32x32x16_bf16 v[48:63], v[152:155], v[84:87], v[48:63]
	ds_read_b64_tr_b16 v[132:133], v177 offset:41984
	ds_read_b64_tr_b16 v[134:135], v177 offset:42496
	v_exp_f32_e32 v116, v116
	v_exp_f32_e32 v117, v117
	ds_read_b128 v[164:167], v235 offset:8192
	ds_read_b128 v[92:95], v235 offset:12288
	v_mfma_f32_32x32x16_bf16 v[32:47], v[152:155], v[88:91], v[32:47]
	ds_read_b64_tr_b16 v[178:179], v177 offset:46080
	ds_read_b64_tr_b16 v[180:181], v177 offset:46592
	v_exp_f32_e32 v118, v118
	v_exp_f32_e32 v119, v119
	ds_read_b128 v[160:163], v236 offset:8192
	ds_read_b128 v[84:87], v236 offset:12288
	v_mfma_f32_32x32x16_bf16 v[48:63], v[148:151], v[194:197], v[48:63]
	ds_read_b64_tr_b16 v[190:191], v177 offset:43008
	ds_read_b64_tr_b16 v[192:193], v177 offset:43520
	v_exp_f32_e32 v120, v120
	v_exp_f32_e32 v121, v121
	ds_read_b128 v[88:91], v237 offset:8192
	ds_read_b128 v[80:83], v237 offset:12288
	v_mfma_f32_32x32x16_bf16 v[32:47], v[148:151], v[140:143], v[32:47]
	ds_read_b64_tr_b16 v[194:195], v177 offset:47104
	ds_read_b64_tr_b16 v[196:197], v177 offset:47616
	v_exp_f32_e32 v122, v122
	v_exp_f32_e32 v123, v123
	v_mfma_f32_32x32x16_bf16 v[48:63], v[144:147], v[136:139], v[48:63]
	ds_read_b64_tr_b16 v[140:141], v177 offset:44032
	ds_read_b64_tr_b16 v[142:143], v177 offset:44544
	v_exp_f32_e32 v124, v124
	v_exp_f32_e32 v125, v125
	v_mfma_f32_32x32x16_bf16 v[32:47], v[144:147], v[72:75], v[32:47]
	ds_read_b64_tr_b16 v[136:137], v177 offset:48128
	ds_read_b64_tr_b16 v[138:139], v177 offset:48640
	v_exp_f32_e32 v126, v126
	v_exp_f32_e32 v127, v127
	s_waitcnt lgkmcnt(14)
	v_mfma_f32_32x32x16_bf16 v[16:31], v[156:159], v[76:79], v[16:31]
	v_exp_f32_e32 v96, v96
	v_exp_f32_e32 v97, v97
	v_mfma_f32_32x32x16_bf16 v[0:15], v[156:159], v[128:131], v[0:15]
	v_exp_f32_e32 v98, v98
	v_exp_f32_e32 v99, v99
	v_mfma_f32_32x32x16_bf16 v[16:31], v[152:155], v[132:135], v[16:31]
	v_exp_f32_e32 v100, v100
	v_exp_f32_e32 v101, v101
	s_waitcnt lgkmcnt(12)
	v_mfma_f32_32x32x16_bf16 v[0:15], v[152:155], v[178:181], v[0:15]
	v_exp_f32_e32 v102, v102
	v_exp_f32_e32 v103, v103
	s_waitcnt lgkmcnt(8)
	v_mfma_f32_32x32x16_bf16 v[16:31], v[148:151], v[190:193], v[16:31]
	v_exp_f32_e32 v104, v104
	v_exp_f32_e32 v105, v105
	s_waitcnt lgkmcnt(4)
	v_mfma_f32_32x32x16_bf16 v[0:15], v[148:151], v[194:197], v[0:15]
	v_exp_f32_e32 v106, v106
	v_exp_f32_e32 v107, v107
	s_waitcnt lgkmcnt(2)
	v_mfma_f32_32x32x16_bf16 v[16:31], v[144:147], v[140:143], v[16:31]
	v_exp_f32_e32 v108, v108
	v_exp_f32_e32 v109, v109
	s_waitcnt lgkmcnt(0)
	v_mfma_f32_32x32x16_bf16 v[0:15], v[144:147], v[136:139], v[0:15]
	v_exp_f32_e32 v110, v110
	v_exp_f32_e32 v111, v111
	s_waitcnt vmcnt(3) lgkmcnt(0)
	s_barrier
	ds_read_b64_tr_b16 v[178:179], v168 offset:24576
	ds_read_b64_tr_b16 v[180:181], v168 offset:25088
	v_add_f32_e32 v76, v112, v113
	ds_read_b128 v[72:75], v188
	v_add_f32_e32 v76, v114, v76
	v_add_f32_e32 v76, v115, v76
	v_add_f32_e32 v76, v116, v76
	v_add_f32_e32 v76, v117, v76
	v_cvt_pk_bf16_f32 v156, v112, v113
	v_cvt_pk_bf16_f32 v157, v114, v115
	s_waitcnt lgkmcnt(0)
	v_mfma_f32_32x32x16_bf16 v[128:143], v[68:71], v[72:75], 0
	ds_read_b64_tr_b16 v[112:113], v168 offset:28672
	ds_read_b64_tr_b16 v[114:115], v168 offset:29184
	ds_read_b128 v[68:71], v188
	v_add_f32_e32 v72, v118, v76
	v_add_f32_e32 v72, v119, v72
	v_add_f32_e32 v72, v120, v72
	v_add_f32_e32 v144, v121, v72
	s_waitcnt lgkmcnt(0)
	v_mfma_f32_32x32x16_bf16 v[64:79], v[64:67], v[68:71], 0
	v_cvt_pk_bf16_f32 v158, v116, v117
	v_cvt_pk_bf16_f32 v159, v118, v119
	ds_read_b64_tr_b16 v[116:117], v168 offset:25600
	ds_read_b64_tr_b16 v[118:119], v168 offset:26112
	ds_read_b128 v[190:193], v188 offset:1024
	v_add_f32_e32 v144, v122, v144
	v_add_f32_e32 v144, v123, v144
	v_add_f32_e32 v144, v124, v144
	v_add_f32_e32 v144, v125, v144
	v_cvt_pk_bf16_f32 v152, v120, v121
	v_cvt_pk_bf16_f32 v153, v122, v123
	s_waitcnt lgkmcnt(0)
	v_mfma_f32_32x32x16_bf16 v[128:143], v[164:167], v[190:193], v[128:143]
	ds_read_b64_tr_b16 v[120:121], v168 offset:29696
	ds_read_b64_tr_b16 v[122:123], v168 offset:30208
	ds_read_b128 v[164:167], v188 offset:1024
	v_add_f32_e32 v144, v126, v144
	v_add_f32_e32 v144, v127, v144
	v_add_f32_e32 v144, v96, v144
	v_add_f32_e32 v144, v97, v144
	s_waitcnt lgkmcnt(0)
	v_mfma_f32_32x32x16_bf16 v[64:79], v[92:95], v[164:167], v[64:79]
	v_cvt_pk_bf16_f32 v154, v124, v125
	v_cvt_pk_bf16_f32 v155, v126, v127
	ds_read_b64_tr_b16 v[92:93], v168 offset:26624
	ds_read_b64_tr_b16 v[94:95], v168 offset:27136
	ds_read_b128 v[124:127], v188 offset:2048
	v_add_f32_e32 v144, v98, v144
	v_add_f32_e32 v144, v99, v144
	v_add_f32_e32 v144, v100, v144
	v_add_f32_e32 v144, v101, v144
	v_cvt_pk_bf16_f32 v148, v96, v97
	v_cvt_pk_bf16_f32 v149, v98, v99
	s_waitcnt lgkmcnt(0)
	v_mfma_f32_32x32x16_bf16 v[128:143], v[160:163], v[124:127], v[128:143]
	ds_read_b64_tr_b16 v[96:97], v168 offset:30720
	ds_read_b64_tr_b16 v[98:99], v168 offset:31232
	ds_read_b128 v[124:127], v188 offset:2048
	v_add_f32_e32 v144, v102, v144
	v_add_f32_e32 v144, v103, v144
	v_add_f32_e32 v144, v104, v144
	v_add_f32_e32 v144, v105, v144
	s_waitcnt lgkmcnt(0)
	v_mfma_f32_32x32x16_bf16 v[64:79], v[84:87], v[124:127], v[64:79]
	v_cvt_pk_bf16_f32 v150, v100, v101
	v_cvt_pk_bf16_f32 v151, v102, v103
	ds_read_b64_tr_b16 v[100:101], v168 offset:27648
	ds_read_b64_tr_b16 v[102:103], v168 offset:28160
	ds_read_b128 v[84:87], v188 offset:3072
	v_add_f32_e32 v124, v106, v144
	v_add_f32_e32 v124, v107, v124
	v_add_f32_e32 v124, v108, v124
	v_add_f32_e32 v124, v109, v124
	v_cvt_pk_bf16_f32 v144, v104, v105
	v_cvt_pk_bf16_f32 v145, v106, v107
	s_waitcnt lgkmcnt(0)
	v_mfma_f32_32x32x16_bf16 v[128:143], v[88:91], v[84:87], v[128:143]
	ds_read_b64_tr_b16 v[88:89], v168 offset:31744
	ds_read_b64_tr_b16 v[90:91], v168 offset:32256
	ds_read_b128 v[84:87], v188 offset:3072
	v_add_f32_e32 v104, v110, v124
	v_add_f32_e32 v104, v111, v104
	v_add_f32_e32 v104, 0, v104
	v_cvt_pk_bf16_f32 v146, v108, v109
	s_waitcnt lgkmcnt(0)
	v_mfma_f32_32x32x16_bf16 v[64:79], v[80:83], v[84:87], v[64:79]
	v_cvt_pk_bf16_f32 v147, v110, v111
	v_lshl_add_u64 v[80:81], v[174:175], 0, s[62:63]
	s_add_i32 s86, s85, 0x2000
	s_mov_b32 s87, m0
	s_mov_b32 m0, s86
	s_nop 0
	global_load_lds_dwordx4 v[80:81], off
	s_mov_b32 m0, s87
	v_lshl_add_u64 v[80:81], v[170:171], 0, s[64:65]
	s_add_i32 s86, s85, 0xe000
	s_mov_b32 s87, m0
	s_mov_b32 m0, s86
	s_nop 0
	global_load_lds_dwordx4 v[80:81], off
	s_mov_b32 m0, s87
	v_lshl_add_u64 v[80:81], v[172:173], 0, s[64:65]
	s_add_i32 s85, s85, 0x10000
	s_mov_b32 s86, m0
	s_mov_b32 m0, s85
	s_nop 0
	global_load_lds_dwordx4 v[80:81], off
	s_mov_b32 m0, s86
	v_add_f32_e32 v198, v198, v104
	v_mfma_f32_32x32x16_bf16 v[48:63], v[156:159], v[178:181], v[48:63]
	ds_read_b64_tr_b16 v[104:105], v168 offset:32768
	ds_read_b64_tr_b16 v[106:107], v168 offset:33280
	v_exp_f32_e32 v128, v128
	v_exp_f32_e32 v129, v129
	v_mfma_f32_32x32x16_bf16 v[32:47], v[156:159], v[112:115], v[32:47]
	ds_read_b64_tr_b16 v[108:109], v168 offset:36864
	ds_read_b64_tr_b16 v[110:111], v168 offset:37376
	v_exp_f32_e32 v130, v130
	v_exp_f32_e32 v131, v131
	ds_read_b128 v[84:87], v234 offset:16384
	ds_read_b128 v[80:83], v234 offset:20480
	v_mfma_f32_32x32x16_bf16 v[48:63], v[152:155], v[116:119], v[48:63]
	ds_read_b64_tr_b16 v[178:179], v168 offset:33792
	ds_read_b64_tr_b16 v[180:181], v168 offset:34304
	v_exp_f32_e32 v132, v132
	v_exp_f32_e32 v133, v133
	ds_read_b128 v[164:167], v235 offset:16384
	ds_read_b128 v[124:127], v235 offset:20480
	v_mfma_f32_32x32x16_bf16 v[32:47], v[152:155], v[120:123], v[32:47]
	ds_read_b64_tr_b16 v[190:191], v168 offset:37888
	ds_read_b64_tr_b16 v[192:193], v168 offset:38400
	v_exp_f32_e32 v134, v134
	v_exp_f32_e32 v135, v135
	ds_read_b128 v[160:163], v236 offset:16384
	ds_read_b128 v[116:119], v236 offset:20480
	v_mfma_f32_32x32x16_bf16 v[48:63], v[148:151], v[92:95], v[48:63]
	ds_read_b64_tr_b16 v[194:195], v168 offset:34816
	ds_read_b64_tr_b16 v[196:197], v168 offset:35328
	v_exp_f32_e32 v136, v136
	v_exp_f32_e32 v137, v137
	ds_read_b128 v[120:123], v237 offset:16384
	ds_read_b128 v[112:115], v237 offset:20480
	v_mfma_f32_32x32x16_bf16 v[32:47], v[148:151], v[96:99], v[32:47]
	ds_read_b64_tr_b16 v[92:93], v168 offset:38912
	ds_read_b64_tr_b16 v[94:95], v168 offset:39424
	v_exp_f32_e32 v138, v138
	v_exp_f32_e32 v139, v139
	v_mfma_f32_32x32x16_bf16 v[48:63], v[144:147], v[100:103], v[48:63]
	ds_read_b64_tr_b16 v[96:97], v168 offset:35840
	ds_read_b64_tr_b16 v[98:99], v168 offset:36352
	v_exp_f32_e32 v140, v140
	v_exp_f32_e32 v141, v141
	v_mfma_f32_32x32x16_bf16 v[32:47], v[144:147], v[88:91], v[32:47]
	ds_read_b64_tr_b16 v[100:101], v168 offset:39936
	ds_read_b64_tr_b16 v[102:103], v168 offset:40448
	v_exp_f32_e32 v142, v142
	v_exp_f32_e32 v143, v143
	s_waitcnt lgkmcnt(14)
	v_mfma_f32_32x32x16_bf16 v[16:31], v[156:159], v[104:107], v[16:31]
	v_exp_f32_e32 v64, v64
	v_exp_f32_e32 v65, v65
	v_mfma_f32_32x32x16_bf16 v[0:15], v[156:159], v[108:111], v[0:15]
	v_exp_f32_e32 v66, v66
	v_exp_f32_e32 v67, v67
	v_mfma_f32_32x32x16_bf16 v[16:31], v[152:155], v[178:181], v[16:31]
	v_exp_f32_e32 v68, v68
	v_exp_f32_e32 v69, v69
	s_waitcnt lgkmcnt(12)
	v_mfma_f32_32x32x16_bf16 v[0:15], v[152:155], v[190:193], v[0:15]
	v_exp_f32_e32 v70, v70
	v_exp_f32_e32 v71, v71
	s_waitcnt lgkmcnt(8)
	v_mfma_f32_32x32x16_bf16 v[16:31], v[148:151], v[194:197], v[16:31]
	v_exp_f32_e32 v72, v72
	v_exp_f32_e32 v73, v73
	s_waitcnt lgkmcnt(4)
	v_mfma_f32_32x32x16_bf16 v[0:15], v[148:151], v[92:95], v[0:15]
	v_exp_f32_e32 v74, v74
	v_exp_f32_e32 v75, v75
	s_waitcnt lgkmcnt(2)
	v_mfma_f32_32x32x16_bf16 v[16:31], v[144:147], v[96:99], v[16:31]
	v_exp_f32_e32 v76, v76
	v_exp_f32_e32 v77, v77
	s_waitcnt lgkmcnt(0)
	v_mfma_f32_32x32x16_bf16 v[0:15], v[144:147], v[100:103], v[0:15]
	v_exp_f32_e32 v78, v78
	v_exp_f32_e32 v79, v79
	s_waitcnt vmcnt(3) lgkmcnt(0)
	s_barrier
	ds_read_b64_tr_b16 v[178:179], v168 offset:40960
	ds_read_b64_tr_b16 v[180:181], v168 offset:41472
	v_add_f32_e32 v92, v128, v129
	ds_read_b128 v[88:91], v188
	v_add_f32_e32 v92, v130, v92
	v_add_f32_e32 v92, v131, v92
	v_add_f32_e32 v92, v132, v92
	v_add_f32_e32 v92, v133, v92
	v_cvt_pk_bf16_f32 v156, v128, v129
	v_cvt_pk_bf16_f32 v157, v130, v131
	s_waitcnt lgkmcnt(0)
	v_mfma_f32_32x32x16_bf16 v[96:111], v[84:87], v[88:91], 0
	ds_read_b64_tr_b16 v[128:129], v168 offset:45056
	ds_read_b64_tr_b16 v[130:131], v168 offset:45568
	ds_read_b128 v[84:87], v188
	v_add_f32_e32 v88, v134, v92
	v_add_f32_e32 v88, v135, v88
	v_add_f32_e32 v88, v136, v88
	v_add_f32_e32 v144, v137, v88
	v_cvt_pk_bf16_f32 v158, v132, v133
	v_cvt_pk_bf16_f32 v159, v134, v135
	s_waitcnt lgkmcnt(0)
	v_mfma_f32_32x32x16_bf16 v[80:95], v[80:83], v[84:87], 0
	ds_read_b64_tr_b16 v[132:133], v168 offset:41984
	ds_read_b64_tr_b16 v[134:135], v168 offset:42496
	ds_read_b128 v[190:193], v188 offset:1024
	v_add_f32_e32 v144, v138, v144
	v_add_f32_e32 v144, v139, v144
	v_add_f32_e32 v144, v140, v144
	v_add_f32_e32 v144, v141, v144
	v_cvt_pk_bf16_f32 v152, v136, v137
	v_cvt_pk_bf16_f32 v153, v138, v139
	s_waitcnt lgkmcnt(0)
	v_mfma_f32_32x32x16_bf16 v[96:111], v[164:167], v[190:193], v[96:111]
	ds_read_b64_tr_b16 v[136:137], v168 offset:46080
	ds_read_b64_tr_b16 v[138:139], v168 offset:46592
	ds_read_b128 v[164:167], v188 offset:1024
	v_add_f32_e32 v144, v142, v144
	v_add_f32_e32 v144, v143, v144
	v_add_f32_e32 v144, v64, v144
	v_add_f32_e32 v144, v65, v144
	v_cvt_pk_bf16_f32 v154, v140, v141
	v_cvt_pk_bf16_f32 v155, v142, v143
	s_waitcnt lgkmcnt(0)
	v_mfma_f32_32x32x16_bf16 v[80:95], v[124:127], v[164:167], v[80:95]
	ds_read_b64_tr_b16 v[124:125], v168 offset:43008
	ds_read_b64_tr_b16 v[126:127], v168 offset:43520
	ds_read_b128 v[140:143], v188 offset:2048
	v_add_f32_e32 v144, v66, v144
	v_add_f32_e32 v144, v67, v144
	v_add_f32_e32 v144, v68, v144
	v_add_f32_e32 v144, v69, v144
	v_cvt_pk_bf16_f32 v148, v64, v65
	v_cvt_pk_bf16_f32 v149, v66, v67
	s_waitcnt lgkmcnt(0)
	v_mfma_f32_32x32x16_bf16 v[96:111], v[160:163], v[140:143], v[96:111]
	ds_read_b64_tr_b16 v[190:191], v168 offset:47104
	ds_read_b64_tr_b16 v[192:193], v168 offset:47616
	ds_read_b128 v[64:67], v188 offset:2048
	v_add_f32_e32 v140, v70, v144
	v_add_f32_e32 v140, v71, v140
	v_add_f32_e32 v140, v72, v140
	v_add_f32_e32 v140, v73, v140
	v_cvt_pk_bf16_f32 v150, v68, v69
	v_cvt_pk_bf16_f32 v151, v70, v71
	s_waitcnt lgkmcnt(0)
	v_mfma_f32_32x32x16_bf16 v[80:95], v[116:119], v[64:67], v[80:95]
	ds_read_b64_tr_b16 v[116:117], v168 offset:44032
	ds_read_b64_tr_b16 v[118:119], v168 offset:44544
	ds_read_b128 v[64:67], v188 offset:3072
	v_add_f32_e32 v68, v74, v140
	v_add_f32_e32 v68, v75, v68
	v_add_f32_e32 v68, v76, v68
	v_add_f32_e32 v68, v77, v68
	v_cvt_pk_bf16_f32 v144, v72, v73
	v_cvt_pk_bf16_f32 v145, v74, v75
	s_waitcnt lgkmcnt(0)
	v_mfma_f32_32x32x16_bf16 v[96:111], v[120:123], v[64:67], v[96:111]
	ds_read_b64_tr_b16 v[72:73], v168 offset:48128
	ds_read_b64_tr_b16 v[74:75], v168 offset:48640
	ds_read_b128 v[64:67], v188 offset:3072
	v_add_f32_e32 v68, v78, v68
	v_add_f32_e32 v68, v79, v68
	v_add_f32_e32 v68, 0, v68
	v_cvt_pk_bf16_f32 v146, v76, v77
	v_cvt_pk_bf16_f32 v147, v78, v79
	s_waitcnt lgkmcnt(0)
	v_mfma_f32_32x32x16_bf16 v[80:95], v[112:115], v[64:67], v[80:95]
	v_lshl_add_u64 v[64:65], v[170:171], 0, s[58:59]
	s_mov_b32 s85, m0
	s_mov_b32 m0, s16
	s_nop 0
	global_load_lds_dwordx4 v[64:65], off
	s_mov_b32 m0, s85
	v_lshl_add_u64 v[64:65], v[172:173], 0, s[58:59]
	s_addk_i32 s16, 0x2000
	s_mov_b32 s85, m0
	s_mov_b32 m0, s16
	s_nop 0
	global_load_lds_dwordx4 v[64:65], off
	s_mov_b32 m0, s85
	v_add_f32_e32 v174, v198, v68
	v_mfma_f32_32x32x16_bf16 v[48:63], v[156:159], v[178:181], v[48:63]
	ds_read_b64_tr_b16 v[76:77], v168 offset:49152
	ds_read_b64_tr_b16 v[78:79], v168 offset:49664
	v_exp_f32_e32 v96, v96
	v_exp_f32_e32 v97, v97
	v_mfma_f32_32x32x16_bf16 v[32:47], v[156:159], v[128:131], v[32:47]
	ds_read_b64_tr_b16 v[112:113], v168 offset:53248
	ds_read_b64_tr_b16 v[114:115], v168 offset:53760
	v_exp_f32_e32 v98, v98
	v_exp_f32_e32 v99, v99
	ds_read_b128 v[68:71], v234
	ds_read_b128 v[64:67], v234 offset:4096
	v_mfma_f32_32x32x16_bf16 v[48:63], v[152:155], v[132:135], v[48:63]
	ds_read_b64_tr_b16 v[120:121], v168 offset:50176
	ds_read_b64_tr_b16 v[122:123], v168 offset:50688
	v_exp_f32_e32 v100, v100
	v_exp_f32_e32 v101, v101
	ds_read_b128 v[164:167], v235
	ds_read_b128 v[140:143], v235 offset:4096
	v_mfma_f32_32x32x16_bf16 v[32:47], v[152:155], v[136:139], v[32:47]
	ds_read_b64_tr_b16 v[178:179], v168 offset:54272
	ds_read_b64_tr_b16 v[180:181], v168 offset:54784
	v_exp_f32_e32 v102, v102
	v_exp_f32_e32 v103, v103
	ds_read_b128 v[160:163], v236
	ds_read_b128 v[132:135], v236 offset:4096
	v_mfma_f32_32x32x16_bf16 v[48:63], v[148:151], v[124:127], v[48:63]
	ds_read_b64_tr_b16 v[194:195], v168 offset:51200
	ds_read_b64_tr_b16 v[196:197], v168 offset:51712
	v_exp_f32_e32 v104, v104
	v_exp_f32_e32 v105, v105
	ds_read_b128 v[136:139], v237
	ds_read_b128 v[128:131], v237 offset:4096
	v_mfma_f32_32x32x16_bf16 v[32:47], v[148:151], v[190:193], v[32:47]
	ds_read_b64_tr_b16 v[124:125], v168 offset:55296
	ds_read_b64_tr_b16 v[126:127], v168 offset:55808
	v_exp_f32_e32 v106, v106
	v_exp_f32_e32 v107, v107
	v_mfma_f32_32x32x16_bf16 v[48:63], v[144:147], v[116:119], v[48:63]
	ds_read_b64_tr_b16 v[190:191], v168 offset:52224
	ds_read_b64_tr_b16 v[192:193], v168 offset:52736
	v_exp_f32_e32 v108, v108
	v_exp_f32_e32 v109, v109
	v_mfma_f32_32x32x16_bf16 v[32:47], v[144:147], v[72:75], v[32:47]
	ds_read_b64_tr_b16 v[116:117], v168 offset:56320
	ds_read_b64_tr_b16 v[118:119], v168 offset:56832
	v_exp_f32_e32 v110, v110
	v_exp_f32_e32 v111, v111
	s_waitcnt lgkmcnt(14)
	v_mfma_f32_32x32x16_bf16 v[16:31], v[156:159], v[76:79], v[16:31]
	v_exp_f32_e32 v80, v80
	v_exp_f32_e32 v81, v81
	v_mfma_f32_32x32x16_bf16 v[0:15], v[156:159], v[112:115], v[0:15]
	v_exp_f32_e32 v82, v82
	v_exp_f32_e32 v83, v83
	v_mfma_f32_32x32x16_bf16 v[16:31], v[152:155], v[120:123], v[16:31]
	v_exp_f32_e32 v84, v84
	v_exp_f32_e32 v85, v85
	s_waitcnt lgkmcnt(12)
	v_mfma_f32_32x32x16_bf16 v[0:15], v[152:155], v[178:181], v[0:15]
	v_exp_f32_e32 v86, v86
	v_exp_f32_e32 v87, v87
	s_waitcnt lgkmcnt(8)
	v_mfma_f32_32x32x16_bf16 v[16:31], v[148:151], v[194:197], v[16:31]
	v_exp_f32_e32 v88, v88
	v_exp_f32_e32 v89, v89
	s_waitcnt lgkmcnt(4)
	v_mfma_f32_32x32x16_bf16 v[0:15], v[148:151], v[124:127], v[0:15]
	v_exp_f32_e32 v90, v90
	v_exp_f32_e32 v91, v91
	s_waitcnt lgkmcnt(2)
	v_mfma_f32_32x32x16_bf16 v[16:31], v[144:147], v[190:193], v[16:31]
	v_exp_f32_e32 v92, v92
	v_exp_f32_e32 v93, v93
	s_waitcnt lgkmcnt(0)
	v_mfma_f32_32x32x16_bf16 v[0:15], v[144:147], v[116:119], v[0:15]
	v_exp_f32_e32 v94, v94
	v_exp_f32_e32 v95, v95
	s_waitcnt vmcnt(2) lgkmcnt(0)
	s_barrier
; #define WAIT_BAR(N) asm volatile("s_waitcnt vmcnt(" #N ") lgkmcnt(0)\n\ts_barrier":::"memory")
;   #define RESC() do{ if(!NOMAX&&resc){ asm volatile("s_waitcnt lgkmcnt(0)":::"memory"); \
;       _Pragma("unroll") for(int d_=0;d_<2*VM;++d_) _Pragma("unroll") for(int r=0;r<16;++r)o[d_][r]*=wsf[crow(r,hi)]; } }while(0)
;   #define ROT() do{sl_prev=sl_cur;sl_cur=sl_next;sl_next=(sl_next==(NSLOT-1)*SLOTB)?0:sl_next+SLOTB;}while(0)
;   #define ENDW(tt) do{ if((tt)+3<NT){ if constexpr(VM==2){WAIT_BAR(3);}else{WAIT_BAR(2);} } else if((tt)+2<NT){ if constexpr(VM==2){WAIT_BAR(2);}else{WAIT_BAR(1);} } else {WAIT_BAR(0);} }while(0)
; template<int THRL,int VM,bool NOMAX> __device__ __forceinline__ void attn_unit(const bf16*Qb,const bf16*__restrict__ Kh,const bf16*__restrict__ Vh,bf16*Ob,const int NT,const int sp,float*wscr,char*shm){
;     ...
;   int t=1;
;   for(;t+5<NT;t+=2){
;     STEP(pB0,pB1,pA0,pA1,t,true,true,true);     if constexpr(VM==2){WAIT_BAR(3);}else{WAIT_BAR(2);} RESC(); ROT();
;     STEP(pA0,pA1,pB0,pB1,t+1,true,true,true);   if constexpr(VM==2){WAIT_BAR(3);}else{WAIT_BAR(2);} RESC(); ROT();
;   }
;     ...
;   for(;t+1<NT;t+=2){
;     STEP(pB0,pB1,pA0,pA1,t,(t+3<NT),(t+1<NT),(t+1<NT));       ENDW(t);   RESC(); ROT();
;     STEP(pA0,pA1,pB0,pB1,t+1,(t+4<NT),(t+2<NT),(t+2<NT));     ENDW(t+1); RESC(); ROT();
	ds_read_b64_tr_b16 v[178:179], v168 offset:57344
	ds_read_b64_tr_b16 v[180:181], v168 offset:57856
	v_add_f32_e32 v76, v96, v97
	ds_read_b128 v[72:75], v188
	v_add_f32_e32 v76, v98, v76
	v_add_f32_e32 v76, v99, v76
	v_add_f32_e32 v76, v100, v76
	v_add_f32_e32 v76, v101, v76
	v_cvt_pk_bf16_f32 v156, v96, v97
	v_cvt_pk_bf16_f32 v157, v98, v99
	s_waitcnt lgkmcnt(0)
	v_mfma_f32_32x32x16_bf16 v[112:127], v[68:71], v[72:75], 0
	ds_read_b64_tr_b16 v[96:97], v168 offset:61440
	ds_read_b64_tr_b16 v[98:99], v168 offset:61952
	ds_read_b128 v[68:71], v188
	v_add_f32_e32 v72, v102, v76
	v_add_f32_e32 v72, v103, v72
	v_add_f32_e32 v72, v104, v72
	v_add_f32_e32 v144, v105, v72
	s_waitcnt lgkmcnt(0)
	v_mfma_f32_32x32x16_bf16 v[64:79], v[64:67], v[68:71], 0
	v_cvt_pk_bf16_f32 v158, v100, v101
	v_cvt_pk_bf16_f32 v159, v102, v103
	ds_read_b64_tr_b16 v[100:101], v168 offset:58368
	ds_read_b64_tr_b16 v[102:103], v168 offset:58880
	ds_read_b128 v[190:193], v188 offset:1024
	v_add_f32_e32 v144, v106, v144
	v_add_f32_e32 v144, v107, v144
	v_add_f32_e32 v144, v108, v144
	v_add_f32_e32 v144, v109, v144
	v_cvt_pk_bf16_f32 v152, v104, v105
	v_cvt_pk_bf16_f32 v153, v106, v107
	s_waitcnt lgkmcnt(0)
	v_mfma_f32_32x32x16_bf16 v[112:127], v[164:167], v[190:193], v[112:127]
	ds_read_b64_tr_b16 v[104:105], v168 offset:62464
	ds_read_b64_tr_b16 v[106:107], v168 offset:62976
	ds_read_b128 v[164:167], v188 offset:1024
	v_add_f32_e32 v144, v110, v144
	v_add_f32_e32 v144, v111, v144
	v_add_f32_e32 v144, v80, v144
	v_add_f32_e32 v144, v81, v144
	s_waitcnt lgkmcnt(0)
	v_mfma_f32_32x32x16_bf16 v[64:79], v[140:143], v[164:167], v[64:79]
	v_cvt_pk_bf16_f32 v154, v108, v109
	v_cvt_pk_bf16_f32 v155, v110, v111
	ds_read_b64_tr_b16 v[108:109], v168 offset:59392
	ds_read_b64_tr_b16 v[110:111], v168 offset:59904
	ds_read_b128 v[140:143], v188 offset:2048
	v_add_f32_e32 v144, v82, v144
	v_add_f32_e32 v144, v83, v144
	v_add_f32_e32 v144, v84, v144
	v_add_f32_e32 v144, v85, v144
	v_cvt_pk_bf16_f32 v148, v80, v81
	v_cvt_pk_bf16_f32 v149, v82, v83
	s_waitcnt lgkmcnt(0)
	v_mfma_f32_32x32x16_bf16 v[112:127], v[160:163], v[140:143], v[112:127]
	ds_read_b64_tr_b16 v[190:191], v168 offset:63488
	ds_read_b64_tr_b16 v[192:193], v168 offset:64000
	ds_read_b128 v[80:83], v188 offset:2048
	v_add_f32_e32 v140, v86, v144
	v_add_f32_e32 v140, v87, v140
	v_add_f32_e32 v140, v88, v140
	v_add_f32_e32 v140, v89, v140
	s_waitcnt lgkmcnt(0)
	v_mfma_f32_32x32x16_bf16 v[64:79], v[132:135], v[80:83], v[64:79]
	v_cvt_pk_bf16_f32 v150, v84, v85
	v_cvt_pk_bf16_f32 v151, v86, v87
	ds_read_b64_tr_b16 v[84:85], v168 offset:60416
	ds_read_b64_tr_b16 v[86:87], v168 offset:60928
	ds_read_b128 v[80:83], v188 offset:3072
	v_add_f32_e32 v132, v90, v140
	v_add_f32_e32 v132, v91, v132
	v_add_f32_e32 v132, v92, v132
	v_add_f32_e32 v132, v93, v132
	v_cvt_pk_bf16_f32 v144, v88, v89
	v_cvt_pk_bf16_f32 v145, v90, v91
	s_waitcnt lgkmcnt(0)
	v_mfma_f32_32x32x16_bf16 v[112:127], v[136:139], v[80:83], v[112:127]
	ds_read_b64_tr_b16 v[88:89], v168 offset:64512
	ds_read_b64_tr_b16 v[90:91], v168 offset:65024
	ds_read_b128 v[80:83], v188 offset:3072
	v_add_f32_e32 v132, v94, v132
	v_add_f32_e32 v132, v95, v132
	v_add_f32_e32 v132, 0, v132
	v_cvt_pk_bf16_f32 v146, v92, v93
	s_waitcnt lgkmcnt(0)
	v_mfma_f32_32x32x16_bf16 v[64:79], v[128:131], v[80:83], v[64:79]
	v_cvt_pk_bf16_f32 v147, v94, v95
	v_lshl_add_u64 v[80:81], v[170:171], 0, s[62:63]
	s_mov_b32 s16, m0
	s_mov_b32 m0, s17
	s_nop 0
	global_load_lds_dwordx4 v[80:81], off
	s_mov_b32 m0, s16
	v_lshl_add_u64 v[80:81], v[172:173], 0, s[62:63]
	s_mov_b32 s16, m0
	s_mov_b32 m0, s35
	s_nop 0
	global_load_lds_dwordx4 v[80:81], off
	s_mov_b32 m0, s16
	v_add_f32_e32 v174, v174, v132
	v_mfma_f32_32x32x16_bf16 v[48:63], v[156:159], v[178:181], v[48:63]
	ds_read_b64_tr_b16 v[92:93], v177 offset:40960
	ds_read_b64_tr_b16 v[94:95], v177 offset:41472
	v_exp_f32_e32 v112, v112
	v_exp_f32_e32 v113, v113
	v_mfma_f32_32x32x16_bf16 v[32:47], v[156:159], v[96:99], v[32:47]
	ds_read_b64_tr_b16 v[170:171], v177 offset:45056
	ds_read_b64_tr_b16 v[172:173], v177 offset:45568
	v_exp_f32_e32 v114, v114
	v_exp_f32_e32 v115, v115
	ds_read_b128 v[80:83], v234 offset:8192
	ds_read_b128 v[96:99], v234 offset:12288
	v_mfma_f32_32x32x16_bf16 v[48:63], v[152:155], v[100:103], v[48:63]
	ds_read_b64_tr_b16 v[178:179], v177 offset:41984
	ds_read_b64_tr_b16 v[180:181], v177 offset:42496
	v_exp_f32_e32 v116, v116
	v_exp_f32_e32 v117, v117
	ds_read_b128 v[164:167], v235 offset:8192
	ds_read_b128 v[140:143], v235 offset:12288
	v_mfma_f32_32x32x16_bf16 v[32:47], v[152:155], v[104:107], v[32:47]
	ds_read_b64_tr_b16 v[100:101], v177 offset:46080
	ds_read_b64_tr_b16 v[102:103], v177 offset:46592
	v_exp_f32_e32 v118, v118
	v_exp_f32_e32 v119, v119
	ds_read_b128 v[160:163], v236 offset:8192
	ds_read_b128 v[132:135], v236 offset:12288
	v_mfma_f32_32x32x16_bf16 v[48:63], v[148:151], v[108:111], v[48:63]
	ds_read_b64_tr_b16 v[104:105], v177 offset:43008
	ds_read_b64_tr_b16 v[106:107], v177 offset:43520
	v_exp_f32_e32 v120, v120
	v_exp_f32_e32 v121, v121
	ds_read_b128 v[136:139], v237 offset:8192
	ds_read_b128 v[128:131], v237 offset:12288
	v_mfma_f32_32x32x16_bf16 v[32:47], v[148:151], v[190:193], v[32:47]
	ds_read_b64_tr_b16 v[108:109], v177 offset:47104
	ds_read_b64_tr_b16 v[110:111], v177 offset:47616
	v_exp_f32_e32 v122, v122
	v_exp_f32_e32 v123, v123
	v_mfma_f32_32x32x16_bf16 v[48:63], v[144:147], v[84:87], v[48:63]
	ds_read_b64_tr_b16 v[190:191], v177 offset:44032
	ds_read_b64_tr_b16 v[192:193], v177 offset:44544
	v_exp_f32_e32 v124, v124
	v_exp_f32_e32 v125, v125
	v_mfma_f32_32x32x16_bf16 v[32:47], v[144:147], v[88:91], v[32:47]
	ds_read_b64_tr_b16 v[84:85], v177 offset:48128
	ds_read_b64_tr_b16 v[86:87], v177 offset:48640
	v_exp_f32_e32 v126, v126
	v_exp_f32_e32 v127, v127
	s_waitcnt lgkmcnt(14)
	v_mfma_f32_32x32x16_bf16 v[16:31], v[156:159], v[92:95], v[16:31]
	v_exp_f32_e32 v64, v64
	v_exp_f32_e32 v65, v65
	v_mfma_f32_32x32x16_bf16 v[0:15], v[156:159], v[170:173], v[0:15]
	v_exp_f32_e32 v66, v66
	v_exp_f32_e32 v67, v67
	v_mfma_f32_32x32x16_bf16 v[16:31], v[152:155], v[178:181], v[16:31]
	v_exp_f32_e32 v68, v68
	v_exp_f32_e32 v69, v69
	s_waitcnt lgkmcnt(12)
	v_mfma_f32_32x32x16_bf16 v[0:15], v[152:155], v[100:103], v[0:15]
	v_exp_f32_e32 v70, v70
	v_exp_f32_e32 v71, v71
	s_waitcnt lgkmcnt(8)
	v_mfma_f32_32x32x16_bf16 v[16:31], v[148:151], v[104:107], v[16:31]
	v_exp_f32_e32 v72, v72
	v_exp_f32_e32 v73, v73
	s_waitcnt lgkmcnt(4)
	v_mfma_f32_32x32x16_bf16 v[0:15], v[148:151], v[108:111], v[0:15]
	v_exp_f32_e32 v74, v74
	v_exp_f32_e32 v75, v75
	s_waitcnt lgkmcnt(2)
	v_mfma_f32_32x32x16_bf16 v[16:31], v[144:147], v[190:193], v[16:31]
	v_exp_f32_e32 v76, v76
	v_exp_f32_e32 v77, v77
	s_waitcnt lgkmcnt(0)
	v_mfma_f32_32x32x16_bf16 v[0:15], v[144:147], v[84:87], v[0:15]
	v_exp_f32_e32 v78, v78
	v_exp_f32_e32 v79, v79
	s_waitcnt vmcnt(0) lgkmcnt(0)
	s_barrier
;   #define RESC() do{ if(!NOMAX&&resc){ asm volatile("s_waitcnt lgkmcnt(0)":::"memory"); \
;       _Pragma("unroll") for(int d_=0;d_<2*VM;++d_) _Pragma("unroll") for(int r=0;r<16;++r)o[d_][r]*=wsf[crow(r,hi)]; } }while(0)
; template<int THRL,int VM,bool NOMAX> __device__ __forceinline__ void attn_unit(const bf16*Qb,const bf16*__restrict__ Kh,const bf16*__restrict__ Vh,bf16*Ob,const int NT,const int sp,float*wscr,char*shm){
;     ...
;   STEP(pB0,pB1,pA0,pA1,NT-1,false,false,false); RESC();
	ds_read_b64_tr_b16 v[170:171], v168 offset:24576
	ds_read_b64_tr_b16 v[172:173], v168 offset:25088
	v_add_f32_e32 v88, v112, v113
	ds_read_b128 v[84:87], v188
	v_add_f32_e32 v88, v114, v88
	v_add_f32_e32 v88, v115, v88
	v_add_f32_e32 v88, v116, v88
	v_add_f32_e32 v104, v117, v88
	v_cvt_pk_bf16_f32 v156, v112, v113
	v_cvt_pk_bf16_f32 v157, v114, v115
	s_waitcnt lgkmcnt(0)
	v_mfma_f32_32x32x16_bf16 v[80:95], v[80:83], v[84:87], 0
	ds_read_b64_tr_b16 v[112:113], v168 offset:28672
	ds_read_b64_tr_b16 v[114:115], v168 offset:29184
	ds_read_b128 v[100:103], v188
	v_add_f32_e32 v104, v118, v104
	v_add_f32_e32 v104, v119, v104
	v_add_f32_e32 v104, v120, v104
	v_add_f32_e32 v144, v121, v104
	v_cvt_pk_bf16_f32 v158, v116, v117
	v_cvt_pk_bf16_f32 v159, v118, v119
	s_waitcnt lgkmcnt(0)
	v_mfma_f32_32x32x16_bf16 v[96:111], v[96:99], v[100:103], 0
	ds_read_b64_tr_b16 v[116:117], v168 offset:25600
	ds_read_b64_tr_b16 v[118:119], v168 offset:26112
	ds_read_b128 v[178:181], v188 offset:1024
	v_add_f32_e32 v144, v122, v144
	v_add_f32_e32 v144, v123, v144
	v_add_f32_e32 v144, v124, v144
	v_add_f32_e32 v144, v125, v144
	v_cvt_pk_bf16_f32 v152, v120, v121
	v_cvt_pk_bf16_f32 v153, v122, v123
	s_waitcnt lgkmcnt(0)
	v_mfma_f32_32x32x16_bf16 v[80:95], v[164:167], v[178:181], v[80:95]
	ds_read_b64_tr_b16 v[120:121], v168 offset:29696
	ds_read_b64_tr_b16 v[122:123], v168 offset:30208
	ds_read_b128 v[164:167], v188 offset:1024
	v_add_f32_e32 v144, v126, v144
	v_add_f32_e32 v144, v127, v144
	v_add_f32_e32 v144, v64, v144
	v_add_f32_e32 v144, v65, v144
	v_cvt_pk_bf16_f32 v154, v124, v125
	v_cvt_pk_bf16_f32 v155, v126, v127
	s_waitcnt lgkmcnt(0)
	v_mfma_f32_32x32x16_bf16 v[96:111], v[140:143], v[164:167], v[96:111]
	ds_read_b64_tr_b16 v[124:125], v168 offset:26624
	ds_read_b64_tr_b16 v[126:127], v168 offset:27136
	ds_read_b128 v[140:143], v188 offset:2048
	v_add_f32_e32 v144, v66, v144
	v_add_f32_e32 v144, v67, v144
	v_add_f32_e32 v144, v68, v144
	v_add_f32_e32 v144, v69, v144
	v_cvt_pk_bf16_f32 v148, v64, v65
	v_cvt_pk_bf16_f32 v149, v66, v67
	s_waitcnt lgkmcnt(0)
	v_mfma_f32_32x32x16_bf16 v[80:95], v[160:163], v[140:143], v[80:95]
	ds_read_b64_tr_b16 v[64:65], v168 offset:30720
	ds_read_b64_tr_b16 v[66:67], v168 offset:31232
	ds_read_b128 v[140:143], v188 offset:2048
	v_add_f32_e32 v144, v70, v144
	v_add_f32_e32 v144, v71, v144
	v_add_f32_e32 v144, v72, v144
	v_add_f32_e32 v144, v73, v144
	v_cvt_pk_bf16_f32 v150, v68, v69
	v_cvt_pk_bf16_f32 v151, v70, v71
	s_waitcnt lgkmcnt(0)
	v_mfma_f32_32x32x16_bf16 v[96:111], v[132:135], v[140:143], v[96:111]
	ds_read_b64_tr_b16 v[68:69], v168 offset:27648
	ds_read_b64_tr_b16 v[70:71], v168 offset:28160
	ds_read_b128 v[132:135], v188 offset:3072
	v_add_f32_e32 v140, v74, v144
	v_add_f32_e32 v140, v75, v140
	v_add_f32_e32 v140, v76, v140
	v_add_f32_e32 v140, v77, v140
	v_cvt_pk_bf16_f32 v144, v72, v73
	v_cvt_pk_bf16_f32 v145, v74, v75
	s_waitcnt lgkmcnt(0)
	v_mfma_f32_32x32x16_bf16 v[80:95], v[136:139], v[132:135], v[80:95]
	ds_read_b64_tr_b16 v[72:73], v168 offset:31744
	ds_read_b64_tr_b16 v[74:75], v168 offset:32256
	ds_read_b128 v[132:135], v188 offset:3072
	v_add_f32_e32 v136, v78, v140
	v_add_f32_e32 v136, v79, v136
	v_add_f32_e32 v136, 0, v136
	v_cvt_pk_bf16_f32 v146, v76, v77
	v_cvt_pk_bf16_f32 v147, v78, v79
	s_waitcnt lgkmcnt(0)
	v_mfma_f32_32x32x16_bf16 v[96:111], v[128:131], v[132:135], v[96:111]
	v_mfma_f32_32x32x16_bf16 v[48:63], v[156:159], v[170:173], v[48:63]
	ds_read_b64_tr_b16 v[76:77], v168 offset:32768
	ds_read_b64_tr_b16 v[78:79], v168 offset:33280
	v_exp_f32_e32 v80, v80
	v_exp_f32_e32 v81, v81
	v_mfma_f32_32x32x16_bf16 v[32:47], v[156:159], v[112:115], v[32:47]
	ds_read_b64_tr_b16 v[128:129], v168 offset:36864
	ds_read_b64_tr_b16 v[130:131], v168 offset:37376
	v_exp_f32_e32 v82, v82
	v_exp_f32_e32 v83, v83
	v_mfma_f32_32x32x16_bf16 v[48:63], v[152:155], v[116:119], v[48:63]
	ds_read_b64_tr_b16 v[112:113], v168 offset:33792
	ds_read_b64_tr_b16 v[114:115], v168 offset:34304
	v_exp_f32_e32 v84, v84
	v_exp_f32_e32 v85, v85
	v_mfma_f32_32x32x16_bf16 v[32:47], v[152:155], v[120:123], v[32:47]
	ds_read_b64_tr_b16 v[116:117], v168 offset:37888
	ds_read_b64_tr_b16 v[118:119], v168 offset:38400
	v_exp_f32_e32 v86, v86
	v_exp_f32_e32 v87, v87
	v_mfma_f32_32x32x16_bf16 v[48:63], v[148:151], v[124:127], v[48:63]
	ds_read_b64_tr_b16 v[120:121], v168 offset:34816
	ds_read_b64_tr_b16 v[122:123], v168 offset:35328
	v_exp_f32_e32 v88, v88
	v_exp_f32_e32 v89, v89
	v_mfma_f32_32x32x16_bf16 v[32:47], v[148:151], v[64:67], v[32:47]
	ds_read_b64_tr_b16 v[124:125], v168 offset:38912
	ds_read_b64_tr_b16 v[126:127], v168 offset:39424
	v_exp_f32_e32 v90, v90
	v_exp_f32_e32 v91, v91
	v_mfma_f32_32x32x16_bf16 v[48:63], v[144:147], v[68:71], v[48:63]
	ds_read_b64_tr_b16 v[64:65], v168 offset:35840
	ds_read_b64_tr_b16 v[66:67], v168 offset:36352
	v_exp_f32_e32 v92, v92
	v_exp_f32_e32 v93, v93
	v_mfma_f32_32x32x16_bf16 v[32:47], v[144:147], v[72:75], v[32:47]
	ds_read_b64_tr_b16 v[68:69], v168 offset:39936
	ds_read_b64_tr_b16 v[70:71], v168 offset:40448
	v_exp_f32_e32 v94, v94
	v_exp_f32_e32 v95, v95
	s_waitcnt lgkmcnt(14)
	v_mfma_f32_32x32x16_bf16 v[16:31], v[156:159], v[76:79], v[16:31]
	v_exp_f32_e32 v96, v96
	v_exp_f32_e32 v97, v97
	s_waitcnt lgkmcnt(12)
; #define SBAR() __builtin_amdgcn_sched_barrier(0)
;   #define RESC() do{ if(!NOMAX&&resc){ asm volatile("s_waitcnt lgkmcnt(0)":::"memory"); \
;       _Pragma("unroll") for(int d_=0;d_<2*VM;++d_) _Pragma("unroll") for(int r=0;r<16;++r)o[d_][r]*=wsf[crow(r,hi)]; } }while(0)
;   #define PKW(P,B) cvtpk_s(P[B],P[B+1])
; __device__ __forceinline__ void pv(f32x16*o,int vb,bf16x8 pa0,bf16x8 pa1,bf16x8 pa2,bf16x8 pa3){
;   #pragma unroll
;   for(int d0=0;d0<2;++d0){s16x4 lo[4],hi[4];
;     #pragma unroll
;     for(int ks=0;ks<4;++ks){
;       asm volatile("ds_read_b64_tr_b16 %0,%1 offset:%c2":"=&v"(lo[ks]):"v"(vb),"i"(d0*4096+ks*1024):"memory");
;       asm volatile("ds_read_b64_tr_b16 %0,%1 offset:%c2":"=&v"(hi[ks]):"v"(vb),"i"(d0*4096+ks*1024+512):"memory");}
;     asm volatile("s_waitcnt lgkmcnt(0)":::"memory");SBAR();
;     ...
;     o[d0]=__builtin_amdgcn_mfma_f32_32x32x16_bf16(pa0,PK(0),o[d0],0,0,0);
;     o[d0]=__builtin_amdgcn_mfma_f32_32x32x16_bf16(pa1,PK(1),o[d0],0,0,0);
;     o[d0]=__builtin_amdgcn_mfma_f32_32x32x16_bf16(pa2,PK(2),o[d0],0,0,0);
;     o[d0]=__builtin_amdgcn_mfma_f32_32x32x16_bf16(pa3,PK(3),o[d0],0,0,0);
;     ...
;   }
; }
; template<int THRL,int VM,bool NOMAX> __device__ __forceinline__ void attn_unit(const bf16*Qb,const bf16*__restrict__ Kh,const bf16*__restrict__ Vh,bf16*Ob,const int NT,const int sp,float*wscr,char*shm){
;     ...
;   STEP(pB0,pB1,pA0,pA1,NT-1,false,false,false); RESC();
;   { float sacc=pB0[0]+pB0[1]; _Pragma("unroll") for(int r=2;r<16;++r)sacc+=pB0[r]; _Pragma("unroll") for(int r=0;r<16;++r)sacc+=pB1[r]; l_reg+=sacc;
;     pw0=(u32x4){PKW(pB0,0),PKW(pB0,2),PKW(pB0,4),PKW(pB0,6)};pw1=(u32x4){PKW(pB0,8),PKW(pB0,10),PKW(pB0,12),PKW(pB0,14)};pw2=(u32x4){PKW(pB1,0),PKW(pB1,2),PKW(pB1,4),PKW(pB1,6)};pw3=(u32x4){PKW(pB1,8),PKW(pB1,10),PKW(pB1,12),PKW(pB1,14)};
;     SBAR(); pv(o,vb0+VM*sl_cur,PAF(0),PAF(1),PAF(2),PAF(3)); if constexpr(VM==2) pv(o+2,vb0+VM*sl_cur+8192,PAF(0),PAF(1),PAF(2),PAF(3)); }
;     ...
;   {auto rr=__builtin_amdgcn_permlane32_swap(__float_as_uint(l_reg),__float_as_uint(l_reg),false,false);l_reg=__uint_as_float(rr[0])+__uint_as_float(rr[1]);}
;   if(hi==0)wsf[32+r32]=l_reg;asm volatile("s_waitcnt lgkmcnt(0)":::"memory");
	v_mfma_f32_32x32x16_bf16 v[0:15], v[156:159], v[128:131], v[0:15]
	v_exp_f32_e32 v98, v98
	v_exp_f32_e32 v99, v99
	s_waitcnt lgkmcnt(10)
	v_mfma_f32_32x32x16_bf16 v[16:31], v[152:155], v[112:115], v[16:31]
	v_exp_f32_e32 v100, v100
	v_exp_f32_e32 v101, v101
	s_waitcnt lgkmcnt(8)
	v_mfma_f32_32x32x16_bf16 v[0:15], v[152:155], v[116:119], v[0:15]
	v_exp_f32_e32 v102, v102
	v_exp_f32_e32 v103, v103
	s_waitcnt lgkmcnt(6)
	v_mfma_f32_32x32x16_bf16 v[16:31], v[148:151], v[120:123], v[16:31]
	v_exp_f32_e32 v104, v104
	v_exp_f32_e32 v105, v105
	s_waitcnt lgkmcnt(4)
	v_mfma_f32_32x32x16_bf16 v[0:15], v[148:151], v[124:127], v[0:15]
	v_exp_f32_e32 v106, v106
	v_exp_f32_e32 v107, v107
	s_waitcnt lgkmcnt(2)
	v_mfma_f32_32x32x16_bf16 v[16:31], v[144:147], v[64:67], v[16:31]
	v_exp_f32_e32 v108, v108
	v_exp_f32_e32 v109, v109
	s_waitcnt lgkmcnt(0)
	v_mfma_f32_32x32x16_bf16 v[0:15], v[144:147], v[68:71], v[0:15]
	v_exp_f32_e32 v110, v110
	v_exp_f32_e32 v111, v111
	v_add_f32_e32 v64, v80, v81
	v_add_f32_e32 v64, v82, v64
	v_add_f32_e32 v64, v83, v64
	v_add_f32_e32 v64, v84, v64
	v_add_f32_e32 v64, v85, v64
	v_add_f32_e32 v64, v86, v64
	v_add_f32_e32 v64, v87, v64
	v_add_f32_e32 v64, v88, v64
	v_add_f32_e32 v64, v89, v64
	v_add_f32_e32 v64, v90, v64
	v_add_f32_e32 v64, v91, v64
	v_add_f32_e32 v64, v92, v64
	v_add_f32_e32 v64, v93, v64
	v_add_f32_e32 v64, v94, v64
	v_add_f32_e32 v64, v95, v64
	v_add_f32_e32 v64, v64, v96
	v_add_f32_e32 v64, v97, v64
	v_add_f32_e32 v64, v98, v64
	v_add_f32_e32 v64, v99, v64
	v_add_f32_e32 v64, v100, v64
	v_add_f32_e32 v64, v101, v64
	v_add_f32_e32 v64, v102, v64
	v_add_f32_e32 v64, v103, v64
	v_add_f32_e32 v64, v104, v64
	v_add_f32_e32 v64, v105, v64
	v_add_f32_e32 v64, v106, v64
	v_add_f32_e32 v64, v107, v64
	v_add_f32_e32 v64, v108, v64
	v_add_f32_e32 v64, v109, v64
	v_add_f32_e32 v64, v110, v64
	v_add_f32_e32 v64, v111, v64
	v_add_f32_e32 v65, v174, v136
	v_add_f32_e32 v64, v65, v64
	v_cvt_pk_bf16_f32 v66, v80, v81
	v_cvt_pk_bf16_f32 v67, v82, v83
	v_cvt_pk_bf16_f32 v68, v84, v85
	v_cvt_pk_bf16_f32 v69, v86, v87
	v_cvt_pk_bf16_f32 v70, v88, v89
	v_cvt_pk_bf16_f32 v71, v90, v91
	v_cvt_pk_bf16_f32 v72, v92, v93
	v_cvt_pk_bf16_f32 v73, v94, v95
	v_cvt_pk_bf16_f32 v74, v96, v97
	v_cvt_pk_bf16_f32 v75, v98, v99
	v_cvt_pk_bf16_f32 v76, v100, v101
	v_cvt_pk_bf16_f32 v77, v102, v103
	v_cvt_pk_bf16_f32 v78, v104, v105
	v_cvt_pk_bf16_f32 v79, v106, v107
	v_cvt_pk_bf16_f32 v80, v108, v109
	v_cvt_pk_bf16_f32 v81, v110, v111
	v_add_u32_e32 v65, 0x4000, v176
	ds_read_b64_tr_b16 v[82:83],v65 offset:0
	ds_read_b64_tr_b16 v[84:85],v65 offset:512
	ds_read_b64_tr_b16 v[86:87],v65 offset:1024
	ds_read_b64_tr_b16 v[88:89],v65 offset:1536
	ds_read_b64_tr_b16 v[90:91],v65 offset:2048
	ds_read_b64_tr_b16 v[92:93],v65 offset:2560
	ds_read_b64_tr_b16 v[94:95],v65 offset:3072
	ds_read_b64_tr_b16 v[96:97],v65 offset:3584
	s_waitcnt lgkmcnt(0)
	s_nop 0
	v_mfma_f32_32x32x16_bf16 v[48:63], v[66:69], v[82:85], v[48:63]
	ds_read_b64_tr_b16 v[82:83],v65 offset:4096
	ds_read_b64_tr_b16 v[84:85],v65 offset:4608
	v_mfma_f32_32x32x16_bf16 v[48:63], v[70:73], v[86:89], v[48:63]
	ds_read_b64_tr_b16 v[86:87],v65 offset:5120
	ds_read_b64_tr_b16 v[88:89],v65 offset:5632
	v_mfma_f32_32x32x16_bf16 v[48:63], v[74:77], v[90:93], v[48:63]
	ds_read_b64_tr_b16 v[90:91],v65 offset:6144
	ds_read_b64_tr_b16 v[92:93],v65 offset:6656
	ds_read_b64_tr_b16 v[98:99],v65 offset:7168
	ds_read_b64_tr_b16 v[100:101],v65 offset:7680
	s_waitcnt lgkmcnt(0)
	v_mfma_f32_32x32x16_bf16 v[48:63], v[78:81], v[94:97], v[48:63]
	v_mfma_f32_32x32x16_bf16 v[32:47], v[66:69], v[82:85], v[32:47]
	v_add_u32_e32 v65, 0x6000, v176
	ds_read_b64_tr_b16 v[82:83],v65 offset:0
	ds_read_b64_tr_b16 v[84:85],v65 offset:512
	v_mfma_f32_32x32x16_bf16 v[32:47], v[70:73], v[86:89], v[32:47]
	ds_read_b64_tr_b16 v[86:87],v65 offset:1024
	ds_read_b64_tr_b16 v[88:89],v65 offset:1536
	v_mfma_f32_32x32x16_bf16 v[32:47], v[74:77], v[90:93], v[32:47]
	ds_read_b64_tr_b16 v[90:91],v65 offset:2048
	ds_read_b64_tr_b16 v[92:93],v65 offset:2560
	ds_read_b64_tr_b16 v[94:95],v65 offset:3072
	ds_read_b64_tr_b16 v[96:97],v65 offset:3584
	s_waitcnt lgkmcnt(0)
	v_mfma_f32_32x32x16_bf16 v[32:47], v[78:81], v[98:101], v[32:47]
	v_mfma_f32_32x32x16_bf16 v[16:31], v[66:69], v[82:85], v[16:31]
	ds_read_b64_tr_b16 v[82:83],v65 offset:4096
	ds_read_b64_tr_b16 v[84:85],v65 offset:4608
	v_mfma_f32_32x32x16_bf16 v[16:31], v[70:73], v[86:89], v[16:31]
	ds_read_b64_tr_b16 v[86:87],v65 offset:5120
	ds_read_b64_tr_b16 v[88:89],v65 offset:5632
	v_mfma_f32_32x32x16_bf16 v[16:31], v[74:77], v[90:93], v[16:31]
	ds_read_b64_tr_b16 v[90:91],v65 offset:6144
	ds_read_b64_tr_b16 v[92:93],v65 offset:6656
	ds_read_b64_tr_b16 v[98:99],v65 offset:7168
	ds_read_b64_tr_b16 v[100:101],v65 offset:7680
	s_waitcnt lgkmcnt(0)
	v_mfma_f32_32x32x16_bf16 v[16:31], v[78:81], v[94:97], v[16:31]
	v_mfma_f32_32x32x16_bf16 v[0:15], v[66:69], v[82:85], v[0:15]
	v_mov_b32_e32 v65, v64
	s_nop 1
	v_permlane32_swap_b32_e32 v64, v65
	v_cmp_gt_u32_e32 vcc, 32, v187
	v_mfma_f32_32x32x16_bf16 v[0:15], v[70:73], v[86:89], v[0:15]
	v_mfma_f32_32x32x16_bf16 v[0:15], v[74:77], v[90:93], v[0:15]
	v_mfma_f32_32x32x16_bf16 v[0:15], v[78:81], v[98:101], v[0:15]
	s_and_saveexec_b64 s[16:17], vcc
	s_cbranch_execz .LBB0_859
	v_add_f32_e32 v64, v64, v65
	v_lshl_add_u32 v65, v186, 2, s34
	ds_write_b32 v65, v64 offset:128
	s_branch .LBB0_859

; #define WAIT_BAR(N) asm volatile("s_waitcnt vmcnt(" #N ") lgkmcnt(0)\n\ts_barrier":::"memory")
;   #define RESC() do{ if(!NOMAX&&resc){ asm volatile("s_waitcnt lgkmcnt(0)":::"memory"); \
;       _Pragma("unroll") for(int d_=0;d_<2*VM;++d_) _Pragma("unroll") for(int r=0;r<16;++r)o[d_][r]*=wsf[crow(r,hi)]; } }while(0)
;   #define ROT() do{sl_prev=sl_cur;sl_cur=sl_next;sl_next=(sl_next==(NSLOT-1)*SLOTB)?0:sl_next+SLOTB;}while(0)
; template<int THRL,int VM,bool NOMAX> __device__ __forceinline__ void attn_unit(const bf16*Qb,const bf16*__restrict__ Kh,const bf16*__restrict__ Vh,bf16*Ob,const int NT,const int sp,float*wscr,char*shm){
;     ...
;   int t=1;
;   for(;t+5<NT;t+=2){
;     STEP(pB0,pB1,pA0,pA1,t,true,true,true);     if constexpr(VM==2){WAIT_BAR(3);}else{WAIT_BAR(2);} RESC(); ROT();
;     STEP(pA0,pA1,pB0,pB1,t+1,true,true,true);   if constexpr(VM==2){WAIT_BAR(3);}else{WAIT_BAR(2);} RESC(); ROT();
.LBB0_874:
	v_mfma_f32_32x32x16_bf16 v[112:127], v[100:103], v[218:221], 0
	v_lshl_add_u32 v206, s89, 1, v188
	ds_read_b64_tr_b16 v[194:195], v206 offset:24576
	ds_read_b64_tr_b16 v[196:197], v206 offset:25088
	v_add_f32_e32 v108, v80, v81
	v_add_f32_e32 v108, v82, v108
	v_add_f32_e32 v108, v83, v108
	v_add_f32_e32 v108, v84, v108
	v_add_f32_e32 v108, v85, v108
	v_cvt_pk_bf16_f32 v156, v80, v81
	v_cvt_pk_bf16_f32 v157, v82, v83
	ds_read_b64_tr_b16 v[80:81], v206 offset:28672
	ds_read_b64_tr_b16 v[82:83], v206 offset:29184
	v_add_f32_e32 v104, v86, v108
	v_add_f32_e32 v104, v87, v104
	v_add_f32_e32 v104, v88, v104
	v_add_f32_e32 v144, v89, v104
	v_mfma_f32_32x32x16_bf16 v[96:111], v[96:99], v[218:221], 0
	v_cvt_pk_bf16_f32 v158, v84, v85
	v_cvt_pk_bf16_f32 v159, v86, v87
	ds_read_b64_tr_b16 v[84:85], v206 offset:25600
	ds_read_b64_tr_b16 v[86:87], v206 offset:26112
	v_add_f32_e32 v144, v90, v144
	v_add_f32_e32 v144, v91, v144
	v_add_f32_e32 v144, v92, v144
	v_add_f32_e32 v144, v93, v144
	v_cvt_pk_bf16_f32 v152, v88, v89
	v_cvt_pk_bf16_f32 v153, v90, v91
	v_mfma_f32_32x32x16_bf16 v[112:127], v[164:167], v[222:225], v[112:127]
	ds_read_b64_tr_b16 v[88:89], v206 offset:29696
	ds_read_b64_tr_b16 v[90:91], v206 offset:30208
	v_add_f32_e32 v144, v94, v144
	v_add_f32_e32 v144, v95, v144
	v_add_f32_e32 v144, v64, v144
	v_add_f32_e32 v144, v65, v144
	v_mfma_f32_32x32x16_bf16 v[96:111], v[160:163], v[222:225], v[96:111]
	v_cvt_pk_bf16_f32 v154, v92, v93
	v_cvt_pk_bf16_f32 v155, v94, v95
	ds_read_b64_tr_b16 v[92:93], v206 offset:26624
	ds_read_b64_tr_b16 v[94:95], v206 offset:27136
	v_add_f32_e32 v144, v66, v144
	v_add_f32_e32 v144, v67, v144
	v_add_f32_e32 v144, v68, v144
	v_add_f32_e32 v144, v69, v144
	v_cvt_pk_bf16_f32 v148, v64, v65
	v_cvt_pk_bf16_f32 v149, v66, v67
	v_mfma_f32_32x32x16_bf16 v[112:127], v[140:143], v[226:229], v[112:127]
	ds_read_b64_tr_b16 v[198:199], v206 offset:30720
	ds_read_b64_tr_b16 v[200:201], v206 offset:31232
	v_add_f32_e32 v140, v70, v144
	v_add_f32_e32 v140, v71, v140
	v_add_f32_e32 v140, v72, v140
	v_add_f32_e32 v140, v73, v140
	v_mfma_f32_32x32x16_bf16 v[96:111], v[136:139], v[226:229], v[96:111]
	v_cvt_pk_bf16_f32 v150, v68, v69
	v_cvt_pk_bf16_f32 v151, v70, v71
	ds_read_b64_tr_b16 v[202:203], v206 offset:27648
	ds_read_b64_tr_b16 v[204:205], v206 offset:28160
	v_add_f32_e32 v68, v74, v140
	v_add_f32_e32 v68, v75, v68
	v_add_f32_e32 v68, v76, v68
	v_add_f32_e32 v68, v77, v68
	v_cvt_pk_bf16_f32 v144, v72, v73
	v_cvt_pk_bf16_f32 v145, v74, v75
	v_mfma_f32_32x32x16_bf16 v[112:127], v[132:135], v[230:233], v[112:127]
	ds_read_b64_tr_b16 v[72:73], v206 offset:31744
	ds_read_b64_tr_b16 v[74:75], v206 offset:32256
	v_add_f32_e32 v68, v78, v68
	v_add_f32_e32 v68, v79, v68
	v_add_f32_e32 v68, 0, v68
	v_cvt_pk_bf16_f32 v146, v76, v77
	v_mfma_f32_32x32x16_bf16 v[96:111], v[128:131], v[230:233], v[96:111]
	v_cvt_pk_bf16_f32 v147, v78, v79
	v_add_f32_e32 v193, v193, v68
	s_waitcnt lgkmcnt(12)
	v_mfma_f32_32x32x16_bf16 v[48:63], v[156:159], v[194:197], v[48:63]
	ds_read_b64_tr_b16 v[76:77], v206 offset:32768
	ds_read_b64_tr_b16 v[78:79], v206 offset:33280
	v_exp_f32_e32 v112, v112
	v_exp_f32_e32 v113, v113
	v_mfma_f32_32x32x16_bf16 v[32:47], v[156:159], v[80:83], v[32:47]
	ds_read_b64_tr_b16 v[194:195], v206 offset:36864
	ds_read_b64_tr_b16 v[196:197], v206 offset:37376
	v_exp_f32_e32 v114, v114
	v_exp_f32_e32 v115, v115
	v_add_u32_e32 v242, s86, v234
	v_add_u32_e32 v243, s86, v235
	v_add_u32_e32 v244, s86, v236
	v_add_u32_e32 v245, s86, v237
	ds_read_b128 v[68:71], v242
	ds_read_b128 v[64:67], v242 offset:4096
	s_waitcnt lgkmcnt(14)
	v_mfma_f32_32x32x16_bf16 v[48:63], v[152:155], v[84:87], v[48:63]
	ds_read_b64_tr_b16 v[80:81], v206 offset:33792
	ds_read_b64_tr_b16 v[82:83], v206 offset:34304
	v_exp_f32_e32 v116, v116
	v_exp_f32_e32 v117, v117
	ds_read_b128 v[164:167], v243
	ds_read_b128 v[140:143], v243 offset:4096
	v_mfma_f32_32x32x16_bf16 v[32:47], v[152:155], v[88:91], v[32:47]
	ds_read_b64_tr_b16 v[84:85], v206 offset:37888
	ds_read_b64_tr_b16 v[86:87], v206 offset:38400
	v_exp_f32_e32 v118, v118
	v_exp_f32_e32 v119, v119
	ds_read_b128 v[160:163], v244
	ds_read_b128 v[132:135], v244 offset:4096
	s_waitcnt lgkmcnt(14)
	v_mfma_f32_32x32x16_bf16 v[48:63], v[148:151], v[92:95], v[48:63]
	ds_read_b64_tr_b16 v[88:89], v206 offset:34816
	ds_read_b64_tr_b16 v[90:91], v206 offset:35328
	v_exp_f32_e32 v120, v120
	v_exp_f32_e32 v121, v121
	ds_read_b128 v[136:139], v245
	ds_read_b128 v[128:131], v245 offset:4096
	v_mfma_f32_32x32x16_bf16 v[32:47], v[148:151], v[198:201], v[32:47]
	ds_read_b64_tr_b16 v[92:93], v206 offset:38912
	ds_read_b64_tr_b16 v[94:95], v206 offset:39424
	v_exp_f32_e32 v122, v122
	v_exp_f32_e32 v123, v123
	s_waitcnt lgkmcnt(14)
	v_mfma_f32_32x32x16_bf16 v[48:63], v[144:147], v[202:205], v[48:63]
	ds_read_b64_tr_b16 v[198:199], v206 offset:35840
	ds_read_b64_tr_b16 v[200:201], v206 offset:36352
	v_exp_f32_e32 v124, v124
	v_exp_f32_e32 v125, v125
	v_mfma_f32_32x32x16_bf16 v[32:47], v[144:147], v[72:75], v[32:47]
	ds_read_b64_tr_b16 v[202:203], v206 offset:39936
	ds_read_b64_tr_b16 v[204:205], v206 offset:40448
	v_exp_f32_e32 v126, v126
	v_exp_f32_e32 v127, v127
	s_waitcnt lgkmcnt(14)
	v_mfma_f32_32x32x16_bf16 v[16:31], v[156:159], v[76:79], v[16:31]
	s_add_i32 s88, s87, s17
	v_lshl_add_u64 v[238:239], v[180:181], 0, s[56:57]
	s_mov_b32 s89, m0
	s_mov_b32 m0, s88
	s_nop 0
	global_load_lds_dwordx4 v[238:239], off
	s_mov_b32 m0, s89
	v_exp_f32_e32 v96, v96
	v_exp_f32_e32 v97, v97
	v_mfma_f32_32x32x16_bf16 v[0:15], v[156:159], v[194:197], v[0:15]
	s_lshl_b32 s88, s86, 1
	v_lshl_add_u64 v[238:239], v[178:179], 0, s[56:57]
	s_add_i32 s88, s88, s16
	s_mov_b32 s89, m0
	s_mov_b32 m0, s88
	s_nop 0
	global_load_lds_dwordx4 v[238:239], off
	s_mov_b32 m0, s89
	v_exp_f32_e32 v98, v98
	v_exp_f32_e32 v99, v99
	v_mfma_f32_32x32x16_bf16 v[16:31], v[152:155], v[80:83], v[16:31]
	v_lshl_add_u64 v[238:239], v[176:177], 0, s[56:57]
	s_addk_i32 s88, 0x2000
	s_mov_b32 s89, m0
	s_mov_b32 m0, s88
	s_nop 0
	global_load_lds_dwordx4 v[238:239], off
	s_mov_b32 m0, s89
	v_exp_f32_e32 v100, v100
	v_exp_f32_e32 v101, v101
	s_waitcnt lgkmcnt(12)
	v_mfma_f32_32x32x16_bf16 v[0:15], v[152:155], v[84:87], v[0:15]
	v_exp_f32_e32 v102, v102
	v_exp_f32_e32 v103, v103
	s_waitcnt lgkmcnt(8)
	v_mfma_f32_32x32x16_bf16 v[16:31], v[148:151], v[88:91], v[16:31]
	v_exp_f32_e32 v104, v104
	v_exp_f32_e32 v105, v105
	s_waitcnt lgkmcnt(4)
	v_mfma_f32_32x32x16_bf16 v[0:15], v[148:151], v[92:95], v[0:15]
	v_exp_f32_e32 v106, v106
	v_exp_f32_e32 v107, v107
	s_waitcnt lgkmcnt(2)
	v_mfma_f32_32x32x16_bf16 v[16:31], v[144:147], v[198:201], v[16:31]
	v_exp_f32_e32 v108, v108
	v_exp_f32_e32 v109, v109
	s_waitcnt lgkmcnt(0)
	v_mfma_f32_32x32x16_bf16 v[0:15], v[144:147], v[202:205], v[0:15]
	v_exp_f32_e32 v110, v110
	v_exp_f32_e32 v111, v111
	s_waitcnt vmcnt(3) lgkmcnt(0)
	s_barrier
; #define WAIT_BAR(N) asm volatile("s_waitcnt vmcnt(" #N ") lgkmcnt(0)\n\ts_barrier":::"memory")
;   #define RESC() do{ if(!NOMAX&&resc){ asm volatile("s_waitcnt lgkmcnt(0)":::"memory"); \
;       _Pragma("unroll") for(int d_=0;d_<2*VM;++d_) _Pragma("unroll") for(int r=0;r<16;++r)o[d_][r]*=wsf[crow(r,hi)]; } }while(0)
;   #define ROT() do{sl_prev=sl_cur;sl_cur=sl_next;sl_next=(sl_next==(NSLOT-1)*SLOTB)?0:sl_next+SLOTB;}while(0)
; template<int THRL,int VM,bool NOMAX> __device__ __forceinline__ void attn_unit(const bf16*Qb,const bf16*__restrict__ Kh,const bf16*__restrict__ Vh,bf16*Ob,const int NT,const int sp,float*wscr,char*shm){
;     ...
;   int t=1;
;   for(;t+5<NT;t+=2){
;     STEP(pB0,pB1,pA0,pA1,t,true,true,true);     if constexpr(VM==2){WAIT_BAR(3);}else{WAIT_BAR(2);} RESC(); ROT();
;     STEP(pA0,pA1,pB0,pB1,t+1,true,true,true);   if constexpr(VM==2){WAIT_BAR(3);}else{WAIT_BAR(2);} RESC(); ROT();
	v_mfma_f32_32x32x16_bf16 v[80:95], v[68:71], v[218:221], 0
	s_add_i32 s88, s86, 0x2000
	s_cmpk_lg_i32 s86, 0x4000
	s_cselect_b32 s88, s88, 0
	v_lshl_add_u32 v206, s87, 1, v188
	ds_read_b64_tr_b16 v[194:195], v206 offset:24576
	ds_read_b64_tr_b16 v[196:197], v206 offset:25088
	v_add_f32_e32 v76, v112, v113
	v_add_f32_e32 v76, v114, v76
	v_add_f32_e32 v76, v115, v76
	v_add_f32_e32 v76, v116, v76
	v_add_f32_e32 v76, v117, v76
	v_cvt_pk_bf16_f32 v156, v112, v113
	v_cvt_pk_bf16_f32 v157, v114, v115
	ds_read_b64_tr_b16 v[112:113], v206 offset:28672
	ds_read_b64_tr_b16 v[114:115], v206 offset:29184
	v_add_f32_e32 v72, v118, v76
	v_add_f32_e32 v72, v119, v72
	v_add_f32_e32 v72, v120, v72
	v_add_f32_e32 v144, v121, v72
	v_mfma_f32_32x32x16_bf16 v[64:79], v[64:67], v[218:221], 0
	v_cvt_pk_bf16_f32 v158, v116, v117
	v_cvt_pk_bf16_f32 v159, v118, v119
	ds_read_b64_tr_b16 v[116:117], v206 offset:25600
	ds_read_b64_tr_b16 v[118:119], v206 offset:26112
	v_add_f32_e32 v144, v122, v144
	v_add_f32_e32 v144, v123, v144
	v_add_f32_e32 v144, v124, v144
	v_add_f32_e32 v144, v125, v144
	v_mfma_f32_32x32x16_bf16 v[80:95], v[164:167], v[222:225], v[80:95]
	v_cvt_pk_bf16_f32 v152, v120, v121
	v_cvt_pk_bf16_f32 v153, v122, v123
	ds_read_b64_tr_b16 v[120:121], v206 offset:29696
	ds_read_b64_tr_b16 v[122:123], v206 offset:30208
	v_add_f32_e32 v144, v126, v144
	v_add_f32_e32 v144, v127, v144
	v_add_f32_e32 v144, v96, v144
	v_add_f32_e32 v144, v97, v144
	v_mfma_f32_32x32x16_bf16 v[64:79], v[140:143], v[222:225], v[64:79]
	v_cvt_pk_bf16_f32 v154, v124, v125
	v_cvt_pk_bf16_f32 v155, v126, v127
	ds_read_b64_tr_b16 v[124:125], v206 offset:26624
	ds_read_b64_tr_b16 v[126:127], v206 offset:27136
	v_add_f32_e32 v144, v98, v144
	v_add_f32_e32 v144, v99, v144
	v_add_f32_e32 v144, v100, v144
	v_add_f32_e32 v144, v101, v144
	v_mfma_f32_32x32x16_bf16 v[80:95], v[160:163], v[226:229], v[80:95]
	v_cvt_pk_bf16_f32 v148, v96, v97
	v_cvt_pk_bf16_f32 v149, v98, v99
	ds_read_b64_tr_b16 v[198:199], v206 offset:30720
	ds_read_b64_tr_b16 v[200:201], v206 offset:31232
	v_add_f32_e32 v140, v102, v144
	v_add_f32_e32 v140, v103, v140
	v_add_f32_e32 v140, v104, v140
	v_add_f32_e32 v140, v105, v140
	v_mfma_f32_32x32x16_bf16 v[64:79], v[132:135], v[226:229], v[64:79]
	v_cvt_pk_bf16_f32 v150, v100, v101
	v_cvt_pk_bf16_f32 v151, v102, v103
	ds_read_b64_tr_b16 v[202:203], v206 offset:27648
	ds_read_b64_tr_b16 v[204:205], v206 offset:28160
	v_add_f32_e32 v100, v106, v140
	v_add_f32_e32 v100, v107, v100
	v_add_f32_e32 v100, v108, v100
	v_add_f32_e32 v100, v109, v100
	v_mfma_f32_32x32x16_bf16 v[80:95], v[136:139], v[230:233], v[80:95]
	v_cvt_pk_bf16_f32 v144, v104, v105
	v_cvt_pk_bf16_f32 v145, v106, v107
	ds_read_b64_tr_b16 v[104:105], v206 offset:31744
	ds_read_b64_tr_b16 v[106:107], v206 offset:32256
	v_add_f32_e32 v100, v110, v100
	v_add_f32_e32 v100, v111, v100
	v_add_f32_e32 v100, 0, v100
	v_cvt_pk_bf16_f32 v146, v108, v109
	v_mfma_f32_32x32x16_bf16 v[64:79], v[128:131], v[230:233], v[64:79]
	v_cvt_pk_bf16_f32 v147, v110, v111
	v_add_f32_e32 v193, v193, v100
	s_waitcnt lgkmcnt(12)
	v_mfma_f32_32x32x16_bf16 v[48:63], v[156:159], v[194:197], v[48:63]
	ds_read_b64_tr_b16 v[108:109], v206 offset:32768
	ds_read_b64_tr_b16 v[110:111], v206 offset:33280
	v_exp_f32_e32 v80, v80
	v_exp_f32_e32 v81, v81
	v_mfma_f32_32x32x16_bf16 v[32:47], v[156:159], v[112:115], v[32:47]
	ds_read_b64_tr_b16 v[194:195], v206 offset:36864
	ds_read_b64_tr_b16 v[196:197], v206 offset:37376
	v_exp_f32_e32 v82, v82
	v_exp_f32_e32 v83, v83
	v_add_u32_e32 v242, s88, v234
	v_add_u32_e32 v243, s88, v235
	v_add_u32_e32 v244, s88, v236
	v_add_u32_e32 v245, s88, v237
	ds_read_b128 v[100:103], v242
	ds_read_b128 v[96:99], v242 offset:4096
	s_waitcnt lgkmcnt(14)
	v_mfma_f32_32x32x16_bf16 v[48:63], v[152:155], v[116:119], v[48:63]
	ds_read_b64_tr_b16 v[112:113], v206 offset:33792
	ds_read_b64_tr_b16 v[114:115], v206 offset:34304
	v_exp_f32_e32 v84, v84
	v_exp_f32_e32 v85, v85
	ds_read_b128 v[164:167], v243
	ds_read_b128 v[160:163], v243 offset:4096
	v_mfma_f32_32x32x16_bf16 v[32:47], v[152:155], v[120:123], v[32:47]
	ds_read_b64_tr_b16 v[116:117], v206 offset:37888
	ds_read_b64_tr_b16 v[118:119], v206 offset:38400
	v_exp_f32_e32 v86, v86
	v_exp_f32_e32 v87, v87
	ds_read_b128 v[140:143], v244
	ds_read_b128 v[136:139], v244 offset:4096
	s_waitcnt lgkmcnt(14)
	v_mfma_f32_32x32x16_bf16 v[48:63], v[148:151], v[124:127], v[48:63]
	ds_read_b64_tr_b16 v[120:121], v206 offset:34816
	ds_read_b64_tr_b16 v[122:123], v206 offset:35328
	v_exp_f32_e32 v88, v88
	v_exp_f32_e32 v89, v89
	ds_read_b128 v[132:135], v245
	ds_read_b128 v[128:131], v245 offset:4096
	v_mfma_f32_32x32x16_bf16 v[32:47], v[148:151], v[198:201], v[32:47]
	ds_read_b64_tr_b16 v[124:125], v206 offset:38912
	ds_read_b64_tr_b16 v[126:127], v206 offset:39424
	v_exp_f32_e32 v90, v90
	v_exp_f32_e32 v91, v91
	s_waitcnt lgkmcnt(14)
	v_mfma_f32_32x32x16_bf16 v[48:63], v[144:147], v[202:205], v[48:63]
	ds_read_b64_tr_b16 v[198:199], v206 offset:35840
	ds_read_b64_tr_b16 v[200:201], v206 offset:36352
	v_exp_f32_e32 v92, v92
	v_exp_f32_e32 v93, v93
	v_mfma_f32_32x32x16_bf16 v[32:47], v[144:147], v[104:107], v[32:47]
	ds_read_b64_tr_b16 v[202:203], v206 offset:39936
	ds_read_b64_tr_b16 v[204:205], v206 offset:40448
	v_exp_f32_e32 v94, v94
	v_exp_f32_e32 v95, v95
	s_waitcnt lgkmcnt(14)
	v_mfma_f32_32x32x16_bf16 v[16:31], v[156:159], v[108:111], v[16:31]
	s_add_i32 s87, s86, s17
	s_mov_b32 s89, m0
	s_mov_b32 m0, s87
	s_nop 0
	global_load_lds_dwordx4 v[180:181], off
	s_mov_b32 m0, s89
	v_exp_f32_e32 v64, v64
	v_exp_f32_e32 v65, v65
	v_mfma_f32_32x32x16_bf16 v[0:15], v[156:159], v[194:197], v[0:15]
	s_lshl_b32 s87, s88, 1
	s_add_i32 s87, s87, s16
	s_mov_b32 s89, m0
	s_mov_b32 m0, s87
	s_nop 0
	global_load_lds_dwordx4 v[178:179], off
	s_mov_b32 m0, s89
	v_exp_f32_e32 v66, v66
	v_exp_f32_e32 v67, v67
	v_mfma_f32_32x32x16_bf16 v[16:31], v[152:155], v[112:115], v[16:31]
	s_addk_i32 s87, 0x2000
	s_mov_b32 s89, m0
	s_mov_b32 m0, s87
	s_nop 0
	global_load_lds_dwordx4 v[176:177], off
	s_mov_b32 m0, s89
	v_exp_f32_e32 v68, v68
	v_exp_f32_e32 v69, v69
	s_waitcnt lgkmcnt(12)
	v_mfma_f32_32x32x16_bf16 v[0:15], v[152:155], v[116:119], v[0:15]
	v_exp_f32_e32 v70, v70
	v_exp_f32_e32 v71, v71
	s_waitcnt lgkmcnt(8)
	v_mfma_f32_32x32x16_bf16 v[16:31], v[148:151], v[120:123], v[16:31]
	v_exp_f32_e32 v72, v72
	v_exp_f32_e32 v73, v73
	s_waitcnt lgkmcnt(4)
	v_mfma_f32_32x32x16_bf16 v[0:15], v[148:151], v[124:127], v[0:15]
	v_exp_f32_e32 v74, v74
	v_exp_f32_e32 v75, v75
	s_waitcnt lgkmcnt(2)
	v_mfma_f32_32x32x16_bf16 v[16:31], v[144:147], v[198:201], v[16:31]
	v_exp_f32_e32 v76, v76
	v_exp_f32_e32 v77, v77
	s_waitcnt lgkmcnt(0)
	v_mfma_f32_32x32x16_bf16 v[0:15], v[144:147], v[202:205], v[0:15]
	v_exp_f32_e32 v78, v78
	v_exp_f32_e32 v79, v79
	s_add_i32 s90, s88, 0x2000
	s_waitcnt vmcnt(3) lgkmcnt(0)
	s_barrier
; #define WAIT_BAR(N) asm volatile("s_waitcnt vmcnt(" #N ") lgkmcnt(0)\n\ts_barrier":::"memory")
;   #define RESC() do{ if(!NOMAX&&resc){ asm volatile("s_waitcnt lgkmcnt(0)":::"memory"); \
;       _Pragma("unroll") for(int d_=0;d_<2*VM;++d_) _Pragma("unroll") for(int r=0;r<16;++r)o[d_][r]*=wsf[crow(r,hi)]; } }while(0)
;   #define ROT() do{sl_prev=sl_cur;sl_cur=sl_next;sl_next=(sl_next==(NSLOT-1)*SLOTB)?0:sl_next+SLOTB;}while(0)
;   #define ENDW(tt) do{ if((tt)+3<NT){ if constexpr(VM==2){WAIT_BAR(3);}else{WAIT_BAR(2);} } else if((tt)+2<NT){ if constexpr(VM==2){WAIT_BAR(2);}else{WAIT_BAR(1);} } else {WAIT_BAR(0);} }while(0)
; template<int THRL,int VM,bool NOMAX> __device__ __forceinline__ void attn_unit(const bf16*Qb,const bf16*__restrict__ Kh,const bf16*__restrict__ Vh,bf16*Ob,const int NT,const int sp,float*wscr,char*shm){
;     ...
;   int t=1;
;   for(;t+5<NT;t+=2){
;     STEP(pB0,pB1,pA0,pA1,t,true,true,true);     if constexpr(VM==2){WAIT_BAR(3);}else{WAIT_BAR(2);} RESC(); ROT();
;     STEP(pA0,pA1,pB0,pB1,t+1,true,true,true);   if constexpr(VM==2){WAIT_BAR(3);}else{WAIT_BAR(2);} RESC(); ROT();
;   }
;     ...
;   for(;t+1<NT;t+=2){
;     STEP(pB0,pB1,pA0,pA1,t,(t+3<NT),(t+1<NT),(t+1<NT));       ENDW(t);   RESC(); ROT();
	s_cmpk_lg_i32 s88, 0x4000
	s_mov_b32 s89, s86
	s_cselect_b32 s86, s90, 0
	s_add_i32 s85, s85, 2
	v_lshl_add_u64 v[176:177], v[176:177], 0, s[58:59]
	v_lshl_add_u64 v[178:179], v[178:179], 0, s[58:59]
	v_lshl_add_u64 v[180:181], v[180:181], 0, s[58:59]
	s_mov_b32 s87, s88
	s_cmp_lt_u32 s85, 57
	s_cbranch_scc1 .LBB0_874
	s_and_b32 s34, s34, 0x3fffffc0
	s_lshl_b32 s34, s34, 2
	s_add_i32 s34, s34, 0
	s_add_i32 s34, s34, 0x12000
	s_cmp_lg_u32 0, -1
	s_cselect_b32 s85, 0, 0
	s_add_i32 s86, s85, 0x6000
	v_add_u32_e32 v104, s86, v191
	v_add3_u32 v176, v104, v190, v192
	v_add_u32_e32 v177, 0x6000, v188
	ds_read_b64_tr_b16 v[178:179], v188 offset:40960
	ds_read_b64_tr_b16 v[180:181], v188 offset:41472
	v_add_f32_e32 v108, v80, v81
	ds_read_b128 v[104:107], v168
	v_add_f32_e32 v108, v82, v108
	v_add_f32_e32 v108, v83, v108
	v_add_f32_e32 v108, v84, v108
	v_add_f32_e32 v108, v85, v108
	v_cvt_pk_bf16_f32 v156, v80, v81
	v_cvt_pk_bf16_f32 v157, v82, v83
	s_waitcnt lgkmcnt(0)
	v_mfma_f32_32x32x16_bf16 v[112:127], v[100:103], v[104:107], 0
	ds_read_b64_tr_b16 v[80:81], v188 offset:45056
	ds_read_b64_tr_b16 v[82:83], v188 offset:45568
	ds_read_b128 v[100:103], v168
	v_add_f32_e32 v104, v86, v108
	v_add_f32_e32 v104, v87, v104
	v_add_f32_e32 v104, v88, v104
	v_add_f32_e32 v144, v89, v104
	v_cvt_pk_bf16_f32 v158, v84, v85
	v_cvt_pk_bf16_f32 v159, v86, v87
	s_waitcnt lgkmcnt(0)
	v_mfma_f32_32x32x16_bf16 v[96:111], v[96:99], v[100:103], 0
	ds_read_b64_tr_b16 v[84:85], v188 offset:41984
	ds_read_b64_tr_b16 v[86:87], v188 offset:42496
	ds_read_b128 v[194:197], v168 offset:1024
	v_add_f32_e32 v144, v90, v144
	v_add_f32_e32 v144, v91, v144
	v_add_f32_e32 v144, v92, v144
	v_add_f32_e32 v144, v93, v144
	v_cvt_pk_bf16_f32 v152, v88, v89
	v_cvt_pk_bf16_f32 v153, v90, v91
	s_waitcnt lgkmcnt(0)
	v_mfma_f32_32x32x16_bf16 v[112:127], v[164:167], v[194:197], v[112:127]
	ds_read_b64_tr_b16 v[88:89], v188 offset:46080
	ds_read_b64_tr_b16 v[90:91], v188 offset:46592
	ds_read_b128 v[164:167], v168 offset:1024
	v_add_f32_e32 v144, v94, v144
	v_add_f32_e32 v144, v95, v144
	v_add_f32_e32 v144, v64, v144
	v_add_f32_e32 v144, v65, v144
	v_cvt_pk_bf16_f32 v154, v92, v93
	v_cvt_pk_bf16_f32 v155, v94, v95
	s_waitcnt lgkmcnt(0)
	v_mfma_f32_32x32x16_bf16 v[96:111], v[160:163], v[164:167], v[96:111]
	ds_read_b64_tr_b16 v[194:195], v188 offset:43008
	ds_read_b64_tr_b16 v[196:197], v188 offset:43520
	ds_read_b128 v[92:95], v168 offset:2048
	v_add_f32_e32 v144, v66, v144
	v_add_f32_e32 v144, v67, v144
	v_add_f32_e32 v144, v68, v144
	v_add_f32_e32 v144, v69, v144
	v_cvt_pk_bf16_f32 v148, v64, v65
	v_cvt_pk_bf16_f32 v149, v66, v67
	s_waitcnt lgkmcnt(0)
	v_mfma_f32_32x32x16_bf16 v[112:127], v[140:143], v[92:95], v[112:127]
	ds_read_b64_tr_b16 v[140:141], v188 offset:47104
	ds_read_b64_tr_b16 v[142:143], v188 offset:47616
	ds_read_b128 v[64:67], v168 offset:2048
	v_add_f32_e32 v92, v70, v144
	v_add_f32_e32 v92, v71, v92
	v_add_f32_e32 v92, v72, v92
	v_add_f32_e32 v92, v73, v92
	v_cvt_pk_bf16_f32 v150, v68, v69
	v_cvt_pk_bf16_f32 v151, v70, v71
	s_waitcnt lgkmcnt(0)
	v_mfma_f32_32x32x16_bf16 v[96:111], v[136:139], v[64:67], v[96:111]
	ds_read_b64_tr_b16 v[136:137], v188 offset:44032
	ds_read_b64_tr_b16 v[138:139], v188 offset:44544
	ds_read_b128 v[64:67], v168 offset:3072
	v_add_f32_e32 v68, v74, v92
	v_add_f32_e32 v68, v75, v68
	v_add_f32_e32 v68, v76, v68
	v_add_f32_e32 v68, v77, v68
	v_cvt_pk_bf16_f32 v144, v72, v73
	v_cvt_pk_bf16_f32 v145, v74, v75
	s_waitcnt lgkmcnt(0)
	v_mfma_f32_32x32x16_bf16 v[112:127], v[132:135], v[64:67], v[112:127]
	ds_read_b64_tr_b16 v[72:73], v188 offset:48128
	ds_read_b64_tr_b16 v[74:75], v188 offset:48640
	ds_read_b128 v[64:67], v168 offset:3072
	v_add_f32_e32 v68, v78, v68
	v_add_f32_e32 v68, v79, v68
	v_add_f32_e32 v68, 0, v68
	v_cvt_pk_bf16_f32 v146, v76, v77
	v_cvt_pk_bf16_f32 v147, v78, v79
	s_waitcnt lgkmcnt(0)
	v_mfma_f32_32x32x16_bf16 v[96:111], v[128:131], v[64:67], v[96:111]
	s_add_i32 s85, s85, s35
	v_lshl_add_u64 v[64:65], v[174:175], 0, s[60:61]
	s_add_i32 s35, s85, 0x4000
	s_mov_b32 s86, m0
	s_mov_b32 m0, s35
	s_nop 0
	global_load_lds_dwordx4 v[64:65], off
	s_mov_b32 m0, s86
	v_lshl_add_u64 v[64:65], v[170:171], 0, s[62:63]
	s_mov_b32 s35, m0
	s_mov_b32 m0, s16
	s_nop 0
	global_load_lds_dwordx4 v[64:65], off
	s_mov_b32 m0, s35
	v_lshl_add_u64 v[64:65], v[172:173], 0, s[62:63]
	s_add_i32 s35, s16, 0x2000
	s_mov_b32 s86, m0
	s_mov_b32 m0, s35
	s_nop 0
	global_load_lds_dwordx4 v[64:65], off
	s_mov_b32 m0, s86
	v_add_f32_e32 v198, v193, v68
	v_mfma_f32_32x32x16_bf16 v[48:63], v[156:159], v[178:181], v[48:63]
	ds_read_b64_tr_b16 v[76:77], v188 offset:49152
	ds_read_b64_tr_b16 v[78:79], v188 offset:49664
	v_exp_f32_e32 v112, v112
	v_exp_f32_e32 v113, v113
	v_mfma_f32_32x32x16_bf16 v[32:47], v[156:159], v[80:83], v[32:47]
	ds_read_b64_tr_b16 v[128:129], v188 offset:53248
	ds_read_b64_tr_b16 v[130:131], v188 offset:53760
	v_exp_f32_e32 v114, v114
	v_exp_f32_e32 v115, v115
	ds_read_b128 v[68:71], v234
	ds_read_b128 v[64:67], v234 offset:4096
	v_mfma_f32_32x32x16_bf16 v[48:63], v[152:155], v[84:87], v[48:63]
	ds_read_b64_tr_b16 v[132:133], v188 offset:50176
	ds_read_b64_tr_b16 v[134:135], v188 offset:50688
	v_exp_f32_e32 v116, v116
	v_exp_f32_e32 v117, v117
	ds_read_b128 v[164:167], v235
	ds_read_b128 v[92:95], v235 offset:4096
	v_mfma_f32_32x32x16_bf16 v[32:47], v[152:155], v[88:91], v[32:47]
	ds_read_b64_tr_b16 v[178:179], v188 offset:54272
	ds_read_b64_tr_b16 v[180:181], v188 offset:54784
	v_exp_f32_e32 v118, v118
	v_exp_f32_e32 v119, v119
	ds_read_b128 v[160:163], v236
	ds_read_b128 v[84:87], v236 offset:4096
	v_mfma_f32_32x32x16_bf16 v[48:63], v[148:151], v[194:197], v[48:63]
	ds_read_b64_tr_b16 v[190:191], v188 offset:51200
	ds_read_b64_tr_b16 v[192:193], v188 offset:51712
	v_exp_f32_e32 v120, v120
	v_exp_f32_e32 v121, v121
	ds_read_b128 v[88:91], v237
	ds_read_b128 v[80:83], v237 offset:4096
	v_mfma_f32_32x32x16_bf16 v[32:47], v[148:151], v[140:143], v[32:47]
	ds_read_b64_tr_b16 v[194:195], v188 offset:55296
	ds_read_b64_tr_b16 v[196:197], v188 offset:55808
	v_exp_f32_e32 v122, v122
	v_exp_f32_e32 v123, v123
	v_mfma_f32_32x32x16_bf16 v[48:63], v[144:147], v[136:139], v[48:63]
	ds_read_b64_tr_b16 v[140:141], v188 offset:52224
	ds_read_b64_tr_b16 v[142:143], v188 offset:52736
	v_exp_f32_e32 v124, v124
	v_exp_f32_e32 v125, v125
	v_mfma_f32_32x32x16_bf16 v[32:47], v[144:147], v[72:75], v[32:47]
	ds_read_b64_tr_b16 v[136:137], v188 offset:56320
	ds_read_b64_tr_b16 v[138:139], v188 offset:56832
	v_exp_f32_e32 v126, v126
	v_exp_f32_e32 v127, v127
	s_waitcnt lgkmcnt(14)
; #define WAIT_BAR(N) asm volatile("s_waitcnt vmcnt(" #N ") lgkmcnt(0)\n\ts_barrier":::"memory")
;   #define RESC() do{ if(!NOMAX&&resc){ asm volatile("s_waitcnt lgkmcnt(0)":::"memory"); \
;       _Pragma("unroll") for(int d_=0;d_<2*VM;++d_) _Pragma("unroll") for(int r=0;r<16;++r)o[d_][r]*=wsf[crow(r,hi)]; } }while(0)
;   #define ROT() do{sl_prev=sl_cur;sl_cur=sl_next;sl_next=(sl_next==(NSLOT-1)*SLOTB)?0:sl_next+SLOTB;}while(0)
;   #define ENDW(tt) do{ if((tt)+3<NT){ if constexpr(VM==2){WAIT_BAR(3);}else{WAIT_BAR(2);} } else if((tt)+2<NT){ if constexpr(VM==2){WAIT_BAR(2);}else{WAIT_BAR(1);} } else {WAIT_BAR(0);} }while(0)
; template<int THRL,int VM,bool NOMAX> __device__ __forceinline__ void attn_unit(const bf16*Qb,const bf16*__restrict__ Kh,const bf16*__restrict__ Vh,bf16*Ob,const int NT,const int sp,float*wscr,char*shm){
;     ...
;   int t=1;
;   for(;t+5<NT;t+=2){
;     STEP(pB0,pB1,pA0,pA1,t,true,true,true);     if constexpr(VM==2){WAIT_BAR(3);}else{WAIT_BAR(2);} RESC(); ROT();
;     STEP(pA0,pA1,pB0,pB1,t+1,true,true,true);   if constexpr(VM==2){WAIT_BAR(3);}else{WAIT_BAR(2);} RESC(); ROT();
;   }
;     ...
;   for(;t+1<NT;t+=2){
;     STEP(pB0,pB1,pA0,pA1,t,(t+3<NT),(t+1<NT),(t+1<NT));       ENDW(t);   RESC(); ROT();
;     STEP(pA0,pA1,pB0,pB1,t+1,(t+4<NT),(t+2<NT),(t+2<NT));     ENDW(t+1); RESC(); ROT();
	v_mfma_f32_32x32x16_bf16 v[16:31], v[156:159], v[76:79], v[16:31]
	v_exp_f32_e32 v96, v96
	v_exp_f32_e32 v97, v97
	v_mfma_f32_32x32x16_bf16 v[0:15], v[156:159], v[128:131], v[0:15]
	v_exp_f32_e32 v98, v98
	v_exp_f32_e32 v99, v99
	v_mfma_f32_32x32x16_bf16 v[16:31], v[152:155], v[132:135], v[16:31]
	v_exp_f32_e32 v100, v100
	v_exp_f32_e32 v101, v101
	s_waitcnt lgkmcnt(12)
	v_mfma_f32_32x32x16_bf16 v[0:15], v[152:155], v[178:181], v[0:15]
	v_exp_f32_e32 v102, v102
	v_exp_f32_e32 v103, v103
	s_waitcnt lgkmcnt(8)
	v_mfma_f32_32x32x16_bf16 v[16:31], v[148:151], v[190:193], v[16:31]
	v_exp_f32_e32 v104, v104
	v_exp_f32_e32 v105, v105
	s_waitcnt lgkmcnt(4)
	v_mfma_f32_32x32x16_bf16 v[0:15], v[148:151], v[194:197], v[0:15]
	v_exp_f32_e32 v106, v106
	v_exp_f32_e32 v107, v107
	s_waitcnt lgkmcnt(2)
	v_mfma_f32_32x32x16_bf16 v[16:31], v[144:147], v[140:143], v[16:31]
	v_exp_f32_e32 v108, v108
	v_exp_f32_e32 v109, v109
	s_waitcnt lgkmcnt(0)
	v_mfma_f32_32x32x16_bf16 v[0:15], v[144:147], v[136:139], v[0:15]
	v_exp_f32_e32 v110, v110
	v_exp_f32_e32 v111, v111
	s_waitcnt vmcnt(3) lgkmcnt(0)
	s_barrier
	ds_read_b64_tr_b16 v[178:179], v188 offset:57344
	ds_read_b64_tr_b16 v[180:181], v188 offset:57856
	v_add_f32_e32 v76, v112, v113
	ds_read_b128 v[72:75], v168
	v_add_f32_e32 v76, v114, v76
	v_add_f32_e32 v76, v115, v76
	v_add_f32_e32 v76, v116, v76
	v_add_f32_e32 v76, v117, v76
	v_cvt_pk_bf16_f32 v156, v112, v113
	v_cvt_pk_bf16_f32 v157, v114, v115
	s_waitcnt lgkmcnt(0)
	v_mfma_f32_32x32x16_bf16 v[128:143], v[68:71], v[72:75], 0
	ds_read_b64_tr_b16 v[112:113], v188 offset:61440
	ds_read_b64_tr_b16 v[114:115], v188 offset:61952
	ds_read_b128 v[68:71], v168
	v_add_f32_e32 v72, v118, v76
	v_add_f32_e32 v72, v119, v72
	v_add_f32_e32 v72, v120, v72
	v_add_f32_e32 v144, v121, v72
	s_waitcnt lgkmcnt(0)
	v_mfma_f32_32x32x16_bf16 v[64:79], v[64:67], v[68:71], 0
	v_cvt_pk_bf16_f32 v158, v116, v117
	v_cvt_pk_bf16_f32 v159, v118, v119
	ds_read_b64_tr_b16 v[116:117], v188 offset:58368
	ds_read_b64_tr_b16 v[118:119], v188 offset:58880
	ds_read_b128 v[190:193], v168 offset:1024
	v_add_f32_e32 v144, v122, v144
	v_add_f32_e32 v144, v123, v144
	v_add_f32_e32 v144, v124, v144
	v_add_f32_e32 v144, v125, v144
	v_cvt_pk_bf16_f32 v152, v120, v121
	v_cvt_pk_bf16_f32 v153, v122, v123
	s_waitcnt lgkmcnt(0)
	v_mfma_f32_32x32x16_bf16 v[128:143], v[164:167], v[190:193], v[128:143]
	ds_read_b64_tr_b16 v[120:121], v188 offset:62464
	ds_read_b64_tr_b16 v[122:123], v188 offset:62976
	ds_read_b128 v[164:167], v168 offset:1024
	v_add_f32_e32 v144, v126, v144
	v_add_f32_e32 v144, v127, v144
	v_add_f32_e32 v144, v96, v144
	v_add_f32_e32 v144, v97, v144
	s_waitcnt lgkmcnt(0)
	v_mfma_f32_32x32x16_bf16 v[64:79], v[92:95], v[164:167], v[64:79]
	v_cvt_pk_bf16_f32 v154, v124, v125
	v_cvt_pk_bf16_f32 v155, v126, v127
	ds_read_b64_tr_b16 v[92:93], v188 offset:59392
	ds_read_b64_tr_b16 v[94:95], v188 offset:59904
	ds_read_b128 v[124:127], v168 offset:2048
	v_add_f32_e32 v144, v98, v144
	v_add_f32_e32 v144, v99, v144
	v_add_f32_e32 v144, v100, v144
	v_add_f32_e32 v144, v101, v144
	v_cvt_pk_bf16_f32 v148, v96, v97
	v_cvt_pk_bf16_f32 v149, v98, v99
	s_waitcnt lgkmcnt(0)
	v_mfma_f32_32x32x16_bf16 v[128:143], v[160:163], v[124:127], v[128:143]
	ds_read_b64_tr_b16 v[96:97], v188 offset:63488
	ds_read_b64_tr_b16 v[98:99], v188 offset:64000
	ds_read_b128 v[124:127], v168 offset:2048
	v_add_f32_e32 v144, v102, v144
	v_add_f32_e32 v144, v103, v144
	v_add_f32_e32 v144, v104, v144
	v_add_f32_e32 v144, v105, v144
	s_waitcnt lgkmcnt(0)
	v_mfma_f32_32x32x16_bf16 v[64:79], v[84:87], v[124:127], v[64:79]
	v_cvt_pk_bf16_f32 v150, v100, v101
	v_cvt_pk_bf16_f32 v151, v102, v103
	ds_read_b64_tr_b16 v[100:101], v188 offset:60416
	ds_read_b64_tr_b16 v[102:103], v188 offset:60928
	ds_read_b128 v[84:87], v168 offset:3072
	v_add_f32_e32 v124, v106, v144
	v_add_f32_e32 v124, v107, v124
	v_add_f32_e32 v124, v108, v124
	v_add_f32_e32 v124, v109, v124
	v_cvt_pk_bf16_f32 v144, v104, v105
	v_cvt_pk_bf16_f32 v145, v106, v107
	s_waitcnt lgkmcnt(0)
	v_mfma_f32_32x32x16_bf16 v[128:143], v[88:91], v[84:87], v[128:143]
	ds_read_b64_tr_b16 v[88:89], v188 offset:64512
	ds_read_b64_tr_b16 v[90:91], v188 offset:65024
	ds_read_b128 v[84:87], v168 offset:3072
	v_add_f32_e32 v104, v110, v124
	v_add_f32_e32 v104, v111, v104
	v_add_f32_e32 v104, 0, v104
	v_cvt_pk_bf16_f32 v146, v108, v109
	s_waitcnt lgkmcnt(0)
; #define WAIT_BAR(N) asm volatile("s_waitcnt vmcnt(" #N ") lgkmcnt(0)\n\ts_barrier":::"memory")
;   #define RESC() do{ if(!NOMAX&&resc){ asm volatile("s_waitcnt lgkmcnt(0)":::"memory"); \
;       _Pragma("unroll") for(int d_=0;d_<2*VM;++d_) _Pragma("unroll") for(int r=0;r<16;++r)o[d_][r]*=wsf[crow(r,hi)]; } }while(0)
;   #define ROT() do{sl_prev=sl_cur;sl_cur=sl_next;sl_next=(sl_next==(NSLOT-1)*SLOTB)?0:sl_next+SLOTB;}while(0)
;   #define ENDW(tt) do{ if((tt)+3<NT){ if constexpr(VM==2){WAIT_BAR(3);}else{WAIT_BAR(2);} } else if((tt)+2<NT){ if constexpr(VM==2){WAIT_BAR(2);}else{WAIT_BAR(1);} } else {WAIT_BAR(0);} }while(0)
; template<int THRL,int VM,bool NOMAX> __device__ __forceinline__ void attn_unit(const bf16*Qb,const bf16*__restrict__ Kh,const bf16*__restrict__ Vh,bf16*Ob,const int NT,const int sp,float*wscr,char*shm){
;     ...
;   int t=1;
;   for(;t+5<NT;t+=2){
;     STEP(pB0,pB1,pA0,pA1,t,true,true,true);     if constexpr(VM==2){WAIT_BAR(3);}else{WAIT_BAR(2);} RESC(); ROT();
;     STEP(pA0,pA1,pB0,pB1,t+1,true,true,true);   if constexpr(VM==2){WAIT_BAR(3);}else{WAIT_BAR(2);} RESC(); ROT();
;   }
;     ...
;   for(;t+1<NT;t+=2){
;     STEP(pB0,pB1,pA0,pA1,t,(t+3<NT),(t+1<NT),(t+1<NT));       ENDW(t);   RESC(); ROT();
;     STEP(pA0,pA1,pB0,pB1,t+1,(t+4<NT),(t+2<NT),(t+2<NT));     ENDW(t+1); RESC(); ROT();
	v_mfma_f32_32x32x16_bf16 v[64:79], v[80:83], v[84:87], v[64:79]
	v_cvt_pk_bf16_f32 v147, v110, v111
	v_lshl_add_u64 v[80:81], v[174:175], 0, s[64:65]
	s_mov_b32 s86, m0
	s_mov_b32 m0, s17
	s_nop 0
	global_load_lds_dwordx4 v[80:81], off
	s_mov_b32 m0, s86
	v_lshl_add_u64 v[80:81], v[170:171], 0, s[66:67]
	s_add_i32 s17, s85, 0xa000
	s_mov_b32 s86, m0
	s_mov_b32 m0, s17
	s_nop 0
	global_load_lds_dwordx4 v[80:81], off
	s_mov_b32 m0, s86
	v_lshl_add_u64 v[80:81], v[172:173], 0, s[66:67]
	s_add_i32 s17, s85, 0xc000
	s_mov_b32 s86, m0
	s_mov_b32 m0, s17
	s_nop 0
	global_load_lds_dwordx4 v[80:81], off
	s_mov_b32 m0, s86
	v_add_f32_e32 v198, v198, v104
	v_mfma_f32_32x32x16_bf16 v[48:63], v[156:159], v[178:181], v[48:63]
	ds_read_b64_tr_b16 v[104:105], v177 offset:40960
	ds_read_b64_tr_b16 v[106:107], v177 offset:41472
	v_exp_f32_e32 v128, v128
	v_exp_f32_e32 v129, v129
	v_mfma_f32_32x32x16_bf16 v[32:47], v[156:159], v[112:115], v[32:47]
	ds_read_b64_tr_b16 v[108:109], v177 offset:45056
	ds_read_b64_tr_b16 v[110:111], v177 offset:45568
	v_exp_f32_e32 v130, v130
	v_exp_f32_e32 v131, v131
	ds_read_b128 v[84:87], v234 offset:8192
	ds_read_b128 v[80:83], v234 offset:12288
	v_mfma_f32_32x32x16_bf16 v[48:63], v[152:155], v[116:119], v[48:63]
	ds_read_b64_tr_b16 v[178:179], v177 offset:41984
	ds_read_b64_tr_b16 v[180:181], v177 offset:42496
	v_exp_f32_e32 v132, v132
	v_exp_f32_e32 v133, v133
	ds_read_b128 v[164:167], v235 offset:8192
	ds_read_b128 v[124:127], v235 offset:12288
	v_mfma_f32_32x32x16_bf16 v[32:47], v[152:155], v[120:123], v[32:47]
	ds_read_b64_tr_b16 v[190:191], v177 offset:46080
	ds_read_b64_tr_b16 v[192:193], v177 offset:46592
	v_exp_f32_e32 v134, v134
	v_exp_f32_e32 v135, v135
	ds_read_b128 v[160:163], v236 offset:8192
	ds_read_b128 v[116:119], v236 offset:12288
	v_mfma_f32_32x32x16_bf16 v[48:63], v[148:151], v[92:95], v[48:63]
	ds_read_b64_tr_b16 v[194:195], v177 offset:43008
	ds_read_b64_tr_b16 v[196:197], v177 offset:43520
	v_exp_f32_e32 v136, v136
	v_exp_f32_e32 v137, v137
	ds_read_b128 v[120:123], v237 offset:8192
	ds_read_b128 v[112:115], v237 offset:12288
	v_mfma_f32_32x32x16_bf16 v[32:47], v[148:151], v[96:99], v[32:47]
	ds_read_b64_tr_b16 v[92:93], v177 offset:47104
	ds_read_b64_tr_b16 v[94:95], v177 offset:47616
	v_exp_f32_e32 v138, v138
	v_exp_f32_e32 v139, v139
	v_mfma_f32_32x32x16_bf16 v[48:63], v[144:147], v[100:103], v[48:63]
	ds_read_b64_tr_b16 v[96:97], v177 offset:44032
	ds_read_b64_tr_b16 v[98:99], v177 offset:44544
	v_exp_f32_e32 v140, v140
	v_exp_f32_e32 v141, v141
	v_mfma_f32_32x32x16_bf16 v[32:47], v[144:147], v[88:91], v[32:47]
	ds_read_b64_tr_b16 v[100:101], v177 offset:48128
	ds_read_b64_tr_b16 v[102:103], v177 offset:48640
	v_exp_f32_e32 v142, v142
	v_exp_f32_e32 v143, v143
	s_waitcnt lgkmcnt(14)
	v_mfma_f32_32x32x16_bf16 v[16:31], v[156:159], v[104:107], v[16:31]
	v_exp_f32_e32 v64, v64
	v_exp_f32_e32 v65, v65
	v_mfma_f32_32x32x16_bf16 v[0:15], v[156:159], v[108:111], v[0:15]
	v_exp_f32_e32 v66, v66
	v_exp_f32_e32 v67, v67
	v_mfma_f32_32x32x16_bf16 v[16:31], v[152:155], v[178:181], v[16:31]
	v_exp_f32_e32 v68, v68
	v_exp_f32_e32 v69, v69
	s_waitcnt lgkmcnt(12)
	v_mfma_f32_32x32x16_bf16 v[0:15], v[152:155], v[190:193], v[0:15]
	v_exp_f32_e32 v70, v70
	v_exp_f32_e32 v71, v71
	s_waitcnt lgkmcnt(8)
	v_mfma_f32_32x32x16_bf16 v[16:31], v[148:151], v[194:197], v[16:31]
	v_exp_f32_e32 v72, v72
	v_exp_f32_e32 v73, v73
	s_waitcnt lgkmcnt(4)
	v_mfma_f32_32x32x16_bf16 v[0:15], v[148:151], v[92:95], v[0:15]
	v_exp_f32_e32 v74, v74
	v_exp_f32_e32 v75, v75
	s_waitcnt lgkmcnt(2)
	v_mfma_f32_32x32x16_bf16 v[16:31], v[144:147], v[96:99], v[16:31]
	v_exp_f32_e32 v76, v76
	v_exp_f32_e32 v77, v77
	s_waitcnt lgkmcnt(0)
	v_mfma_f32_32x32x16_bf16 v[0:15], v[144:147], v[100:103], v[0:15]
	v_exp_f32_e32 v78, v78
	v_exp_f32_e32 v79, v79
	s_waitcnt vmcnt(3) lgkmcnt(0)
	s_barrier
	ds_read_b64_tr_b16 v[178:179], v188 offset:24576
	ds_read_b64_tr_b16 v[180:181], v188 offset:25088
	v_add_f32_e32 v92, v128, v129
	ds_read_b128 v[88:91], v168
	v_add_f32_e32 v92, v130, v92
	v_add_f32_e32 v92, v131, v92
	v_add_f32_e32 v92, v132, v92
	v_add_f32_e32 v92, v133, v92
	v_cvt_pk_bf16_f32 v156, v128, v129
	v_cvt_pk_bf16_f32 v157, v130, v131
	s_waitcnt lgkmcnt(0)
	v_mfma_f32_32x32x16_bf16 v[96:111], v[84:87], v[88:91], 0
	ds_read_b64_tr_b16 v[128:129], v188 offset:28672
	ds_read_b64_tr_b16 v[130:131], v188 offset:29184
	ds_read_b128 v[84:87], v168
	v_add_f32_e32 v88, v134, v92
	v_add_f32_e32 v88, v135, v88
	v_add_f32_e32 v88, v136, v88
	v_add_f32_e32 v144, v137, v88
	v_cvt_pk_bf16_f32 v158, v132, v133
	v_cvt_pk_bf16_f32 v159, v134, v135
	s_waitcnt lgkmcnt(0)
	v_mfma_f32_32x32x16_bf16 v[80:95], v[80:83], v[84:87], 0
	ds_read_b64_tr_b16 v[132:133], v188 offset:25600
	ds_read_b64_tr_b16 v[134:135], v188 offset:26112
	ds_read_b128 v[190:193], v168 offset:1024
	v_add_f32_e32 v144, v138, v144
	v_add_f32_e32 v144, v139, v144
	v_add_f32_e32 v144, v140, v144
	v_add_f32_e32 v144, v141, v144
	v_cvt_pk_bf16_f32 v152, v136, v137
	v_cvt_pk_bf16_f32 v153, v138, v139
	s_waitcnt lgkmcnt(0)
	v_mfma_f32_32x32x16_bf16 v[96:111], v[164:167], v[190:193], v[96:111]
	ds_read_b64_tr_b16 v[136:137], v188 offset:29696
	ds_read_b64_tr_b16 v[138:139], v188 offset:30208
	ds_read_b128 v[164:167], v168 offset:1024
	v_add_f32_e32 v144, v142, v144
	v_add_f32_e32 v144, v143, v144
	v_add_f32_e32 v144, v64, v144
	v_add_f32_e32 v144, v65, v144
	v_cvt_pk_bf16_f32 v154, v140, v141
	v_cvt_pk_bf16_f32 v155, v142, v143
	s_waitcnt lgkmcnt(0)
; #define WAIT_BAR(N) asm volatile("s_waitcnt vmcnt(" #N ") lgkmcnt(0)\n\ts_barrier":::"memory")
;   #define RESC() do{ if(!NOMAX&&resc){ asm volatile("s_waitcnt lgkmcnt(0)":::"memory"); \
;       _Pragma("unroll") for(int d_=0;d_<2*VM;++d_) _Pragma("unroll") for(int r=0;r<16;++r)o[d_][r]*=wsf[crow(r,hi)]; } }while(0)
;   #define ROT() do{sl_prev=sl_cur;sl_cur=sl_next;sl_next=(sl_next==(NSLOT-1)*SLOTB)?0:sl_next+SLOTB;}while(0)
;   #define ENDW(tt) do{ if((tt)+3<NT){ if constexpr(VM==2){WAIT_BAR(3);}else{WAIT_BAR(2);} } else if((tt)+2<NT){ if constexpr(VM==2){WAIT_BAR(2);}else{WAIT_BAR(1);} } else {WAIT_BAR(0);} }while(0)
; template<int THRL,int VM,bool NOMAX> __device__ __forceinline__ void attn_unit(const bf16*Qb,const bf16*__restrict__ Kh,const bf16*__restrict__ Vh,bf16*Ob,const int NT,const int sp,float*wscr,char*shm){
;     ...
;   int t=1;
;   for(;t+5<NT;t+=2){
;     STEP(pB0,pB1,pA0,pA1,t,true,true,true);     if constexpr(VM==2){WAIT_BAR(3);}else{WAIT_BAR(2);} RESC(); ROT();
;     STEP(pA0,pA1,pB0,pB1,t+1,true,true,true);   if constexpr(VM==2){WAIT_BAR(3);}else{WAIT_BAR(2);} RESC(); ROT();
;   }
;     ...
;   for(;t+1<NT;t+=2){
;     STEP(pB0,pB1,pA0,pA1,t,(t+3<NT),(t+1<NT),(t+1<NT));       ENDW(t);   RESC(); ROT();
;     STEP(pA0,pA1,pB0,pB1,t+1,(t+4<NT),(t+2<NT),(t+2<NT));     ENDW(t+1); RESC(); ROT();
	v_mfma_f32_32x32x16_bf16 v[80:95], v[124:127], v[164:167], v[80:95]
	ds_read_b64_tr_b16 v[124:125], v188 offset:26624
	ds_read_b64_tr_b16 v[126:127], v188 offset:27136
	ds_read_b128 v[140:143], v168 offset:2048
	v_add_f32_e32 v144, v66, v144
	v_add_f32_e32 v144, v67, v144
	v_add_f32_e32 v144, v68, v144
	v_add_f32_e32 v144, v69, v144
	v_cvt_pk_bf16_f32 v148, v64, v65
	v_cvt_pk_bf16_f32 v149, v66, v67
	s_waitcnt lgkmcnt(0)
	v_mfma_f32_32x32x16_bf16 v[96:111], v[160:163], v[140:143], v[96:111]
	ds_read_b64_tr_b16 v[190:191], v188 offset:30720
	ds_read_b64_tr_b16 v[192:193], v188 offset:31232
	ds_read_b128 v[64:67], v168 offset:2048
	v_add_f32_e32 v140, v70, v144
	v_add_f32_e32 v140, v71, v140
	v_add_f32_e32 v140, v72, v140
	v_add_f32_e32 v140, v73, v140
	v_cvt_pk_bf16_f32 v150, v68, v69
	v_cvt_pk_bf16_f32 v151, v70, v71
	s_waitcnt lgkmcnt(0)
	v_mfma_f32_32x32x16_bf16 v[80:95], v[116:119], v[64:67], v[80:95]
	ds_read_b64_tr_b16 v[116:117], v188 offset:27648
	ds_read_b64_tr_b16 v[118:119], v188 offset:28160
	ds_read_b128 v[64:67], v168 offset:3072
	v_add_f32_e32 v68, v74, v140
	v_add_f32_e32 v68, v75, v68
	v_add_f32_e32 v68, v76, v68
	v_add_f32_e32 v68, v77, v68
	v_cvt_pk_bf16_f32 v144, v72, v73
	v_cvt_pk_bf16_f32 v145, v74, v75
	s_waitcnt lgkmcnt(0)
	v_mfma_f32_32x32x16_bf16 v[96:111], v[120:123], v[64:67], v[96:111]
	ds_read_b64_tr_b16 v[72:73], v188 offset:31744
	ds_read_b64_tr_b16 v[74:75], v188 offset:32256
	ds_read_b128 v[64:67], v168 offset:3072
	v_add_f32_e32 v68, v78, v68
	v_add_f32_e32 v68, v79, v68
	v_add_f32_e32 v68, 0, v68
	v_cvt_pk_bf16_f32 v146, v76, v77
	v_cvt_pk_bf16_f32 v147, v78, v79
	s_waitcnt lgkmcnt(0)
	v_mfma_f32_32x32x16_bf16 v[80:95], v[112:115], v[64:67], v[80:95]
	v_lshl_add_u64 v[64:65], v[170:171], 0, s[60:61]
	s_add_i32 s17, s85, 0xe000
	s_mov_b32 s86, m0
	s_mov_b32 m0, s17
	s_nop 0
	global_load_lds_dwordx4 v[64:65], off
	s_mov_b32 m0, s86
	v_lshl_add_u64 v[64:65], v[172:173], 0, s[60:61]
	s_add_i32 s85, s85, 0x10000
	s_mov_b32 s17, m0
	s_mov_b32 m0, s85
	s_nop 0
	global_load_lds_dwordx4 v[64:65], off
	s_mov_b32 m0, s17
	v_add_f32_e32 v174, v198, v68
	v_mfma_f32_32x32x16_bf16 v[48:63], v[156:159], v[178:181], v[48:63]
	ds_read_b64_tr_b16 v[76:77], v188 offset:32768
	ds_read_b64_tr_b16 v[78:79], v188 offset:33280
	v_exp_f32_e32 v96, v96
	v_exp_f32_e32 v97, v97
	v_mfma_f32_32x32x16_bf16 v[32:47], v[156:159], v[128:131], v[32:47]
	ds_read_b64_tr_b16 v[112:113], v188 offset:36864
	ds_read_b64_tr_b16 v[114:115], v188 offset:37376
	v_exp_f32_e32 v98, v98
	v_exp_f32_e32 v99, v99
	ds_read_b128 v[68:71], v234 offset:16384
	ds_read_b128 v[64:67], v234 offset:20480
	v_mfma_f32_32x32x16_bf16 v[48:63], v[152:155], v[132:135], v[48:63]
	ds_read_b64_tr_b16 v[120:121], v188 offset:33792
	ds_read_b64_tr_b16 v[122:123], v188 offset:34304
	v_exp_f32_e32 v100, v100
	v_exp_f32_e32 v101, v101
	ds_read_b128 v[164:167], v235 offset:16384
	ds_read_b128 v[140:143], v235 offset:20480
	v_mfma_f32_32x32x16_bf16 v[32:47], v[152:155], v[136:139], v[32:47]
	ds_read_b64_tr_b16 v[178:179], v188 offset:37888
	ds_read_b64_tr_b16 v[180:181], v188 offset:38400
	v_exp_f32_e32 v102, v102
	v_exp_f32_e32 v103, v103
	ds_read_b128 v[160:163], v236 offset:16384
	ds_read_b128 v[132:135], v236 offset:20480
	v_mfma_f32_32x32x16_bf16 v[48:63], v[148:151], v[124:127], v[48:63]
	ds_read_b64_tr_b16 v[194:195], v188 offset:34816
	ds_read_b64_tr_b16 v[196:197], v188 offset:35328
	v_exp_f32_e32 v104, v104
	v_exp_f32_e32 v105, v105
	ds_read_b128 v[136:139], v237 offset:16384
	ds_read_b128 v[128:131], v237 offset:20480
	v_mfma_f32_32x32x16_bf16 v[32:47], v[148:151], v[190:193], v[32:47]
	ds_read_b64_tr_b16 v[124:125], v188 offset:38912
	ds_read_b64_tr_b16 v[126:127], v188 offset:39424
	v_exp_f32_e32 v106, v106
	v_exp_f32_e32 v107, v107
	v_mfma_f32_32x32x16_bf16 v[48:63], v[144:147], v[116:119], v[48:63]
	ds_read_b64_tr_b16 v[190:191], v188 offset:35840
	ds_read_b64_tr_b16 v[192:193], v188 offset:36352
	v_exp_f32_e32 v108, v108
	v_exp_f32_e32 v109, v109
	v_mfma_f32_32x32x16_bf16 v[32:47], v[144:147], v[72:75], v[32:47]
	ds_read_b64_tr_b16 v[116:117], v188 offset:39936
	ds_read_b64_tr_b16 v[118:119], v188 offset:40448
	v_exp_f32_e32 v110, v110
	v_exp_f32_e32 v111, v111
	s_waitcnt lgkmcnt(14)
	v_mfma_f32_32x32x16_bf16 v[16:31], v[156:159], v[76:79], v[16:31]
	v_exp_f32_e32 v80, v80
	v_exp_f32_e32 v81, v81
	v_mfma_f32_32x32x16_bf16 v[0:15], v[156:159], v[112:115], v[0:15]
	v_exp_f32_e32 v82, v82
	v_exp_f32_e32 v83, v83
	v_mfma_f32_32x32x16_bf16 v[16:31], v[152:155], v[120:123], v[16:31]
	v_exp_f32_e32 v84, v84
	v_exp_f32_e32 v85, v85
	s_waitcnt lgkmcnt(12)
	v_mfma_f32_32x32x16_bf16 v[0:15], v[152:155], v[178:181], v[0:15]
	v_exp_f32_e32 v86, v86
	v_exp_f32_e32 v87, v87
	s_waitcnt lgkmcnt(8)
	v_mfma_f32_32x32x16_bf16 v[16:31], v[148:151], v[194:197], v[16:31]
	v_exp_f32_e32 v88, v88
	v_exp_f32_e32 v89, v89
	s_waitcnt lgkmcnt(4)
	v_mfma_f32_32x32x16_bf16 v[0:15], v[148:151], v[124:127], v[0:15]
	v_exp_f32_e32 v90, v90
	v_exp_f32_e32 v91, v91
	s_waitcnt lgkmcnt(2)
	v_mfma_f32_32x32x16_bf16 v[16:31], v[144:147], v[190:193], v[16:31]
	v_exp_f32_e32 v92, v92
	v_exp_f32_e32 v93, v93
	s_waitcnt lgkmcnt(0)
	v_mfma_f32_32x32x16_bf16 v[0:15], v[144:147], v[116:119], v[0:15]
	v_exp_f32_e32 v94, v94
	v_exp_f32_e32 v95, v95
	s_waitcnt vmcnt(2) lgkmcnt(0)
	s_barrier
; #define WAIT_BAR(N) asm volatile("s_waitcnt vmcnt(" #N ") lgkmcnt(0)\n\ts_barrier":::"memory")
;   #define RESC() do{ if(!NOMAX&&resc){ asm volatile("s_waitcnt lgkmcnt(0)":::"memory"); \
;       _Pragma("unroll") for(int d_=0;d_<2*VM;++d_) _Pragma("unroll") for(int r=0;r<16;++r)o[d_][r]*=wsf[crow(r,hi)]; } }while(0)
;   #define ROT() do{sl_prev=sl_cur;sl_cur=sl_next;sl_next=(sl_next==(NSLOT-1)*SLOTB)?0:sl_next+SLOTB;}while(0)
;   #define ENDW(tt) do{ if((tt)+3<NT){ if constexpr(VM==2){WAIT_BAR(3);}else{WAIT_BAR(2);} } else if((tt)+2<NT){ if constexpr(VM==2){WAIT_BAR(2);}else{WAIT_BAR(1);} } else {WAIT_BAR(0);} }while(0)
; template<int THRL,int VM,bool NOMAX> __device__ __forceinline__ void attn_unit(const bf16*Qb,const bf16*__restrict__ Kh,const bf16*__restrict__ Vh,bf16*Ob,const int NT,const int sp,float*wscr,char*shm){
;     ...
;   int t=1;
;   for(;t+5<NT;t+=2){
;     STEP(pB0,pB1,pA0,pA1,t,true,true,true);     if constexpr(VM==2){WAIT_BAR(3);}else{WAIT_BAR(2);} RESC(); ROT();
;     STEP(pA0,pA1,pB0,pB1,t+1,true,true,true);   if constexpr(VM==2){WAIT_BAR(3);}else{WAIT_BAR(2);} RESC(); ROT();
;   }
;     ...
;   for(;t+1<NT;t+=2){
;     STEP(pB0,pB1,pA0,pA1,t,(t+3<NT),(t+1<NT),(t+1<NT));       ENDW(t);   RESC(); ROT();
;     STEP(pA0,pA1,pB0,pB1,t+1,(t+4<NT),(t+2<NT),(t+2<NT));     ENDW(t+1); RESC(); ROT();
	ds_read_b64_tr_b16 v[178:179], v188 offset:40960
	ds_read_b64_tr_b16 v[180:181], v188 offset:41472
	v_add_f32_e32 v76, v96, v97
	ds_read_b128 v[72:75], v168
	v_add_f32_e32 v76, v98, v76
	v_add_f32_e32 v76, v99, v76
	v_add_f32_e32 v76, v100, v76
	v_add_f32_e32 v76, v101, v76
	v_cvt_pk_bf16_f32 v156, v96, v97
	v_cvt_pk_bf16_f32 v157, v98, v99
	s_waitcnt lgkmcnt(0)
	v_mfma_f32_32x32x16_bf16 v[112:127], v[68:71], v[72:75], 0
	ds_read_b64_tr_b16 v[96:97], v188 offset:45056
	ds_read_b64_tr_b16 v[98:99], v188 offset:45568
	ds_read_b128 v[68:71], v168
	v_add_f32_e32 v72, v102, v76
	v_add_f32_e32 v72, v103, v72
	v_add_f32_e32 v72, v104, v72
	v_add_f32_e32 v144, v105, v72
	s_waitcnt lgkmcnt(0)
	v_mfma_f32_32x32x16_bf16 v[64:79], v[64:67], v[68:71], 0
	v_cvt_pk_bf16_f32 v158, v100, v101
	v_cvt_pk_bf16_f32 v159, v102, v103
	ds_read_b64_tr_b16 v[100:101], v188 offset:41984
	ds_read_b64_tr_b16 v[102:103], v188 offset:42496
	ds_read_b128 v[190:193], v168 offset:1024
	v_add_f32_e32 v144, v106, v144
	v_add_f32_e32 v144, v107, v144
	v_add_f32_e32 v144, v108, v144
	v_add_f32_e32 v144, v109, v144
	v_cvt_pk_bf16_f32 v152, v104, v105
	v_cvt_pk_bf16_f32 v153, v106, v107
	s_waitcnt lgkmcnt(0)
	v_mfma_f32_32x32x16_bf16 v[112:127], v[164:167], v[190:193], v[112:127]
	ds_read_b64_tr_b16 v[104:105], v188 offset:46080
	ds_read_b64_tr_b16 v[106:107], v188 offset:46592
	ds_read_b128 v[164:167], v168 offset:1024
	v_add_f32_e32 v144, v110, v144
	v_add_f32_e32 v144, v111, v144
	v_add_f32_e32 v144, v80, v144
	v_add_f32_e32 v144, v81, v144
	s_waitcnt lgkmcnt(0)
	v_mfma_f32_32x32x16_bf16 v[64:79], v[140:143], v[164:167], v[64:79]
	v_cvt_pk_bf16_f32 v154, v108, v109
	v_cvt_pk_bf16_f32 v155, v110, v111
	ds_read_b64_tr_b16 v[108:109], v188 offset:43008
	ds_read_b64_tr_b16 v[110:111], v188 offset:43520
	ds_read_b128 v[140:143], v168 offset:2048
	v_add_f32_e32 v144, v82, v144
	v_add_f32_e32 v144, v83, v144
	v_add_f32_e32 v144, v84, v144
	v_add_f32_e32 v144, v85, v144
	v_cvt_pk_bf16_f32 v148, v80, v81
	v_cvt_pk_bf16_f32 v149, v82, v83
	s_waitcnt lgkmcnt(0)
	v_mfma_f32_32x32x16_bf16 v[112:127], v[160:163], v[140:143], v[112:127]
	ds_read_b64_tr_b16 v[190:191], v188 offset:47104
	ds_read_b64_tr_b16 v[192:193], v188 offset:47616
	ds_read_b128 v[80:83], v168 offset:2048
	v_add_f32_e32 v140, v86, v144
	v_add_f32_e32 v140, v87, v140
	v_add_f32_e32 v140, v88, v140
	v_add_f32_e32 v140, v89, v140
	s_waitcnt lgkmcnt(0)
	v_mfma_f32_32x32x16_bf16 v[64:79], v[132:135], v[80:83], v[64:79]
	v_cvt_pk_bf16_f32 v150, v84, v85
	v_cvt_pk_bf16_f32 v151, v86, v87
	ds_read_b64_tr_b16 v[84:85], v188 offset:44032
	ds_read_b64_tr_b16 v[86:87], v188 offset:44544
	ds_read_b128 v[80:83], v168 offset:3072
	v_add_f32_e32 v132, v90, v140
	v_add_f32_e32 v132, v91, v132
	v_add_f32_e32 v132, v92, v132
	v_add_f32_e32 v132, v93, v132
	v_cvt_pk_bf16_f32 v144, v88, v89
	v_cvt_pk_bf16_f32 v145, v90, v91
	s_waitcnt lgkmcnt(0)
	v_mfma_f32_32x32x16_bf16 v[112:127], v[136:139], v[80:83], v[112:127]
	ds_read_b64_tr_b16 v[88:89], v188 offset:48128
	ds_read_b64_tr_b16 v[90:91], v188 offset:48640
	ds_read_b128 v[80:83], v168 offset:3072
	v_add_f32_e32 v132, v94, v132
	v_add_f32_e32 v132, v95, v132
	v_add_f32_e32 v132, 0, v132
	v_cvt_pk_bf16_f32 v146, v92, v93
	s_waitcnt lgkmcnt(0)
	v_mfma_f32_32x32x16_bf16 v[64:79], v[128:131], v[80:83], v[64:79]
	v_cvt_pk_bf16_f32 v147, v94, v95
	v_lshl_add_u64 v[80:81], v[170:171], 0, s[64:65]
	s_mov_b32 s17, m0
	s_mov_b32 m0, s16
	s_nop 0
	global_load_lds_dwordx4 v[80:81], off
	s_mov_b32 m0, s17
	v_lshl_add_u64 v[80:81], v[172:173], 0, s[64:65]
	s_mov_b32 s16, m0
	s_mov_b32 m0, s35
	s_nop 0
	global_load_lds_dwordx4 v[80:81], off
	s_mov_b32 m0, s16
	v_add_f32_e32 v174, v174, v132
	v_mfma_f32_32x32x16_bf16 v[48:63], v[156:159], v[178:181], v[48:63]
	ds_read_b64_tr_b16 v[92:93], v188 offset:49152
	ds_read_b64_tr_b16 v[94:95], v188 offset:49664
	v_exp_f32_e32 v112, v112
	v_exp_f32_e32 v113, v113
	v_mfma_f32_32x32x16_bf16 v[32:47], v[156:159], v[96:99], v[32:47]
	ds_read_b64_tr_b16 v[170:171], v188 offset:53248
	ds_read_b64_tr_b16 v[172:173], v188 offset:53760
	v_exp_f32_e32 v114, v114
	v_exp_f32_e32 v115, v115
	ds_read_b128 v[80:83], v234
	ds_read_b128 v[96:99], v234 offset:4096
	v_mfma_f32_32x32x16_bf16 v[48:63], v[152:155], v[100:103], v[48:63]
	ds_read_b64_tr_b16 v[178:179], v188 offset:50176
	ds_read_b64_tr_b16 v[180:181], v188 offset:50688
	v_exp_f32_e32 v116, v116
	v_exp_f32_e32 v117, v117
	ds_read_b128 v[164:167], v235
	ds_read_b128 v[140:143], v235 offset:4096
	v_mfma_f32_32x32x16_bf16 v[32:47], v[152:155], v[104:107], v[32:47]
	ds_read_b64_tr_b16 v[100:101], v188 offset:54272
	ds_read_b64_tr_b16 v[102:103], v188 offset:54784
	v_exp_f32_e32 v118, v118
	v_exp_f32_e32 v119, v119
	ds_read_b128 v[160:163], v236
	ds_read_b128 v[132:135], v236 offset:4096
	v_mfma_f32_32x32x16_bf16 v[48:63], v[148:151], v[108:111], v[48:63]
	ds_read_b64_tr_b16 v[104:105], v188 offset:51200
	ds_read_b64_tr_b16 v[106:107], v188 offset:51712
	v_exp_f32_e32 v120, v120
	v_exp_f32_e32 v121, v121
	ds_read_b128 v[136:139], v237
	ds_read_b128 v[128:131], v237 offset:4096
	v_mfma_f32_32x32x16_bf16 v[32:47], v[148:151], v[190:193], v[32:47]
	ds_read_b64_tr_b16 v[108:109], v188 offset:55296
	ds_read_b64_tr_b16 v[110:111], v188 offset:55808
	v_exp_f32_e32 v122, v122
	v_exp_f32_e32 v123, v123
	v_mfma_f32_32x32x16_bf16 v[48:63], v[144:147], v[84:87], v[48:63]
	ds_read_b64_tr_b16 v[190:191], v188 offset:52224
	ds_read_b64_tr_b16 v[192:193], v188 offset:52736
	v_exp_f32_e32 v124, v124
	v_exp_f32_e32 v125, v125
	v_mfma_f32_32x32x16_bf16 v[32:47], v[144:147], v[88:91], v[32:47]
	ds_read_b64_tr_b16 v[84:85], v188 offset:56320
	ds_read_b64_tr_b16 v[86:87], v188 offset:56832
	v_exp_f32_e32 v126, v126
	v_exp_f32_e32 v127, v127
	s_waitcnt lgkmcnt(14)
	v_mfma_f32_32x32x16_bf16 v[16:31], v[156:159], v[92:95], v[16:31]
	v_exp_f32_e32 v64, v64
	v_exp_f32_e32 v65, v65
	v_mfma_f32_32x32x16_bf16 v[0:15], v[156:159], v[170:173], v[0:15]
	v_exp_f32_e32 v66, v66
	v_exp_f32_e32 v67, v67
	v_mfma_f32_32x32x16_bf16 v[16:31], v[152:155], v[178:181], v[16:31]
	v_exp_f32_e32 v68, v68
	v_exp_f32_e32 v69, v69
	s_waitcnt lgkmcnt(12)
	v_mfma_f32_32x32x16_bf16 v[0:15], v[152:155], v[100:103], v[0:15]
	v_exp_f32_e32 v70, v70
	v_exp_f32_e32 v71, v71
	s_waitcnt lgkmcnt(8)
	v_mfma_f32_32x32x16_bf16 v[16:31], v[148:151], v[104:107], v[16:31]
	v_exp_f32_e32 v72, v72
	v_exp_f32_e32 v73, v73
	s_waitcnt lgkmcnt(4)
	v_mfma_f32_32x32x16_bf16 v[0:15], v[148:151], v[108:111], v[0:15]
	v_exp_f32_e32 v74, v74
	v_exp_f32_e32 v75, v75
	s_waitcnt lgkmcnt(2)
	v_mfma_f32_32x32x16_bf16 v[16:31], v[144:147], v[190:193], v[16:31]
	v_exp_f32_e32 v76, v76
	v_exp_f32_e32 v77, v77
	s_waitcnt lgkmcnt(0)
	v_mfma_f32_32x32x16_bf16 v[0:15], v[144:147], v[84:87], v[0:15]
	v_exp_f32_e32 v78, v78
	v_exp_f32_e32 v79, v79
	s_waitcnt vmcnt(0) lgkmcnt(0)
	s_barrier
;   #define RESC() do{ if(!NOMAX&&resc){ asm volatile("s_waitcnt lgkmcnt(0)":::"memory"); \
;       _Pragma("unroll") for(int d_=0;d_<2*VM;++d_) _Pragma("unroll") for(int r=0;r<16;++r)o[d_][r]*=wsf[crow(r,hi)]; } }while(0)
; template<int THRL,int VM,bool NOMAX> __device__ __forceinline__ void attn_unit(const bf16*Qb,const bf16*__restrict__ Kh,const bf16*__restrict__ Vh,bf16*Ob,const int NT,const int sp,float*wscr,char*shm){
;     ...
;   STEP(pB0,pB1,pA0,pA1,NT-1,false,false,false); RESC();
	ds_read_b64_tr_b16 v[170:171], v188 offset:57344
	ds_read_b64_tr_b16 v[172:173], v188 offset:57856
	v_add_f32_e32 v88, v112, v113
	ds_read_b128 v[84:87], v168
	v_add_f32_e32 v88, v114, v88
	v_add_f32_e32 v88, v115, v88
	v_add_f32_e32 v88, v116, v88
	v_add_f32_e32 v104, v117, v88
	v_cvt_pk_bf16_f32 v156, v112, v113
	v_cvt_pk_bf16_f32 v157, v114, v115
	s_waitcnt lgkmcnt(0)
	v_mfma_f32_32x32x16_bf16 v[80:95], v[80:83], v[84:87], 0
	ds_read_b64_tr_b16 v[112:113], v188 offset:61440
	ds_read_b64_tr_b16 v[114:115], v188 offset:61952
	ds_read_b128 v[100:103], v168
	v_add_f32_e32 v104, v118, v104
	v_add_f32_e32 v104, v119, v104
	v_add_f32_e32 v104, v120, v104
	v_add_f32_e32 v144, v121, v104
	v_cvt_pk_bf16_f32 v158, v116, v117
	v_cvt_pk_bf16_f32 v159, v118, v119
	s_waitcnt lgkmcnt(0)
	v_mfma_f32_32x32x16_bf16 v[96:111], v[96:99], v[100:103], 0
	ds_read_b64_tr_b16 v[116:117], v188 offset:58368
	ds_read_b64_tr_b16 v[118:119], v188 offset:58880
	ds_read_b128 v[178:181], v168 offset:1024
	v_add_f32_e32 v144, v122, v144
	v_add_f32_e32 v144, v123, v144
	v_add_f32_e32 v144, v124, v144
	v_add_f32_e32 v144, v125, v144
	v_cvt_pk_bf16_f32 v152, v120, v121
	v_cvt_pk_bf16_f32 v153, v122, v123
	s_waitcnt lgkmcnt(0)
	v_mfma_f32_32x32x16_bf16 v[80:95], v[164:167], v[178:181], v[80:95]
	ds_read_b64_tr_b16 v[120:121], v188 offset:62464
	ds_read_b64_tr_b16 v[122:123], v188 offset:62976
	ds_read_b128 v[164:167], v168 offset:1024
	v_add_f32_e32 v144, v126, v144
	v_add_f32_e32 v144, v127, v144
	v_add_f32_e32 v144, v64, v144
	v_add_f32_e32 v144, v65, v144
	v_cvt_pk_bf16_f32 v154, v124, v125
	v_cvt_pk_bf16_f32 v155, v126, v127
	s_waitcnt lgkmcnt(0)
	v_mfma_f32_32x32x16_bf16 v[96:111], v[140:143], v[164:167], v[96:111]
	ds_read_b64_tr_b16 v[124:125], v188 offset:59392
	ds_read_b64_tr_b16 v[126:127], v188 offset:59904
	ds_read_b128 v[140:143], v168 offset:2048
	v_add_f32_e32 v144, v66, v144
	v_add_f32_e32 v144, v67, v144
	v_add_f32_e32 v144, v68, v144
	v_add_f32_e32 v144, v69, v144
	v_cvt_pk_bf16_f32 v148, v64, v65
	v_cvt_pk_bf16_f32 v149, v66, v67
	s_waitcnt lgkmcnt(0)
	v_mfma_f32_32x32x16_bf16 v[80:95], v[160:163], v[140:143], v[80:95]
	ds_read_b64_tr_b16 v[64:65], v188 offset:63488
	ds_read_b64_tr_b16 v[66:67], v188 offset:64000
	ds_read_b128 v[140:143], v168 offset:2048
	v_add_f32_e32 v144, v70, v144
	v_add_f32_e32 v144, v71, v144
	v_add_f32_e32 v144, v72, v144
	v_add_f32_e32 v144, v73, v144
	v_cvt_pk_bf16_f32 v150, v68, v69
	v_cvt_pk_bf16_f32 v151, v70, v71
	s_waitcnt lgkmcnt(0)
	v_mfma_f32_32x32x16_bf16 v[96:111], v[132:135], v[140:143], v[96:111]
	ds_read_b64_tr_b16 v[68:69], v188 offset:60416
	ds_read_b64_tr_b16 v[70:71], v188 offset:60928
	ds_read_b128 v[132:135], v168 offset:3072
	v_add_f32_e32 v140, v74, v144
	v_add_f32_e32 v140, v75, v140
	v_add_f32_e32 v140, v76, v140
	v_add_f32_e32 v140, v77, v140
	v_cvt_pk_bf16_f32 v144, v72, v73
	v_cvt_pk_bf16_f32 v145, v74, v75
	s_waitcnt lgkmcnt(0)
	v_mfma_f32_32x32x16_bf16 v[80:95], v[136:139], v[132:135], v[80:95]
	ds_read_b64_tr_b16 v[72:73], v188 offset:64512
	ds_read_b64_tr_b16 v[74:75], v188 offset:65024
	ds_read_b128 v[132:135], v168 offset:3072
	v_add_f32_e32 v136, v78, v140
	v_add_f32_e32 v136, v79, v136
	v_add_f32_e32 v136, 0, v136
	v_cvt_pk_bf16_f32 v146, v76, v77
	v_cvt_pk_bf16_f32 v147, v78, v79
	s_waitcnt lgkmcnt(0)
	v_mfma_f32_32x32x16_bf16 v[96:111], v[128:131], v[132:135], v[96:111]
	v_mfma_f32_32x32x16_bf16 v[48:63], v[156:159], v[170:173], v[48:63]
	ds_read_b64_tr_b16 v[76:77], v177 offset:40960
	ds_read_b64_tr_b16 v[78:79], v177 offset:41472
	v_exp_f32_e32 v80, v80
	v_exp_f32_e32 v81, v81
	v_mfma_f32_32x32x16_bf16 v[32:47], v[156:159], v[112:115], v[32:47]
	ds_read_b64_tr_b16 v[128:129], v177 offset:45056
	ds_read_b64_tr_b16 v[130:131], v177 offset:45568
	v_exp_f32_e32 v82, v82
	v_exp_f32_e32 v83, v83
	v_mfma_f32_32x32x16_bf16 v[48:63], v[152:155], v[116:119], v[48:63]
	ds_read_b64_tr_b16 v[112:113], v177 offset:41984
	ds_read_b64_tr_b16 v[114:115], v177 offset:42496
	v_exp_f32_e32 v84, v84
	v_exp_f32_e32 v85, v85
	v_mfma_f32_32x32x16_bf16 v[32:47], v[152:155], v[120:123], v[32:47]
	ds_read_b64_tr_b16 v[116:117], v177 offset:46080
	ds_read_b64_tr_b16 v[118:119], v177 offset:46592
	v_exp_f32_e32 v86, v86
	v_exp_f32_e32 v87, v87
	v_mfma_f32_32x32x16_bf16 v[48:63], v[148:151], v[124:127], v[48:63]
	ds_read_b64_tr_b16 v[120:121], v177 offset:43008
	ds_read_b64_tr_b16 v[122:123], v177 offset:43520
	v_exp_f32_e32 v88, v88
	v_exp_f32_e32 v89, v89
	v_mfma_f32_32x32x16_bf16 v[32:47], v[148:151], v[64:67], v[32:47]
	ds_read_b64_tr_b16 v[124:125], v177 offset:47104
	ds_read_b64_tr_b16 v[126:127], v177 offset:47616
	v_exp_f32_e32 v90, v90
	v_exp_f32_e32 v91, v91
	v_mfma_f32_32x32x16_bf16 v[48:63], v[144:147], v[68:71], v[48:63]
	ds_read_b64_tr_b16 v[64:65], v177 offset:44032
	ds_read_b64_tr_b16 v[66:67], v177 offset:44544
	v_exp_f32_e32 v92, v92
	v_exp_f32_e32 v93, v93
	v_mfma_f32_32x32x16_bf16 v[32:47], v[144:147], v[72:75], v[32:47]
	ds_read_b64_tr_b16 v[68:69], v177 offset:48128
	ds_read_b64_tr_b16 v[70:71], v177 offset:48640
	v_exp_f32_e32 v94, v94
	v_exp_f32_e32 v95, v95
	s_waitcnt lgkmcnt(14)
	v_mfma_f32_32x32x16_bf16 v[16:31], v[156:159], v[76:79], v[16:31]
	v_exp_f32_e32 v96, v96
	v_exp_f32_e32 v97, v97
	s_waitcnt lgkmcnt(12)
; #define SBAR() __builtin_amdgcn_sched_barrier(0)
;   #define RESC() do{ if(!NOMAX&&resc){ asm volatile("s_waitcnt lgkmcnt(0)":::"memory"); \
;       _Pragma("unroll") for(int d_=0;d_<2*VM;++d_) _Pragma("unroll") for(int r=0;r<16;++r)o[d_][r]*=wsf[crow(r,hi)]; } }while(0)
;   #define PKW(P,B) cvtpk_s(P[B],P[B+1])
; __device__ __forceinline__ void pv(f32x16*o,int vb,bf16x8 pa0,bf16x8 pa1,bf16x8 pa2,bf16x8 pa3){
;   #pragma unroll
;   for(int d0=0;d0<2;++d0){s16x4 lo[4],hi[4];
;     #pragma unroll
;     for(int ks=0;ks<4;++ks){
;       asm volatile("ds_read_b64_tr_b16 %0,%1 offset:%c2":"=&v"(lo[ks]):"v"(vb),"i"(d0*4096+ks*1024):"memory");
;       asm volatile("ds_read_b64_tr_b16 %0,%1 offset:%c2":"=&v"(hi[ks]):"v"(vb),"i"(d0*4096+ks*1024+512):"memory");}
;     asm volatile("s_waitcnt lgkmcnt(0)":::"memory");SBAR();
;     ...
;     o[d0]=__builtin_amdgcn_mfma_f32_32x32x16_bf16(pa0,PK(0),o[d0],0,0,0);
;     o[d0]=__builtin_amdgcn_mfma_f32_32x32x16_bf16(pa1,PK(1),o[d0],0,0,0);
;     o[d0]=__builtin_amdgcn_mfma_f32_32x32x16_bf16(pa2,PK(2),o[d0],0,0,0);
;     o[d0]=__builtin_amdgcn_mfma_f32_32x32x16_bf16(pa3,PK(3),o[d0],0,0,0);
;     ...
;   }
; }
; template<int THRL,int VM,bool NOMAX> __device__ __forceinline__ void attn_unit(const bf16*Qb,const bf16*__restrict__ Kh,const bf16*__restrict__ Vh,bf16*Ob,const int NT,const int sp,float*wscr,char*shm){
;     ...
;   STEP(pB0,pB1,pA0,pA1,NT-1,false,false,false); RESC();
;   { float sacc=pB0[0]+pB0[1]; _Pragma("unroll") for(int r=2;r<16;++r)sacc+=pB0[r]; _Pragma("unroll") for(int r=0;r<16;++r)sacc+=pB1[r]; l_reg+=sacc;
;     pw0=(u32x4){PKW(pB0,0),PKW(pB0,2),PKW(pB0,4),PKW(pB0,6)};pw1=(u32x4){PKW(pB0,8),PKW(pB0,10),PKW(pB0,12),PKW(pB0,14)};pw2=(u32x4){PKW(pB1,0),PKW(pB1,2),PKW(pB1,4),PKW(pB1,6)};pw3=(u32x4){PKW(pB1,8),PKW(pB1,10),PKW(pB1,12),PKW(pB1,14)};
;     SBAR(); pv(o,vb0+VM*sl_cur,PAF(0),PAF(1),PAF(2),PAF(3)); if constexpr(VM==2) pv(o+2,vb0+VM*sl_cur+8192,PAF(0),PAF(1),PAF(2),PAF(3)); }
;     ...
;   {auto rr=__builtin_amdgcn_permlane32_swap(__float_as_uint(l_reg),__float_as_uint(l_reg),false,false);l_reg=__uint_as_float(rr[0])+__uint_as_float(rr[1]);}
;   if(hi==0)wsf[32+r32]=l_reg;asm volatile("s_waitcnt lgkmcnt(0)":::"memory");
	v_mfma_f32_32x32x16_bf16 v[0:15], v[156:159], v[128:131], v[0:15]
	v_exp_f32_e32 v98, v98
	v_exp_f32_e32 v99, v99
	s_waitcnt lgkmcnt(10)
	v_mfma_f32_32x32x16_bf16 v[16:31], v[152:155], v[112:115], v[16:31]
	v_exp_f32_e32 v100, v100
	v_exp_f32_e32 v101, v101
	s_waitcnt lgkmcnt(8)
	v_mfma_f32_32x32x16_bf16 v[0:15], v[152:155], v[116:119], v[0:15]
	v_exp_f32_e32 v102, v102
	v_exp_f32_e32 v103, v103
	s_waitcnt lgkmcnt(6)
	v_mfma_f32_32x32x16_bf16 v[16:31], v[148:151], v[120:123], v[16:31]
	v_exp_f32_e32 v104, v104
	v_exp_f32_e32 v105, v105
	s_waitcnt lgkmcnt(4)
	v_mfma_f32_32x32x16_bf16 v[0:15], v[148:151], v[124:127], v[0:15]
	v_exp_f32_e32 v106, v106
	v_exp_f32_e32 v107, v107
	s_waitcnt lgkmcnt(2)
	v_mfma_f32_32x32x16_bf16 v[16:31], v[144:147], v[64:67], v[16:31]
	v_exp_f32_e32 v108, v108
	v_exp_f32_e32 v109, v109
	s_waitcnt lgkmcnt(0)
	v_mfma_f32_32x32x16_bf16 v[0:15], v[144:147], v[68:71], v[0:15]
	v_exp_f32_e32 v110, v110
	v_exp_f32_e32 v111, v111
	v_add_f32_e32 v64, v80, v81
	v_add_f32_e32 v64, v82, v64
	v_add_f32_e32 v64, v83, v64
	v_add_f32_e32 v64, v84, v64
	v_add_f32_e32 v64, v85, v64
	v_add_f32_e32 v64, v86, v64
	v_add_f32_e32 v64, v87, v64
	v_add_f32_e32 v64, v88, v64
	v_add_f32_e32 v64, v89, v64
	v_add_f32_e32 v64, v90, v64
	v_add_f32_e32 v64, v91, v64
	v_add_f32_e32 v64, v92, v64
	v_add_f32_e32 v64, v93, v64
	v_add_f32_e32 v64, v94, v64
	v_add_f32_e32 v64, v95, v64
	v_add_f32_e32 v64, v64, v96
	v_add_f32_e32 v64, v97, v64
	v_add_f32_e32 v64, v98, v64
	v_add_f32_e32 v64, v99, v64
	v_add_f32_e32 v64, v100, v64
	v_add_f32_e32 v64, v101, v64
	v_add_f32_e32 v64, v102, v64
	v_add_f32_e32 v64, v103, v64
	v_add_f32_e32 v64, v104, v64
	v_add_f32_e32 v64, v105, v64
	v_add_f32_e32 v64, v106, v64
	v_add_f32_e32 v64, v107, v64
	v_add_f32_e32 v64, v108, v64
	v_add_f32_e32 v64, v109, v64
	v_add_f32_e32 v64, v110, v64
	v_add_f32_e32 v64, v111, v64
	v_add_f32_e32 v65, v174, v136
	v_add_f32_e32 v64, v65, v64
	v_cvt_pk_bf16_f32 v66, v80, v81
	v_cvt_pk_bf16_f32 v67, v82, v83
	v_cvt_pk_bf16_f32 v68, v84, v85
	v_cvt_pk_bf16_f32 v69, v86, v87
	v_cvt_pk_bf16_f32 v70, v88, v89
	v_cvt_pk_bf16_f32 v71, v90, v91
	v_cvt_pk_bf16_f32 v72, v92, v93
	v_cvt_pk_bf16_f32 v73, v94, v95
	v_cvt_pk_bf16_f32 v74, v96, v97
	v_cvt_pk_bf16_f32 v75, v98, v99
	v_cvt_pk_bf16_f32 v76, v100, v101
	v_cvt_pk_bf16_f32 v77, v102, v103
	v_cvt_pk_bf16_f32 v78, v104, v105
	v_cvt_pk_bf16_f32 v79, v106, v107
	v_cvt_pk_bf16_f32 v80, v108, v109
	v_cvt_pk_bf16_f32 v81, v110, v111
	ds_read_b64_tr_b16 v[82:83],v176 offset:0
	ds_read_b64_tr_b16 v[84:85],v176 offset:512
	ds_read_b64_tr_b16 v[86:87],v176 offset:1024
	ds_read_b64_tr_b16 v[88:89],v176 offset:1536
	ds_read_b64_tr_b16 v[90:91],v176 offset:2048
	ds_read_b64_tr_b16 v[92:93],v176 offset:2560
	ds_read_b64_tr_b16 v[94:95],v176 offset:3072
	ds_read_b64_tr_b16 v[96:97],v176 offset:3584
	s_waitcnt lgkmcnt(0)
	s_nop 0
	v_mfma_f32_32x32x16_bf16 v[48:63], v[66:69], v[82:85], v[48:63]
	ds_read_b64_tr_b16 v[82:83],v176 offset:4096
	ds_read_b64_tr_b16 v[84:85],v176 offset:4608
	v_mfma_f32_32x32x16_bf16 v[48:63], v[70:73], v[86:89], v[48:63]
	ds_read_b64_tr_b16 v[86:87],v176 offset:5120
	ds_read_b64_tr_b16 v[88:89],v176 offset:5632
	v_mfma_f32_32x32x16_bf16 v[48:63], v[74:77], v[90:93], v[48:63]
	ds_read_b64_tr_b16 v[90:91],v176 offset:6144
	ds_read_b64_tr_b16 v[92:93],v176 offset:6656
	ds_read_b64_tr_b16 v[98:99],v176 offset:7168
	ds_read_b64_tr_b16 v[100:101],v176 offset:7680
	s_waitcnt lgkmcnt(0)
	v_mfma_f32_32x32x16_bf16 v[48:63], v[78:81], v[94:97], v[48:63]
	v_mfma_f32_32x32x16_bf16 v[32:47], v[66:69], v[82:85], v[32:47]
	v_add_u32_e32 v65, 0x2000, v176
	ds_read_b64_tr_b16 v[82:83],v65 offset:0
	ds_read_b64_tr_b16 v[84:85],v65 offset:512
	v_mfma_f32_32x32x16_bf16 v[32:47], v[70:73], v[86:89], v[32:47]
	ds_read_b64_tr_b16 v[86:87],v65 offset:1024
	ds_read_b64_tr_b16 v[88:89],v65 offset:1536
	v_mfma_f32_32x32x16_bf16 v[32:47], v[74:77], v[90:93], v[32:47]
	ds_read_b64_tr_b16 v[90:91],v65 offset:2048
	ds_read_b64_tr_b16 v[92:93],v65 offset:2560
	ds_read_b64_tr_b16 v[94:95],v65 offset:3072
	ds_read_b64_tr_b16 v[96:97],v65 offset:3584
	s_waitcnt lgkmcnt(0)
	v_mfma_f32_32x32x16_bf16 v[32:47], v[78:81], v[98:101], v[32:47]
	v_mfma_f32_32x32x16_bf16 v[16:31], v[66:69], v[82:85], v[16:31]
	ds_read_b64_tr_b16 v[82:83],v65 offset:4096
	ds_read_b64_tr_b16 v[84:85],v65 offset:4608
	v_mfma_f32_32x32x16_bf16 v[16:31], v[70:73], v[86:89], v[16:31]
	ds_read_b64_tr_b16 v[86:87],v65 offset:5120
	ds_read_b64_tr_b16 v[88:89],v65 offset:5632
	v_mfma_f32_32x32x16_bf16 v[16:31], v[74:77], v[90:93], v[16:31]
	ds_read_b64_tr_b16 v[90:91],v65 offset:6144
	ds_read_b64_tr_b16 v[92:93],v65 offset:6656
	ds_read_b64_tr_b16 v[98:99],v65 offset:7168
	ds_read_b64_tr_b16 v[100:101],v65 offset:7680
	s_waitcnt lgkmcnt(0)
	v_mfma_f32_32x32x16_bf16 v[16:31], v[78:81], v[94:97], v[16:31]
	v_mfma_f32_32x32x16_bf16 v[0:15], v[66:69], v[82:85], v[0:15]
	v_mov_b32_e32 v65, v64
	s_nop 1
	v_permlane32_swap_b32_e32 v64, v65
	v_cmp_gt_u32_e32 vcc, 32, v187
	v_mfma_f32_32x32x16_bf16 v[0:15], v[70:73], v[86:89], v[0:15]
	v_mfma_f32_32x32x16_bf16 v[0:15], v[74:77], v[90:93], v[0:15]
	v_mfma_f32_32x32x16_bf16 v[0:15], v[78:81], v[98:101], v[0:15]
	s_and_saveexec_b64 s[16:17], vcc
	s_cbranch_execz .LBB0_870
	v_add_f32_e32 v64, v64, v65
	v_lshl_add_u32 v65, v186, 2, s34
	ds_write_b32 v65, v64 offset:128
	s_branch .LBB0_870

; #define WAIT_BAR(N) asm volatile("s_waitcnt vmcnt(" #N ") lgkmcnt(0)\n\ts_barrier":::"memory")
;   #define RESC() do{ if(!NOMAX&&resc){ asm volatile("s_waitcnt lgkmcnt(0)":::"memory"); \
;       _Pragma("unroll") for(int d_=0;d_<2*VM;++d_) _Pragma("unroll") for(int r=0;r<16;++r)o[d_][r]*=wsf[crow(r,hi)]; } }while(0)
;   #define ROT() do{sl_prev=sl_cur;sl_cur=sl_next;sl_next=(sl_next==(NSLOT-1)*SLOTB)?0:sl_next+SLOTB;}while(0)
; template<int THRL,int VM,bool NOMAX> __device__ __forceinline__ void attn_unit(const bf16*Qb,const bf16*__restrict__ Kh,const bf16*__restrict__ Vh,bf16*Ob,const int NT,const int sp,float*wscr,char*shm){
;     ...
;   int t=1;
;   for(;t+5<NT;t+=2){
;     STEP(pB0,pB1,pA0,pA1,t,true,true,true);     if constexpr(VM==2){WAIT_BAR(3);}else{WAIT_BAR(2);} RESC(); ROT();
;     STEP(pA0,pA1,pB0,pB1,t+1,true,true,true);   if constexpr(VM==2){WAIT_BAR(3);}else{WAIT_BAR(2);} RESC(); ROT();
.LBB0_882:
	v_mfma_f32_32x32x16_bf16 v[96:111], v[84:87], v[156:159], 0
	v_add_u32_e32 v187, s54, v182
	ds_read_b64_tr_b16 v[188:189], v187 offset:24576
	ds_read_b64_tr_b16 v[190:191], v187 offset:25088
	v_add_f32_e32 v88, v64, v65
	v_add_f32_e32 v88, v66, v88
	v_add_f32_e32 v88, v67, v88
	v_add_f32_e32 v88, v68, v88
	v_add_f32_e32 v88, v69, v88
	v_cvt_pk_bf16_f32 v140, v64, v65
	v_cvt_pk_bf16_f32 v141, v66, v67
	ds_read_b64_tr_b16 v[64:65], v187 offset:28672
	ds_read_b64_tr_b16 v[66:67], v187 offset:29184
	v_add_f32_e32 v84, v70, v88
	v_add_f32_e32 v84, v71, v84
	v_add_f32_e32 v84, v72, v84
	v_add_f32_e32 v128, v73, v84
	s_waitcnt lgkmcnt(10)
	v_mfma_f32_32x32x16_bf16 v[80:95], v[80:83], v[156:159], 0
	v_cvt_pk_bf16_f32 v142, v68, v69
	v_cvt_pk_bf16_f32 v143, v70, v71
	ds_read_b64_tr_b16 v[68:69], v187 offset:25600
	ds_read_b64_tr_b16 v[70:71], v187 offset:26112
	v_add_f32_e32 v128, v74, v128
	v_add_f32_e32 v128, v75, v128
	v_add_f32_e32 v128, v76, v128
	v_add_f32_e32 v128, v77, v128
	v_cvt_pk_bf16_f32 v136, v72, v73
	v_cvt_pk_bf16_f32 v137, v74, v75
	s_waitcnt lgkmcnt(11)
	v_mfma_f32_32x32x16_bf16 v[96:111], v[164:167], v[152:155], v[96:111]
	ds_read_b64_tr_b16 v[72:73], v187 offset:29696
	ds_read_b64_tr_b16 v[74:75], v187 offset:30208
	s_waitcnt lgkmcnt(12)
	v_mfma_f32_32x32x16_bf16 v[80:95], v[160:163], v[152:155], v[80:95]
	v_add_f32_e32 v128, v78, v128
	v_add_f32_e32 v128, v79, v128
	v_add_f32_e32 v128, v48, v128
	v_add_f32_e32 v128, v49, v128
	v_cvt_pk_bf16_f32 v138, v76, v77
	v_cvt_pk_bf16_f32 v139, v78, v79
	ds_read_b64_tr_b16 v[76:77], v187 offset:26624
	ds_read_b64_tr_b16 v[78:79], v187 offset:27136
	v_add_f32_e32 v128, v50, v128
	v_add_f32_e32 v128, v51, v128
	v_add_f32_e32 v128, v52, v128
	v_add_f32_e32 v128, v53, v128
	v_cvt_pk_bf16_f32 v132, v48, v49
	v_cvt_pk_bf16_f32 v133, v50, v51
	s_waitcnt lgkmcnt(13)
	v_mfma_f32_32x32x16_bf16 v[96:111], v[124:127], v[148:151], v[96:111]
	ds_read_b64_tr_b16 v[48:49], v187 offset:30720
	ds_read_b64_tr_b16 v[50:51], v187 offset:31232
	s_waitcnt lgkmcnt(14)
	v_mfma_f32_32x32x16_bf16 v[80:95], v[120:123], v[148:151], v[80:95]
	v_add_f32_e32 v124, v54, v128
	v_add_f32_e32 v124, v55, v124
	v_add_f32_e32 v124, v56, v124
	v_add_f32_e32 v124, v57, v124
	v_cvt_pk_bf16_f32 v134, v52, v53
	v_cvt_pk_bf16_f32 v135, v54, v55
	ds_read_b64_tr_b16 v[52:53], v187 offset:27648
	ds_read_b64_tr_b16 v[54:55], v187 offset:28160
	v_add_f32_e32 v120, v58, v124
	v_add_f32_e32 v120, v59, v120
	v_add_f32_e32 v120, v60, v120
	v_add_f32_e32 v120, v61, v120
	v_cvt_pk_bf16_f32 v128, v56, v57
	v_cvt_pk_bf16_f32 v129, v58, v59
	s_waitcnt lgkmcnt(14)
	v_mfma_f32_32x32x16_bf16 v[96:111], v[116:119], v[144:147], v[96:111]
	ds_read_b64_tr_b16 v[56:57], v187 offset:31744
	ds_read_b64_tr_b16 v[58:59], v187 offset:32256
	v_mfma_f32_32x32x16_bf16 v[80:95], v[112:115], v[144:147], v[80:95]
	v_add_f32_e32 v116, v62, v120
	v_add_f32_e32 v116, v63, v116
	v_add_f32_e32 v116, 0, v116
	v_cvt_pk_bf16_f32 v130, v60, v61
	v_cvt_pk_bf16_f32 v131, v62, v63
	v_add_f32_e32 v202, v186, v116
	s_waitcnt lgkmcnt(14)
	v_mfma_f32_32x32x16_bf16 v[16:31], v[140:143], v[188:191], v[16:31]
	v_exp_f32_e32 v96, v96
	v_exp_f32_e32 v97, v97
	v_exp_f32_e32 v98, v98
	v_exp_f32_e32 v99, v99
	s_waitcnt lgkmcnt(12)
	v_mfma_f32_32x32x16_bf16 v[32:47], v[140:143], v[64:67], v[32:47]
	v_exp_f32_e32 v100, v100
	v_exp_f32_e32 v101, v101
	v_exp_f32_e32 v102, v102
	v_exp_f32_e32 v103, v103
	v_add_u32_e32 v242, s35, v234
	v_add_u32_e32 v243, s35, v235
	v_add_u32_e32 v244, s35, v236
	v_add_u32_e32 v245, s35, v237
	ds_read_b128 v[60:63], v242
	ds_read_b128 v[112:115], v242 offset:4096
	s_waitcnt lgkmcnt(12)
	v_mfma_f32_32x32x16_bf16 v[16:31], v[136:139], v[68:71], v[16:31]
	v_exp_f32_e32 v104, v104
	v_exp_f32_e32 v105, v105
	v_exp_f32_e32 v106, v106
	v_exp_f32_e32 v107, v107
	ds_read_b128 v[116:119], v243
	ds_read_b128 v[120:123], v243 offset:4096
	s_waitcnt lgkmcnt(12)
	v_mfma_f32_32x32x16_bf16 v[32:47], v[136:139], v[72:75], v[32:47]
	v_exp_f32_e32 v108, v108
	v_exp_f32_e32 v109, v109
	v_exp_f32_e32 v110, v110
	v_exp_f32_e32 v111, v111
	ds_read_b128 v[124:127], v244
	ds_read_b128 v[160:163], v244 offset:4096
	s_waitcnt lgkmcnt(12)
	v_mfma_f32_32x32x16_bf16 v[16:31], v[132:135], v[76:79], v[16:31]
	v_exp_f32_e32 v80, v80
	v_exp_f32_e32 v81, v81
	v_exp_f32_e32 v82, v82
	v_exp_f32_e32 v83, v83
	ds_read_b128 v[164:167], v245
	ds_read_b128 v[186:189], v245 offset:4096
	s_waitcnt lgkmcnt(12)
	v_mfma_f32_32x32x16_bf16 v[32:47], v[132:135], v[48:51], v[32:47]
	v_lshl_add_u64 v[238:239], v[176:177], 0, s[38:39]
	s_add_i32 s53, s52, s33
	s_mov_b32 s54, m0
	s_mov_b32 m0, s53
	s_nop 0
	global_load_lds_dwordx4 v[238:239], off
	s_mov_b32 m0, s54
	v_exp_f32_e32 v84, v84
	v_exp_f32_e32 v85, v85
	v_exp_f32_e32 v86, v86
	v_exp_f32_e32 v87, v87
	s_waitcnt lgkmcnt(10)
	v_mfma_f32_32x32x16_bf16 v[16:31], v[128:131], v[52:55], v[16:31]
	v_lshl_add_u64 v[238:239], v[174:175], 0, s[38:39]
	s_add_i32 s53, s35, s16
	s_mov_b32 s54, m0
	s_mov_b32 m0, s53
	s_nop 0
	global_load_lds_dwordx4 v[238:239], off
	s_mov_b32 m0, s54
	v_exp_f32_e32 v88, v88
	v_exp_f32_e32 v89, v89
	v_exp_f32_e32 v90, v90
	v_exp_f32_e32 v91, v91
	s_waitcnt lgkmcnt(8)
	v_mfma_f32_32x32x16_bf16 v[32:47], v[128:131], v[56:59], v[32:47]
	v_exp_f32_e32 v92, v92
	v_exp_f32_e32 v93, v93
	v_exp_f32_e32 v94, v94
	v_exp_f32_e32 v95, v95
	s_waitcnt vmcnt(2) lgkmcnt(0)
	s_barrier
; #define WAIT_BAR(N) asm volatile("s_waitcnt vmcnt(" #N ") lgkmcnt(0)\n\ts_barrier":::"memory")
;   #define RESC() do{ if(!NOMAX&&resc){ asm volatile("s_waitcnt lgkmcnt(0)":::"memory"); \
;       _Pragma("unroll") for(int d_=0;d_<2*VM;++d_) _Pragma("unroll") for(int r=0;r<16;++r)o[d_][r]*=wsf[crow(r,hi)]; } }while(0)
;   #define ROT() do{sl_prev=sl_cur;sl_cur=sl_next;sl_next=(sl_next==(NSLOT-1)*SLOTB)?0:sl_next+SLOTB;}while(0)
; template<int THRL,int VM,bool NOMAX> __device__ __forceinline__ void attn_unit(const bf16*Qb,const bf16*__restrict__ Kh,const bf16*__restrict__ Vh,bf16*Ob,const int NT,const int sp,float*wscr,char*shm){
;     ...
;   int t=1;
;   for(;t+5<NT;t+=2){
;     STEP(pB0,pB1,pA0,pA1,t,true,true,true);     if constexpr(VM==2){WAIT_BAR(3);}else{WAIT_BAR(2);} RESC(); ROT();
;     STEP(pA0,pA1,pB0,pB1,t+1,true,true,true);   if constexpr(VM==2){WAIT_BAR(3);}else{WAIT_BAR(2);} RESC(); ROT();
	v_mfma_f32_32x32x16_bf16 v[64:79], v[60:63], v[156:159], 0
	s_add_i32 s53, s35, 0x2000
	s_cmpk_lg_i32 s35, 0x4000
	s_cselect_b32 s53, s53, 0
	v_add_u32_e32 v203, s52, v182
	ds_read_b64_tr_b16 v[190:191], v203 offset:24576
	ds_read_b64_tr_b16 v[192:193], v203 offset:25088
	v_add_f32_e32 v48, v96, v97
	v_add_f32_e32 v48, v98, v48
	v_add_f32_e32 v48, v99, v48
	v_add_f32_e32 v48, v100, v48
	v_add_f32_e32 v48, v101, v48
	v_cvt_pk_bf16_f32 v140, v96, v97
	v_cvt_pk_bf16_f32 v141, v98, v99
	ds_read_b64_tr_b16 v[96:97], v203 offset:28672
	ds_read_b64_tr_b16 v[98:99], v203 offset:29184
	v_add_f32_e32 v48, v102, v48
	v_add_f32_e32 v48, v103, v48
	v_add_f32_e32 v48, v104, v48
	v_add_f32_e32 v128, v105, v48
	s_waitcnt lgkmcnt(10)
	v_mfma_f32_32x32x16_bf16 v[48:63], v[112:115], v[156:159], 0
	v_cvt_pk_bf16_f32 v142, v100, v101
	v_cvt_pk_bf16_f32 v143, v102, v103
	ds_read_b64_tr_b16 v[100:101], v203 offset:25600
	ds_read_b64_tr_b16 v[102:103], v203 offset:26112
	s_waitcnt lgkmcnt(11)
	v_mfma_f32_32x32x16_bf16 v[64:79], v[116:119], v[152:155], v[64:79]
	v_add_f32_e32 v112, v106, v128
	v_add_f32_e32 v112, v107, v112
	v_add_f32_e32 v112, v108, v112
	v_add_f32_e32 v112, v109, v112
	v_cvt_pk_bf16_f32 v136, v104, v105
	v_cvt_pk_bf16_f32 v137, v106, v107
	ds_read_b64_tr_b16 v[104:105], v203 offset:29696
	ds_read_b64_tr_b16 v[106:107], v203 offset:30208
	s_waitcnt lgkmcnt(12)
	v_mfma_f32_32x32x16_bf16 v[48:63], v[120:123], v[152:155], v[48:63]
	v_add_f32_e32 v112, v110, v112
	v_add_f32_e32 v112, v111, v112
	v_add_f32_e32 v112, v80, v112
	v_add_f32_e32 v112, v81, v112
	v_cvt_pk_bf16_f32 v138, v108, v109
	v_cvt_pk_bf16_f32 v139, v110, v111
	ds_read_b64_tr_b16 v[108:109], v203 offset:26624
	ds_read_b64_tr_b16 v[110:111], v203 offset:27136
	s_waitcnt lgkmcnt(13)
	v_mfma_f32_32x32x16_bf16 v[64:79], v[124:127], v[148:151], v[64:79]
	v_add_f32_e32 v112, v82, v112
	v_add_f32_e32 v112, v83, v112
	v_add_f32_e32 v112, v84, v112
	v_add_f32_e32 v112, v85, v112
	v_cvt_pk_bf16_f32 v132, v80, v81
	v_cvt_pk_bf16_f32 v133, v82, v83
	ds_read_b64_tr_b16 v[194:195], v203 offset:30720
	ds_read_b64_tr_b16 v[196:197], v203 offset:31232
	s_waitcnt lgkmcnt(14)
	v_mfma_f32_32x32x16_bf16 v[48:63], v[160:163], v[148:151], v[48:63]
	v_add_f32_e32 v80, v86, v112
	v_add_f32_e32 v80, v87, v80
	v_add_f32_e32 v80, v88, v80
	v_add_f32_e32 v80, v89, v80
	v_cvt_pk_bf16_f32 v134, v84, v85
	v_cvt_pk_bf16_f32 v135, v86, v87
	ds_read_b64_tr_b16 v[198:199], v203 offset:27648
	ds_read_b64_tr_b16 v[200:201], v203 offset:28160
	s_waitcnt lgkmcnt(14)
	v_mfma_f32_32x32x16_bf16 v[64:79], v[164:167], v[144:147], v[64:79]
	v_add_f32_e32 v80, v90, v80
	v_add_f32_e32 v80, v91, v80
	v_add_f32_e32 v80, v92, v80
	v_add_f32_e32 v80, v93, v80
	v_cvt_pk_bf16_f32 v128, v88, v89
	v_cvt_pk_bf16_f32 v129, v90, v91
	ds_read_b64_tr_b16 v[88:89], v203 offset:31744
	ds_read_b64_tr_b16 v[90:91], v203 offset:32256
	v_mfma_f32_32x32x16_bf16 v[48:63], v[186:189], v[144:147], v[48:63]
	v_add_f32_e32 v80, v94, v80
	v_add_f32_e32 v80, v95, v80
	v_add_f32_e32 v80, 0, v80
	v_cvt_pk_bf16_f32 v130, v92, v93
	v_cvt_pk_bf16_f32 v131, v94, v95
	v_add_f32_e32 v186, v202, v80
	s_waitcnt lgkmcnt(14)
	v_mfma_f32_32x32x16_bf16 v[16:31], v[140:143], v[190:193], v[16:31]
	v_exp_f32_e32 v64, v64
	v_exp_f32_e32 v65, v65
	v_exp_f32_e32 v66, v66
	v_exp_f32_e32 v67, v67
	s_waitcnt lgkmcnt(12)
	v_mfma_f32_32x32x16_bf16 v[32:47], v[140:143], v[96:99], v[32:47]
	v_exp_f32_e32 v68, v68
	v_exp_f32_e32 v69, v69
	v_exp_f32_e32 v70, v70
	v_exp_f32_e32 v71, v71
	v_add_u32_e32 v242, s53, v234
	v_add_u32_e32 v243, s53, v235
	v_add_u32_e32 v244, s53, v236
	v_add_u32_e32 v245, s53, v237
	ds_read_b128 v[84:87], v242
	ds_read_b128 v[80:83], v242 offset:4096
	s_waitcnt lgkmcnt(12)
	v_mfma_f32_32x32x16_bf16 v[16:31], v[136:139], v[100:103], v[16:31]
	v_exp_f32_e32 v72, v72
	v_exp_f32_e32 v73, v73
	v_exp_f32_e32 v74, v74
	v_exp_f32_e32 v75, v75
	ds_read_b128 v[164:167], v243
	ds_read_b128 v[160:163], v243 offset:4096
	s_waitcnt lgkmcnt(12)
	v_mfma_f32_32x32x16_bf16 v[32:47], v[136:139], v[104:107], v[32:47]
	v_exp_f32_e32 v76, v76
	v_exp_f32_e32 v77, v77
	v_exp_f32_e32 v78, v78
	v_exp_f32_e32 v79, v79
	ds_read_b128 v[124:127], v244
	ds_read_b128 v[120:123], v244 offset:4096
	s_waitcnt lgkmcnt(12)
	v_mfma_f32_32x32x16_bf16 v[16:31], v[132:135], v[108:111], v[16:31]
	v_exp_f32_e32 v48, v48
	v_exp_f32_e32 v49, v49
	v_exp_f32_e32 v50, v50
	v_exp_f32_e32 v51, v51
	ds_read_b128 v[116:119], v245
	ds_read_b128 v[112:115], v245 offset:4096
	s_waitcnt lgkmcnt(12)
	v_mfma_f32_32x32x16_bf16 v[32:47], v[132:135], v[194:197], v[32:47]
	s_add_i32 s52, s35, s33
	s_mov_b32 s54, m0
	s_mov_b32 m0, s52
	s_nop 0
	global_load_lds_dwordx4 v[176:177], off
	s_mov_b32 m0, s54
	v_exp_f32_e32 v52, v52
	v_exp_f32_e32 v53, v53
	v_exp_f32_e32 v54, v54
	v_exp_f32_e32 v55, v55
	s_waitcnt lgkmcnt(10)
	v_mfma_f32_32x32x16_bf16 v[16:31], v[128:131], v[198:201], v[16:31]
	s_add_i32 s52, s53, s16
	s_mov_b32 s54, m0
	s_mov_b32 m0, s52
	s_nop 0
	global_load_lds_dwordx4 v[174:175], off
	s_mov_b32 m0, s54
	v_exp_f32_e32 v56, v56
	v_exp_f32_e32 v57, v57
	v_exp_f32_e32 v58, v58
	v_exp_f32_e32 v59, v59
	s_waitcnt lgkmcnt(8)
	v_mfma_f32_32x32x16_bf16 v[32:47], v[128:131], v[88:91], v[32:47]
	v_exp_f32_e32 v60, v60
	v_exp_f32_e32 v61, v61
	v_exp_f32_e32 v62, v62
	v_exp_f32_e32 v63, v63
	s_add_i32 s55, s53, 0x2000
	s_waitcnt vmcnt(2) lgkmcnt(0)
	s_barrier
	s_cmpk_lg_i32 s53, 0x4000
	s_mov_b32 s54, s35
	s_cselect_b32 s35, s55, 0
	s_add_i32 s34, s34, 2
	v_lshl_add_u64 v[174:175], v[174:175], 0, s[8:9]
	v_lshl_add_u64 v[176:177], v[176:177], 0, s[8:9]
	s_mov_b32 s52, s53
	s_cmpk_lt_u32 s34, 0x79
	s_cbranch_scc1 .LBB0_882
; #define WAIT_BAR(N) asm volatile("s_waitcnt vmcnt(" #N ") lgkmcnt(0)\n\ts_barrier":::"memory")
;   #define RESC() do{ if(!NOMAX&&resc){ asm volatile("s_waitcnt lgkmcnt(0)":::"memory"); \
;       _Pragma("unroll") for(int d_=0;d_<2*VM;++d_) _Pragma("unroll") for(int r=0;r<16;++r)o[d_][r]*=wsf[crow(r,hi)]; } }while(0)
;   #define ROT() do{sl_prev=sl_cur;sl_cur=sl_next;sl_next=(sl_next==(NSLOT-1)*SLOTB)?0:sl_next+SLOTB;}while(0)
;   #define ENDW(tt) do{ if((tt)+3<NT){ if constexpr(VM==2){WAIT_BAR(3);}else{WAIT_BAR(2);} } else if((tt)+2<NT){ if constexpr(VM==2){WAIT_BAR(2);}else{WAIT_BAR(1);} } else {WAIT_BAR(0);} }while(0)
; template<int THRL,int VM,bool NOMAX> __device__ __forceinline__ void attn_unit(const bf16*Qb,const bf16*__restrict__ Kh,const bf16*__restrict__ Vh,bf16*Ob,const int NT,const int sp,float*wscr,char*shm){
;     ...
;   int t=1;
;   for(;t+5<NT;t+=2){
;     STEP(pB0,pB1,pA0,pA1,t,true,true,true);     if constexpr(VM==2){WAIT_BAR(3);}else{WAIT_BAR(2);} RESC(); ROT();
;     STEP(pA0,pA1,pB0,pB1,t+1,true,true,true);   if constexpr(VM==2){WAIT_BAR(3);}else{WAIT_BAR(2);} RESC(); ROT();
;   }
;     ...
;   for(;t+1<NT;t+=2){
;     STEP(pB0,pB1,pA0,pA1,t,(t+3<NT),(t+1<NT),(t+1<NT));       ENDW(t);   RESC(); ROT();
;     STEP(pA0,pA1,pB0,pB1,t+1,(t+4<NT),(t+2<NT),(t+2<NT));     ENDW(t+1); RESC(); ROT();
	s_and_b32 s29, s29, 0x3fffffc0
	s_lshl_b32 s29, s29, 2
	s_add_i32 s29, s29, 0
	s_cmp_lg_u32 0, -1
	s_cselect_b32 s34, 0, 0
	s_add_i32 s35, s34, 0x6000
	v_add3_u32 v174, v185, s35, v184
	ds_read_b64_tr_b16 v[188:189], v182 offset:40960
	ds_read_b64_tr_b16 v[190:191], v182 offset:41472
	v_add_f32_e32 v88, v64, v65
	v_add_f32_e32 v88, v66, v88
	v_add_f32_e32 v88, v67, v88
	v_add_f32_e32 v88, v68, v88
	v_add_f32_e32 v88, v69, v88
	v_cvt_pk_bf16_f32 v140, v64, v65
	v_cvt_pk_bf16_f32 v141, v66, v67
	s_waitcnt lgkmcnt(9)
	v_mfma_f32_32x32x16_bf16 v[96:111], v[84:87], v[156:159], 0
	ds_read_b64_tr_b16 v[64:65], v182 offset:45056
	ds_read_b64_tr_b16 v[66:67], v182 offset:45568
	v_add_f32_e32 v84, v70, v88
	v_add_f32_e32 v84, v71, v84
	v_add_f32_e32 v84, v72, v84
	v_add_f32_e32 v128, v73, v84
	v_cvt_pk_bf16_f32 v142, v68, v69
	v_cvt_pk_bf16_f32 v143, v70, v71
	s_waitcnt lgkmcnt(10)
	v_mfma_f32_32x32x16_bf16 v[80:95], v[80:83], v[156:159], 0
	ds_read_b64_tr_b16 v[68:69], v182 offset:41984
	ds_read_b64_tr_b16 v[70:71], v182 offset:42496
	v_add_f32_e32 v128, v74, v128
	v_add_f32_e32 v128, v75, v128
	v_add_f32_e32 v128, v76, v128
	v_add_f32_e32 v128, v77, v128
	v_cvt_pk_bf16_f32 v136, v72, v73
	v_cvt_pk_bf16_f32 v137, v74, v75
	s_waitcnt lgkmcnt(11)
	v_mfma_f32_32x32x16_bf16 v[96:111], v[164:167], v[152:155], v[96:111]
	ds_read_b64_tr_b16 v[72:73], v182 offset:46080
	ds_read_b64_tr_b16 v[74:75], v182 offset:46592
	v_add_f32_e32 v128, v78, v128
	v_add_f32_e32 v128, v79, v128
	v_add_f32_e32 v128, v48, v128
	v_add_f32_e32 v128, v49, v128
	v_cvt_pk_bf16_f32 v138, v76, v77
	v_cvt_pk_bf16_f32 v139, v78, v79
	s_waitcnt lgkmcnt(12)
	v_mfma_f32_32x32x16_bf16 v[80:95], v[160:163], v[152:155], v[80:95]
	ds_read_b64_tr_b16 v[76:77], v182 offset:43008
	ds_read_b64_tr_b16 v[78:79], v182 offset:43520
	v_add_f32_e32 v128, v50, v128
	v_add_f32_e32 v128, v51, v128
	v_add_f32_e32 v128, v52, v128
	v_add_f32_e32 v128, v53, v128
	v_cvt_pk_bf16_f32 v132, v48, v49
	v_cvt_pk_bf16_f32 v133, v50, v51
	s_waitcnt lgkmcnt(13)
	v_mfma_f32_32x32x16_bf16 v[96:111], v[124:127], v[148:151], v[96:111]
	ds_read_b64_tr_b16 v[48:49], v182 offset:47104
	ds_read_b64_tr_b16 v[50:51], v182 offset:47616
	v_add_f32_e32 v124, v54, v128
	v_add_f32_e32 v124, v55, v124
	v_add_f32_e32 v124, v56, v124
	v_add_f32_e32 v124, v57, v124
	v_cvt_pk_bf16_f32 v134, v52, v53
	v_cvt_pk_bf16_f32 v135, v54, v55
	s_waitcnt lgkmcnt(14)
	v_mfma_f32_32x32x16_bf16 v[80:95], v[120:123], v[148:151], v[80:95]
	ds_read_b64_tr_b16 v[52:53], v182 offset:44032
	ds_read_b64_tr_b16 v[54:55], v182 offset:44544
	v_add_f32_e32 v120, v58, v124
	v_add_f32_e32 v120, v59, v120
	v_add_f32_e32 v120, v60, v120
	v_add_f32_e32 v120, v61, v120
	v_cvt_pk_bf16_f32 v128, v56, v57
	v_cvt_pk_bf16_f32 v129, v58, v59
	s_waitcnt lgkmcnt(14)
	v_mfma_f32_32x32x16_bf16 v[96:111], v[116:119], v[144:147], v[96:111]
	ds_read_b64_tr_b16 v[56:57], v182 offset:48128
	ds_read_b64_tr_b16 v[58:59], v182 offset:48640
	v_add_f32_e32 v116, v62, v120
	v_add_f32_e32 v116, v63, v116
	v_add_f32_e32 v116, 0, v116
	v_cvt_pk_bf16_f32 v130, v60, v61
	v_cvt_pk_bf16_f32 v131, v62, v63
	v_mfma_f32_32x32x16_bf16 v[80:95], v[112:115], v[144:147], v[80:95]
	v_lshl_add_u64 v[60:61], v[172:173], 0, s[40:41]
	s_mov_b32 s35, m0
	s_mov_b32 m0, s33
	s_nop 0
	global_load_lds_dwordx4 v[60:61], off
	s_mov_b32 m0, s35
	s_add_i32 s33, s34, s17
	v_lshl_add_u64 v[60:61], v[170:171], 0, s[42:43]
	s_add_i32 s17, s33, 0x8000
	s_mov_b32 s34, m0
	s_mov_b32 m0, s17
	s_nop 0
	global_load_lds_dwordx4 v[60:61], off
	s_mov_b32 m0, s34
	v_add_f32_e32 v175, v186, v116
	s_waitcnt lgkmcnt(14)
	v_mfma_f32_32x32x16_bf16 v[16:31], v[140:143], v[188:191], v[16:31]
	v_exp_f32_e32 v96, v96
	v_exp_f32_e32 v97, v97
	v_exp_f32_e32 v98, v98
	v_exp_f32_e32 v99, v99
	s_waitcnt lgkmcnt(12)
	v_mfma_f32_32x32x16_bf16 v[32:47], v[140:143], v[64:67], v[32:47]
	v_exp_f32_e32 v100, v100
	v_exp_f32_e32 v101, v101
	v_exp_f32_e32 v102, v102
	v_exp_f32_e32 v103, v103
	ds_read_b128 v[60:63], v234 offset:8192
	ds_read_b128 v[64:67], v234 offset:12288
	s_waitcnt lgkmcnt(12)
	v_mfma_f32_32x32x16_bf16 v[16:31], v[136:139], v[68:71], v[16:31]
	v_exp_f32_e32 v104, v104
	v_exp_f32_e32 v105, v105
	v_exp_f32_e32 v106, v106
	v_exp_f32_e32 v107, v107
	ds_read_b128 v[68:71], v235 offset:8192
	ds_read_b128 v[160:163], v235 offset:12288
	s_waitcnt lgkmcnt(12)
	v_mfma_f32_32x32x16_bf16 v[32:47], v[136:139], v[72:75], v[32:47]
	v_exp_f32_e32 v108, v108
	v_exp_f32_e32 v109, v109
	v_exp_f32_e32 v110, v110
	v_exp_f32_e32 v111, v111
	ds_read_b128 v[72:75], v236 offset:8192
	ds_read_b128 v[164:167], v236 offset:12288
	s_waitcnt lgkmcnt(12)
	v_mfma_f32_32x32x16_bf16 v[16:31], v[132:135], v[76:79], v[16:31]
	v_exp_f32_e32 v80, v80
	v_exp_f32_e32 v81, v81
	v_exp_f32_e32 v82, v82
	v_exp_f32_e32 v83, v83
	ds_read_b128 v[76:79], v237 offset:8192
	ds_read_b128 v[184:187], v237 offset:12288
	s_waitcnt lgkmcnt(12)
	v_mfma_f32_32x32x16_bf16 v[32:47], v[132:135], v[48:51], v[32:47]
	v_exp_f32_e32 v84, v84
	v_exp_f32_e32 v85, v85
	v_exp_f32_e32 v86, v86
	v_exp_f32_e32 v87, v87
	s_waitcnt lgkmcnt(10)
	v_mfma_f32_32x32x16_bf16 v[16:31], v[128:131], v[52:55], v[16:31]
	v_exp_f32_e32 v88, v88
	v_exp_f32_e32 v89, v89
	v_exp_f32_e32 v90, v90
	v_exp_f32_e32 v91, v91
	s_waitcnt lgkmcnt(8)
	v_mfma_f32_32x32x16_bf16 v[32:47], v[128:131], v[56:59], v[32:47]
	v_exp_f32_e32 v92, v92
	v_exp_f32_e32 v93, v93
	v_exp_f32_e32 v94, v94
	v_exp_f32_e32 v95, v95
	s_waitcnt vmcnt(2) lgkmcnt(0)
	s_barrier
; #define WAIT_BAR(N) asm volatile("s_waitcnt vmcnt(" #N ") lgkmcnt(0)\n\ts_barrier":::"memory")
;   #define RESC() do{ if(!NOMAX&&resc){ asm volatile("s_waitcnt lgkmcnt(0)":::"memory"); \
;       _Pragma("unroll") for(int d_=0;d_<2*VM;++d_) _Pragma("unroll") for(int r=0;r<16;++r)o[d_][r]*=wsf[crow(r,hi)]; } }while(0)
;   #define ROT() do{sl_prev=sl_cur;sl_cur=sl_next;sl_next=(sl_next==(NSLOT-1)*SLOTB)?0:sl_next+SLOTB;}while(0)
;   #define ENDW(tt) do{ if((tt)+3<NT){ if constexpr(VM==2){WAIT_BAR(3);}else{WAIT_BAR(2);} } else if((tt)+2<NT){ if constexpr(VM==2){WAIT_BAR(2);}else{WAIT_BAR(1);} } else {WAIT_BAR(0);} }while(0)
; template<int THRL,int VM,bool NOMAX> __device__ __forceinline__ void attn_unit(const bf16*Qb,const bf16*__restrict__ Kh,const bf16*__restrict__ Vh,bf16*Ob,const int NT,const int sp,float*wscr,char*shm){
;     ...
;   int t=1;
;   for(;t+5<NT;t+=2){
;     STEP(pB0,pB1,pA0,pA1,t,true,true,true);     if constexpr(VM==2){WAIT_BAR(3);}else{WAIT_BAR(2);} RESC(); ROT();
;     STEP(pA0,pA1,pB0,pB1,t+1,true,true,true);   if constexpr(VM==2){WAIT_BAR(3);}else{WAIT_BAR(2);} RESC(); ROT();
;   }
;     ...
;   for(;t+1<NT;t+=2){
;     STEP(pB0,pB1,pA0,pA1,t,(t+3<NT),(t+1<NT),(t+1<NT));       ENDW(t);   RESC(); ROT();
;     STEP(pA0,pA1,pB0,pB1,t+1,(t+4<NT),(t+2<NT),(t+2<NT));     ENDW(t+1); RESC(); ROT();
	ds_read_b64_tr_b16 v[188:189], v182 offset:24576
	ds_read_b64_tr_b16 v[190:191], v182 offset:25088
	v_add_f32_e32 v48, v96, v97
	v_add_f32_e32 v48, v98, v48
	v_add_f32_e32 v48, v99, v48
	v_add_f32_e32 v48, v100, v48
	v_add_f32_e32 v48, v101, v48
	v_cvt_pk_bf16_f32 v140, v96, v97
	v_cvt_pk_bf16_f32 v141, v98, v99
	s_waitcnt lgkmcnt(9)
	v_mfma_f32_32x32x16_bf16 v[112:127], v[60:63], v[156:159], 0
	ds_read_b64_tr_b16 v[96:97], v182 offset:28672
	ds_read_b64_tr_b16 v[98:99], v182 offset:29184
	v_add_f32_e32 v48, v102, v48
	v_add_f32_e32 v48, v103, v48
	v_add_f32_e32 v48, v104, v48
	v_add_f32_e32 v128, v105, v48
	s_waitcnt lgkmcnt(10)
	v_mfma_f32_32x32x16_bf16 v[48:63], v[64:67], v[156:159], 0
	v_cvt_pk_bf16_f32 v142, v100, v101
	v_cvt_pk_bf16_f32 v143, v102, v103
	ds_read_b64_tr_b16 v[64:65], v182 offset:25600
	ds_read_b64_tr_b16 v[66:67], v182 offset:26112
	v_add_f32_e32 v100, v106, v128
	v_add_f32_e32 v100, v107, v100
	v_add_f32_e32 v100, v108, v100
	v_add_f32_e32 v100, v109, v100
	v_cvt_pk_bf16_f32 v136, v104, v105
	v_cvt_pk_bf16_f32 v137, v106, v107
	s_waitcnt lgkmcnt(11)
	v_mfma_f32_32x32x16_bf16 v[112:127], v[68:71], v[152:155], v[112:127]
	ds_read_b64_tr_b16 v[68:69], v182 offset:29696
	ds_read_b64_tr_b16 v[70:71], v182 offset:30208
	s_waitcnt lgkmcnt(12)
	v_mfma_f32_32x32x16_bf16 v[48:63], v[160:163], v[152:155], v[48:63]
	v_add_f32_e32 v100, v110, v100
	v_add_f32_e32 v100, v111, v100
	v_add_f32_e32 v100, v80, v100
	v_add_f32_e32 v104, v81, v100
	v_cvt_pk_bf16_f32 v138, v108, v109
	v_cvt_pk_bf16_f32 v139, v110, v111
	ds_read_b64_tr_b16 v[100:101], v182 offset:26624
	ds_read_b64_tr_b16 v[102:103], v182 offset:27136
	v_add_f32_e32 v104, v82, v104
	v_add_f32_e32 v104, v83, v104
	v_add_f32_e32 v104, v84, v104
	v_add_f32_e32 v104, v85, v104
	v_cvt_pk_bf16_f32 v132, v80, v81
	v_cvt_pk_bf16_f32 v133, v82, v83
	s_waitcnt lgkmcnt(13)
	v_mfma_f32_32x32x16_bf16 v[112:127], v[72:75], v[148:151], v[112:127]
	ds_read_b64_tr_b16 v[72:73], v182 offset:30720
	ds_read_b64_tr_b16 v[74:75], v182 offset:31232
	s_waitcnt lgkmcnt(14)
	v_mfma_f32_32x32x16_bf16 v[48:63], v[164:167], v[148:151], v[48:63]
	v_add_f32_e32 v80, v86, v104
	v_add_f32_e32 v80, v87, v80
	v_add_f32_e32 v80, v88, v80
	v_add_f32_e32 v104, v89, v80
	v_cvt_pk_bf16_f32 v134, v84, v85
	v_cvt_pk_bf16_f32 v135, v86, v87
	ds_read_b64_tr_b16 v[80:81], v182 offset:27648
	ds_read_b64_tr_b16 v[82:83], v182 offset:28160
	v_add_f32_e32 v84, v90, v104
	v_add_f32_e32 v84, v91, v84
	v_add_f32_e32 v84, v92, v84
	v_add_f32_e32 v84, v93, v84
	v_cvt_pk_bf16_f32 v128, v88, v89
	v_cvt_pk_bf16_f32 v129, v90, v91
	s_waitcnt lgkmcnt(14)
	v_mfma_f32_32x32x16_bf16 v[112:127], v[76:79], v[144:147], v[112:127]
	ds_read_b64_tr_b16 v[76:77], v182 offset:31744
	ds_read_b64_tr_b16 v[78:79], v182 offset:32256
	v_mfma_f32_32x32x16_bf16 v[48:63], v[184:187], v[144:147], v[48:63]
	v_add_f32_e32 v84, v94, v84
	v_add_f32_e32 v84, v95, v84
	v_add_f32_e32 v84, 0, v84
	v_cvt_pk_bf16_f32 v130, v92, v93
	v_cvt_pk_bf16_f32 v131, v94, v95
	s_nop 0
	v_add_f32_e32 v175, v175, v84
	v_lshl_add_u64 v[84:85], v[172:173], 0, s[44:45]
	s_add_i32 s34, s33, 0x2000
	s_mov_b32 s35, m0
	s_mov_b32 m0, s34
	s_nop 0
	global_load_lds_dwordx4 v[84:85], off
	s_mov_b32 m0, s35
	v_lshl_add_u64 v[84:85], v[170:171], 0, s[48:49]
	s_add_i32 s33, s33, 0xa000
	s_mov_b32 s34, m0
	s_mov_b32 m0, s33
	s_nop 0
	global_load_lds_dwordx4 v[84:85], off
	s_mov_b32 m0, s34
	s_waitcnt lgkmcnt(14)
	v_mfma_f32_32x32x16_bf16 v[16:31], v[140:143], v[188:191], v[16:31]
	v_exp_f32_e32 v112, v112
	v_exp_f32_e32 v113, v113
	v_exp_f32_e32 v114, v114
	v_exp_f32_e32 v115, v115
	s_waitcnt lgkmcnt(12)
	v_mfma_f32_32x32x16_bf16 v[32:47], v[140:143], v[96:99], v[32:47]
	v_exp_f32_e32 v116, v116
	v_exp_f32_e32 v117, v117
	v_exp_f32_e32 v118, v118
	v_exp_f32_e32 v119, v119
	ds_read_b128 v[84:87], v234 offset:16384
	ds_read_b128 v[96:99], v234 offset:20480
	s_waitcnt lgkmcnt(12)
	v_mfma_f32_32x32x16_bf16 v[16:31], v[136:139], v[64:67], v[16:31]
	v_exp_f32_e32 v120, v120
	v_exp_f32_e32 v121, v121
	v_exp_f32_e32 v122, v122
	v_exp_f32_e32 v123, v123
	ds_read_b128 v[104:107], v235 offset:16384
	ds_read_b128 v[108:111], v235 offset:20480
	s_waitcnt lgkmcnt(12)
	v_mfma_f32_32x32x16_bf16 v[32:47], v[136:139], v[68:71], v[32:47]
	v_exp_f32_e32 v124, v124
	v_exp_f32_e32 v125, v125
	v_exp_f32_e32 v126, v126
	v_exp_f32_e32 v127, v127
	ds_read_b128 v[160:163], v236 offset:16384
	ds_read_b128 v[164:167], v236 offset:20480
	s_waitcnt lgkmcnt(12)
	v_mfma_f32_32x32x16_bf16 v[16:31], v[132:135], v[100:103], v[16:31]
	v_exp_f32_e32 v48, v48
	v_exp_f32_e32 v49, v49
	v_exp_f32_e32 v50, v50
	v_exp_f32_e32 v51, v51
	ds_read_b128 v[100:103], v237 offset:16384
	ds_read_b128 v[184:187], v237 offset:20480
	s_waitcnt lgkmcnt(12)
	v_mfma_f32_32x32x16_bf16 v[32:47], v[132:135], v[72:75], v[32:47]
	v_exp_f32_e32 v52, v52
	v_exp_f32_e32 v53, v53
	v_exp_f32_e32 v54, v54
	v_exp_f32_e32 v55, v55
	s_waitcnt lgkmcnt(10)
	v_mfma_f32_32x32x16_bf16 v[16:31], v[128:131], v[80:83], v[16:31]
	v_exp_f32_e32 v56, v56
	v_exp_f32_e32 v57, v57
	v_exp_f32_e32 v58, v58
	v_exp_f32_e32 v59, v59
	s_waitcnt lgkmcnt(8)
	v_mfma_f32_32x32x16_bf16 v[32:47], v[128:131], v[76:79], v[32:47]
	v_exp_f32_e32 v60, v60
	v_exp_f32_e32 v61, v61
	v_exp_f32_e32 v62, v62
	v_exp_f32_e32 v63, v63
	s_waitcnt vmcnt(2) lgkmcnt(0)
	s_barrier
; #define WAIT_BAR(N) asm volatile("s_waitcnt vmcnt(" #N ") lgkmcnt(0)\n\ts_barrier":::"memory")
;   #define RESC() do{ if(!NOMAX&&resc){ asm volatile("s_waitcnt lgkmcnt(0)":::"memory"); \
;       _Pragma("unroll") for(int d_=0;d_<2*VM;++d_) _Pragma("unroll") for(int r=0;r<16;++r)o[d_][r]*=wsf[crow(r,hi)]; } }while(0)
;   #define ROT() do{sl_prev=sl_cur;sl_cur=sl_next;sl_next=(sl_next==(NSLOT-1)*SLOTB)?0:sl_next+SLOTB;}while(0)
;   #define ENDW(tt) do{ if((tt)+3<NT){ if constexpr(VM==2){WAIT_BAR(3);}else{WAIT_BAR(2);} } else if((tt)+2<NT){ if constexpr(VM==2){WAIT_BAR(2);}else{WAIT_BAR(1);} } else {WAIT_BAR(0);} }while(0)
; template<int THRL,int VM,bool NOMAX> __device__ __forceinline__ void attn_unit(const bf16*Qb,const bf16*__restrict__ Kh,const bf16*__restrict__ Vh,bf16*Ob,const int NT,const int sp,float*wscr,char*shm){
;     ...
;   int t=1;
;   for(;t+5<NT;t+=2){
;     STEP(pB0,pB1,pA0,pA1,t,true,true,true);     if constexpr(VM==2){WAIT_BAR(3);}else{WAIT_BAR(2);} RESC(); ROT();
;     STEP(pA0,pA1,pB0,pB1,t+1,true,true,true);   if constexpr(VM==2){WAIT_BAR(3);}else{WAIT_BAR(2);} RESC(); ROT();
;   }
;     ...
;   for(;t+1<NT;t+=2){
;     STEP(pB0,pB1,pA0,pA1,t,(t+3<NT),(t+1<NT),(t+1<NT));       ENDW(t);   RESC(); ROT();
;     STEP(pA0,pA1,pB0,pB1,t+1,(t+4<NT),(t+2<NT),(t+2<NT));     ENDW(t+1); RESC(); ROT();
	ds_read_b64_tr_b16 v[188:189], v182 offset:32768
	ds_read_b64_tr_b16 v[190:191], v182 offset:33280
	v_add_f32_e32 v64, v112, v113
	v_add_f32_e32 v64, v114, v64
	v_add_f32_e32 v64, v115, v64
	v_add_f32_e32 v64, v116, v64
	v_add_f32_e32 v64, v117, v64
	v_cvt_pk_bf16_f32 v140, v112, v113
	v_cvt_pk_bf16_f32 v141, v114, v115
	s_waitcnt lgkmcnt(9)
	v_mfma_f32_32x32x16_bf16 v[80:95], v[84:87], v[156:159], 0
	ds_read_b64_tr_b16 v[112:113], v182 offset:36864
	ds_read_b64_tr_b16 v[114:115], v182 offset:37376
	v_add_f32_e32 v64, v118, v64
	v_add_f32_e32 v64, v119, v64
	v_add_f32_e32 v64, v120, v64
	v_add_f32_e32 v128, v121, v64
	v_cvt_pk_bf16_f32 v142, v116, v117
	v_cvt_pk_bf16_f32 v143, v118, v119
	s_waitcnt lgkmcnt(10)
	v_mfma_f32_32x32x16_bf16 v[64:79], v[96:99], v[156:159], 0
	ds_read_b64_tr_b16 v[96:97], v182 offset:33792
	ds_read_b64_tr_b16 v[98:99], v182 offset:34304
	v_add_f32_e32 v116, v122, v128
	v_add_f32_e32 v116, v123, v116
	v_add_f32_e32 v116, v124, v116
	v_add_f32_e32 v116, v125, v116
	v_cvt_pk_bf16_f32 v136, v120, v121
	v_cvt_pk_bf16_f32 v137, v122, v123
	s_waitcnt lgkmcnt(11)
	v_mfma_f32_32x32x16_bf16 v[80:95], v[104:107], v[152:155], v[80:95]
	ds_read_b64_tr_b16 v[104:105], v182 offset:37888
	ds_read_b64_tr_b16 v[106:107], v182 offset:38400
	v_add_f32_e32 v116, v126, v116
	v_add_f32_e32 v116, v127, v116
	v_add_f32_e32 v116, v48, v116
	v_add_f32_e32 v116, v49, v116
	v_cvt_pk_bf16_f32 v138, v124, v125
	v_cvt_pk_bf16_f32 v139, v126, v127
	s_waitcnt lgkmcnt(12)
	v_mfma_f32_32x32x16_bf16 v[64:79], v[108:111], v[152:155], v[64:79]
	ds_read_b64_tr_b16 v[108:109], v182 offset:34816
	ds_read_b64_tr_b16 v[110:111], v182 offset:35328
	v_add_f32_e32 v116, v50, v116
	v_add_f32_e32 v116, v51, v116
	v_add_f32_e32 v116, v52, v116
	v_add_f32_e32 v116, v53, v116
	v_cvt_pk_bf16_f32 v132, v48, v49
	v_cvt_pk_bf16_f32 v133, v50, v51
	s_waitcnt lgkmcnt(13)
	v_mfma_f32_32x32x16_bf16 v[80:95], v[160:163], v[148:151], v[80:95]
	ds_read_b64_tr_b16 v[48:49], v182 offset:38912
	ds_read_b64_tr_b16 v[50:51], v182 offset:39424
	v_add_f32_e32 v116, v54, v116
	v_add_f32_e32 v116, v55, v116
	v_add_f32_e32 v116, v56, v116
	v_add_f32_e32 v116, v57, v116
	v_cvt_pk_bf16_f32 v134, v52, v53
	v_cvt_pk_bf16_f32 v135, v54, v55
	s_waitcnt lgkmcnt(14)
	v_mfma_f32_32x32x16_bf16 v[64:79], v[164:167], v[148:151], v[64:79]
	ds_read_b64_tr_b16 v[52:53], v182 offset:35840
	ds_read_b64_tr_b16 v[54:55], v182 offset:36352
	v_add_f32_e32 v116, v58, v116
	v_add_f32_e32 v116, v59, v116
	v_add_f32_e32 v116, v60, v116
	v_add_f32_e32 v116, v61, v116
	v_cvt_pk_bf16_f32 v128, v56, v57
	v_cvt_pk_bf16_f32 v129, v58, v59
	s_waitcnt lgkmcnt(14)
	v_mfma_f32_32x32x16_bf16 v[80:95], v[100:103], v[144:147], v[80:95]
	ds_read_b64_tr_b16 v[56:57], v182 offset:39936
	ds_read_b64_tr_b16 v[58:59], v182 offset:40448
	v_add_f32_e32 v100, v62, v116
	v_add_f32_e32 v100, v63, v100
	v_add_f32_e32 v100, 0, v100
	v_cvt_pk_bf16_f32 v130, v60, v61
	v_cvt_pk_bf16_f32 v131, v62, v63
	v_mfma_f32_32x32x16_bf16 v[64:79], v[184:187], v[144:147], v[64:79]
	v_lshl_add_u64 v[60:61], v[170:171], 0, s[40:41]
	s_mov_b32 s33, m0
	s_mov_b32 m0, s16
	s_nop 0
	global_load_lds_dwordx4 v[60:61], off
	s_mov_b32 m0, s33
	v_add_f32_e32 v172, v175, v100
	s_waitcnt lgkmcnt(14)
	v_mfma_f32_32x32x16_bf16 v[16:31], v[140:143], v[188:191], v[16:31]
	v_exp_f32_e32 v80, v80
	v_exp_f32_e32 v81, v81
	v_exp_f32_e32 v82, v82
	v_exp_f32_e32 v83, v83
	s_waitcnt lgkmcnt(12)
	v_mfma_f32_32x32x16_bf16 v[32:47], v[140:143], v[112:115], v[32:47]
	v_exp_f32_e32 v84, v84
	v_exp_f32_e32 v85, v85
	v_exp_f32_e32 v86, v86
	v_exp_f32_e32 v87, v87
	ds_read_b128 v[60:63], v234
	ds_read_b128 v[112:115], v234 offset:4096
	s_waitcnt lgkmcnt(12)
	v_mfma_f32_32x32x16_bf16 v[16:31], v[136:139], v[96:99], v[16:31]
	v_exp_f32_e32 v88, v88
	v_exp_f32_e32 v89, v89
	v_exp_f32_e32 v90, v90
	v_exp_f32_e32 v91, v91
	ds_read_b128 v[116:119], v235
	ds_read_b128 v[120:123], v235 offset:4096
	s_waitcnt lgkmcnt(12)
	v_mfma_f32_32x32x16_bf16 v[32:47], v[136:139], v[104:107], v[32:47]
	v_exp_f32_e32 v92, v92
	v_exp_f32_e32 v93, v93
	v_exp_f32_e32 v94, v94
	v_exp_f32_e32 v95, v95
	ds_read_b128 v[124:127], v236
	ds_read_b128 v[160:163], v236 offset:4096
	s_waitcnt lgkmcnt(12)
	v_mfma_f32_32x32x16_bf16 v[16:31], v[132:135], v[108:111], v[16:31]
	v_exp_f32_e32 v64, v64
	v_exp_f32_e32 v65, v65
	v_exp_f32_e32 v66, v66
	v_exp_f32_e32 v67, v67
	ds_read_b128 v[164:167], v237
	ds_read_b128 v[184:187], v237 offset:4096
	s_waitcnt lgkmcnt(12)
	v_mfma_f32_32x32x16_bf16 v[32:47], v[132:135], v[48:51], v[32:47]
	v_exp_f32_e32 v68, v68
	v_exp_f32_e32 v69, v69
	v_exp_f32_e32 v70, v70
	v_exp_f32_e32 v71, v71
	s_waitcnt lgkmcnt(10)
	v_mfma_f32_32x32x16_bf16 v[16:31], v[128:131], v[52:55], v[16:31]
	v_exp_f32_e32 v72, v72
	v_exp_f32_e32 v73, v73
	v_exp_f32_e32 v74, v74
	v_exp_f32_e32 v75, v75
	s_waitcnt lgkmcnt(8)
	v_mfma_f32_32x32x16_bf16 v[32:47], v[128:131], v[56:59], v[32:47]
	v_exp_f32_e32 v76, v76
	v_exp_f32_e32 v77, v77
	v_exp_f32_e32 v78, v78
	v_exp_f32_e32 v79, v79
	s_waitcnt vmcnt(1) lgkmcnt(0)
	s_barrier
; #define WAIT_BAR(N) asm volatile("s_waitcnt vmcnt(" #N ") lgkmcnt(0)\n\ts_barrier":::"memory")
;   #define RESC() do{ if(!NOMAX&&resc){ asm volatile("s_waitcnt lgkmcnt(0)":::"memory"); \
;       _Pragma("unroll") for(int d_=0;d_<2*VM;++d_) _Pragma("unroll") for(int r=0;r<16;++r)o[d_][r]*=wsf[crow(r,hi)]; } }while(0)
;   #define ROT() do{sl_prev=sl_cur;sl_cur=sl_next;sl_next=(sl_next==(NSLOT-1)*SLOTB)?0:sl_next+SLOTB;}while(0)
;   #define ENDW(tt) do{ if((tt)+3<NT){ if constexpr(VM==2){WAIT_BAR(3);}else{WAIT_BAR(2);} } else if((tt)+2<NT){ if constexpr(VM==2){WAIT_BAR(2);}else{WAIT_BAR(1);} } else {WAIT_BAR(0);} }while(0)
; template<int THRL,int VM,bool NOMAX> __device__ __forceinline__ void attn_unit(const bf16*Qb,const bf16*__restrict__ Kh,const bf16*__restrict__ Vh,bf16*Ob,const int NT,const int sp,float*wscr,char*shm){
;     ...
;   int t=1;
;   for(;t+5<NT;t+=2){
;     STEP(pB0,pB1,pA0,pA1,t,true,true,true);     if constexpr(VM==2){WAIT_BAR(3);}else{WAIT_BAR(2);} RESC(); ROT();
;     STEP(pA0,pA1,pB0,pB1,t+1,true,true,true);   if constexpr(VM==2){WAIT_BAR(3);}else{WAIT_BAR(2);} RESC(); ROT();
;   }
;     ...
;   for(;t+1<NT;t+=2){
;     STEP(pB0,pB1,pA0,pA1,t,(t+3<NT),(t+1<NT),(t+1<NT));       ENDW(t);   RESC(); ROT();
;     STEP(pA0,pA1,pB0,pB1,t+1,(t+4<NT),(t+2<NT),(t+2<NT));     ENDW(t+1); RESC(); ROT();
	ds_read_b64_tr_b16 v[188:189], v182 offset:40960
	ds_read_b64_tr_b16 v[190:191], v182 offset:41472
	v_add_f32_e32 v48, v80, v81
	v_add_f32_e32 v48, v82, v48
	v_add_f32_e32 v48, v83, v48
	v_add_f32_e32 v48, v84, v48
	v_add_f32_e32 v48, v85, v48
	v_cvt_pk_bf16_f32 v140, v80, v81
	v_cvt_pk_bf16_f32 v141, v82, v83
	s_waitcnt lgkmcnt(9)
	v_mfma_f32_32x32x16_bf16 v[96:111], v[60:63], v[156:159], 0
	ds_read_b64_tr_b16 v[80:81], v182 offset:45056
	ds_read_b64_tr_b16 v[82:83], v182 offset:45568
	v_add_f32_e32 v48, v86, v48
	v_add_f32_e32 v48, v87, v48
	v_add_f32_e32 v48, v88, v48
	v_add_f32_e32 v128, v89, v48
	s_waitcnt lgkmcnt(10)
	v_mfma_f32_32x32x16_bf16 v[48:63], v[112:115], v[156:159], 0
	v_cvt_pk_bf16_f32 v142, v84, v85
	v_cvt_pk_bf16_f32 v143, v86, v87
	ds_read_b64_tr_b16 v[84:85], v182 offset:41984
	ds_read_b64_tr_b16 v[86:87], v182 offset:42496
	v_add_f32_e32 v112, v90, v128
	v_add_f32_e32 v112, v91, v112
	v_add_f32_e32 v112, v92, v112
	v_add_f32_e32 v112, v93, v112
	v_cvt_pk_bf16_f32 v136, v88, v89
	v_cvt_pk_bf16_f32 v137, v90, v91
	s_waitcnt lgkmcnt(11)
	v_mfma_f32_32x32x16_bf16 v[96:111], v[116:119], v[152:155], v[96:111]
	ds_read_b64_tr_b16 v[88:89], v182 offset:46080
	ds_read_b64_tr_b16 v[90:91], v182 offset:46592
	s_waitcnt lgkmcnt(12)
	v_mfma_f32_32x32x16_bf16 v[48:63], v[120:123], v[152:155], v[48:63]
	v_add_f32_e32 v112, v94, v112
	v_add_f32_e32 v112, v95, v112
	v_add_f32_e32 v112, v64, v112
	v_add_f32_e32 v112, v65, v112
	v_cvt_pk_bf16_f32 v138, v92, v93
	v_cvt_pk_bf16_f32 v139, v94, v95
	ds_read_b64_tr_b16 v[92:93], v182 offset:43008
	ds_read_b64_tr_b16 v[94:95], v182 offset:43520
	v_add_f32_e32 v112, v66, v112
	v_add_f32_e32 v112, v67, v112
	v_add_f32_e32 v112, v68, v112
	v_add_f32_e32 v112, v69, v112
	v_cvt_pk_bf16_f32 v132, v64, v65
	v_cvt_pk_bf16_f32 v133, v66, v67
	s_waitcnt lgkmcnt(13)
	v_mfma_f32_32x32x16_bf16 v[96:111], v[124:127], v[148:151], v[96:111]
	ds_read_b64_tr_b16 v[64:65], v182 offset:47104
	ds_read_b64_tr_b16 v[66:67], v182 offset:47616
	s_waitcnt lgkmcnt(14)
	v_mfma_f32_32x32x16_bf16 v[48:63], v[160:163], v[148:151], v[48:63]
	v_add_f32_e32 v112, v70, v112
	v_add_f32_e32 v112, v71, v112
	v_add_f32_e32 v112, v72, v112
	v_add_f32_e32 v112, v73, v112
	v_cvt_pk_bf16_f32 v134, v68, v69
	v_cvt_pk_bf16_f32 v135, v70, v71
	ds_read_b64_tr_b16 v[68:69], v182 offset:44032
	ds_read_b64_tr_b16 v[70:71], v182 offset:44544
	v_add_f32_e32 v112, v74, v112
	v_add_f32_e32 v112, v75, v112
	v_add_f32_e32 v112, v76, v112
	v_add_f32_e32 v112, v77, v112
	v_cvt_pk_bf16_f32 v128, v72, v73
	v_cvt_pk_bf16_f32 v129, v74, v75
	s_waitcnt lgkmcnt(14)
	v_mfma_f32_32x32x16_bf16 v[96:111], v[164:167], v[144:147], v[96:111]
	ds_read_b64_tr_b16 v[72:73], v182 offset:48128
	ds_read_b64_tr_b16 v[74:75], v182 offset:48640
	v_mfma_f32_32x32x16_bf16 v[48:63], v[184:187], v[144:147], v[48:63]
	v_add_f32_e32 v112, v78, v112
	v_add_f32_e32 v112, v79, v112
	v_add_f32_e32 v112, 0, v112
	v_cvt_pk_bf16_f32 v130, v76, v77
	v_cvt_pk_bf16_f32 v131, v78, v79
	v_lshl_add_u64 v[76:77], v[170:171], 0, s[44:45]
	s_mov_b32 s16, m0
	s_mov_b32 m0, s17
	s_nop 0
	global_load_lds_dwordx4 v[76:77], off
	s_mov_b32 m0, s16
	v_add_f32_e32 v120, v172, v112
	s_waitcnt lgkmcnt(14)
	v_mfma_f32_32x32x16_bf16 v[16:31], v[140:143], v[188:191], v[16:31]
	v_exp_f32_e32 v96, v96
	v_exp_f32_e32 v97, v97
	v_exp_f32_e32 v98, v98
	v_exp_f32_e32 v99, v99
	s_waitcnt lgkmcnt(12)
	v_mfma_f32_32x32x16_bf16 v[32:47], v[140:143], v[80:83], v[32:47]
	v_exp_f32_e32 v100, v100
	v_exp_f32_e32 v101, v101
	v_exp_f32_e32 v102, v102
	v_exp_f32_e32 v103, v103
	ds_read_b128 v[76:79], v234 offset:8192
	ds_read_b128 v[80:83], v234 offset:12288
	s_waitcnt lgkmcnt(12)
	v_mfma_f32_32x32x16_bf16 v[16:31], v[136:139], v[84:87], v[16:31]
	v_exp_f32_e32 v104, v104
	v_exp_f32_e32 v105, v105
	v_exp_f32_e32 v106, v106
	v_exp_f32_e32 v107, v107
	ds_read_b128 v[122:125], v235 offset:8192
	ds_read_b128 v[160:163], v235 offset:12288
	s_waitcnt lgkmcnt(12)
	v_mfma_f32_32x32x16_bf16 v[32:47], v[136:139], v[88:91], v[32:47]
	v_exp_f32_e32 v108, v108
	v_exp_f32_e32 v109, v109
	v_exp_f32_e32 v110, v110
	v_exp_f32_e32 v111, v111
	ds_read_b128 v[164:167], v236 offset:8192
	ds_read_b128 v[170:173], v236 offset:12288
	s_waitcnt lgkmcnt(12)
	v_mfma_f32_32x32x16_bf16 v[16:31], v[132:135], v[92:95], v[16:31]
	v_exp_f32_e32 v48, v48
	v_exp_f32_e32 v49, v49
	v_exp_f32_e32 v50, v50
	v_exp_f32_e32 v51, v51
	ds_read_b128 v[184:187], v237 offset:8192
	ds_read_b128 v[188:191], v237 offset:12288
	s_waitcnt lgkmcnt(12)
	v_mfma_f32_32x32x16_bf16 v[32:47], v[132:135], v[64:67], v[32:47]
	v_exp_f32_e32 v52, v52
	v_exp_f32_e32 v53, v53
	v_exp_f32_e32 v54, v54
	v_exp_f32_e32 v55, v55
	s_waitcnt lgkmcnt(10)
	v_mfma_f32_32x32x16_bf16 v[16:31], v[128:131], v[68:71], v[16:31]
	v_exp_f32_e32 v56, v56
	v_exp_f32_e32 v57, v57
	v_exp_f32_e32 v58, v58
	v_exp_f32_e32 v59, v59
	s_waitcnt lgkmcnt(8)
	v_mfma_f32_32x32x16_bf16 v[32:47], v[128:131], v[72:75], v[32:47]
	v_exp_f32_e32 v60, v60
	v_exp_f32_e32 v61, v61
	v_exp_f32_e32 v62, v62
	v_exp_f32_e32 v63, v63
	s_waitcnt vmcnt(0) lgkmcnt(0)
	s_barrier
;   #define RESC() do{ if(!NOMAX&&resc){ asm volatile("s_waitcnt lgkmcnt(0)":::"memory"); \
;       _Pragma("unroll") for(int d_=0;d_<2*VM;++d_) _Pragma("unroll") for(int r=0;r<16;++r)o[d_][r]*=wsf[crow(r,hi)]; } }while(0)
; template<int THRL,int VM,bool NOMAX> __device__ __forceinline__ void attn_unit(const bf16*Qb,const bf16*__restrict__ Kh,const bf16*__restrict__ Vh,bf16*Ob,const int NT,const int sp,float*wscr,char*shm){
;     ...
;   STEP(pB0,pB1,pA0,pA1,NT-1,false,false,false); RESC();
	ds_read_b64_tr_b16 v[112:113], v182 offset:24576
	ds_read_b64_tr_b16 v[114:115], v182 offset:25088
	v_add_f32_e32 v64, v96, v97
	v_add_f32_e32 v64, v98, v64
	v_add_f32_e32 v64, v99, v64
	v_add_f32_e32 v64, v100, v64
	v_add_f32_e32 v84, v101, v64
	v_cvt_pk_bf16_f32 v140, v96, v97
	v_cvt_pk_bf16_f32 v141, v98, v99
	s_waitcnt lgkmcnt(9)
	v_mfma_f32_32x32x16_bf16 v[64:79], v[76:79], v[156:159], 0
	ds_read_b64_tr_b16 v[96:97], v182 offset:28672
	ds_read_b64_tr_b16 v[98:99], v182 offset:29184
	v_add_f32_e32 v84, v102, v84
	v_add_f32_e32 v84, v103, v84
	v_add_f32_e32 v84, v104, v84
	v_add_f32_e32 v121, v105, v84
	v_cvt_pk_bf16_f32 v142, v100, v101
	v_cvt_pk_bf16_f32 v143, v102, v103
	s_waitcnt lgkmcnt(10)
	v_mfma_f32_32x32x16_bf16 v[80:95], v[80:83], v[156:159], 0
	ds_read_b64_tr_b16 v[116:117], v182 offset:25600
	ds_read_b64_tr_b16 v[118:119], v182 offset:26112
	v_add_f32_e32 v100, v106, v121
	v_add_f32_e32 v100, v107, v100
	v_add_f32_e32 v100, v108, v100
	v_add_f32_e32 v121, v109, v100
	v_cvt_pk_bf16_f32 v136, v104, v105
	v_cvt_pk_bf16_f32 v137, v106, v107
	s_waitcnt lgkmcnt(11)
	v_mfma_f32_32x32x16_bf16 v[64:79], v[122:125], v[152:155], v[64:79]
	ds_read_b64_tr_b16 v[100:101], v182 offset:29696
	ds_read_b64_tr_b16 v[102:103], v182 offset:30208
	v_add_f32_e32 v104, v110, v121
	v_add_f32_e32 v104, v111, v104
	v_add_f32_e32 v104, v48, v104
	v_add_f32_e32 v121, v49, v104
	v_cvt_pk_bf16_f32 v138, v108, v109
	v_cvt_pk_bf16_f32 v139, v110, v111
	s_waitcnt lgkmcnt(12)
	v_mfma_f32_32x32x16_bf16 v[80:95], v[160:163], v[152:155], v[80:95]
	ds_read_b64_tr_b16 v[104:105], v182 offset:26624
	ds_read_b64_tr_b16 v[106:107], v182 offset:27136
	v_add_f32_e32 v108, v50, v121
	v_add_f32_e32 v108, v51, v108
	v_add_f32_e32 v108, v52, v108
	v_add_f32_e32 v108, v53, v108
	v_cvt_pk_bf16_f32 v132, v48, v49
	v_cvt_pk_bf16_f32 v133, v50, v51
	s_waitcnt lgkmcnt(13)
	v_mfma_f32_32x32x16_bf16 v[64:79], v[164:167], v[148:151], v[64:79]
	ds_read_b64_tr_b16 v[48:49], v182 offset:30720
	ds_read_b64_tr_b16 v[50:51], v182 offset:31232
	v_add_f32_e32 v108, v54, v108
	v_add_f32_e32 v108, v55, v108
	v_add_f32_e32 v108, v56, v108
	v_add_f32_e32 v121, v57, v108
	v_cvt_pk_bf16_f32 v134, v52, v53
	v_cvt_pk_bf16_f32 v135, v54, v55
	s_waitcnt lgkmcnt(14)
	v_mfma_f32_32x32x16_bf16 v[80:95], v[170:173], v[148:151], v[80:95]
	ds_read_b64_tr_b16 v[108:109], v182 offset:27648
	ds_read_b64_tr_b16 v[110:111], v182 offset:28160
	v_add_f32_e32 v52, v58, v121
	v_add_f32_e32 v52, v59, v52
	v_add_f32_e32 v52, v60, v52
	v_add_f32_e32 v121, v61, v52
	v_cvt_pk_bf16_f32 v128, v56, v57
	v_cvt_pk_bf16_f32 v129, v58, v59
	s_waitcnt lgkmcnt(14)
	v_mfma_f32_32x32x16_bf16 v[64:79], v[184:187], v[144:147], v[64:79]
	ds_read_b64_tr_b16 v[52:53], v182 offset:31744
	ds_read_b64_tr_b16 v[54:55], v182 offset:32256
	v_add_f32_e32 v56, v62, v121
	v_add_f32_e32 v56, v63, v56
	v_add_f32_e32 v56, 0, v56
	v_cvt_pk_bf16_f32 v130, v60, v61
	v_cvt_pk_bf16_f32 v131, v62, v63
	v_mfma_f32_32x32x16_bf16 v[80:95], v[188:191], v[144:147], v[80:95]
	s_nop 3
	v_exp_f32_e32 v64, v64
	v_exp_f32_e32 v65, v65
	v_exp_f32_e32 v66, v66
	v_exp_f32_e32 v67, v67
	s_nop 0
	v_exp_f32_e32 v68, v68
	v_exp_f32_e32 v69, v69
	v_exp_f32_e32 v70, v70
	v_exp_f32_e32 v71, v71
	s_nop 0
	v_exp_f32_e32 v72, v72
	v_exp_f32_e32 v73, v73
	v_exp_f32_e32 v74, v74
	v_exp_f32_e32 v75, v75
	s_nop 0
	v_exp_f32_e32 v76, v76
	v_exp_f32_e32 v77, v77
	v_exp_f32_e32 v78, v78
	v_exp_f32_e32 v79, v79
	v_exp_f32_e32 v80, v80
	v_exp_f32_e32 v81, v81
	v_exp_f32_e32 v82, v82
	v_exp_f32_e32 v83, v83
	s_nop 0
	v_exp_f32_e32 v84, v84
	v_exp_f32_e32 v85, v85
	v_exp_f32_e32 v86, v86
	v_exp_f32_e32 v87, v87
	s_nop 0
	v_exp_f32_e32 v88, v88
	v_exp_f32_e32 v89, v89
	v_exp_f32_e32 v90, v90
	v_exp_f32_e32 v91, v91
	s_nop 0
	v_exp_f32_e32 v92, v92
	v_exp_f32_e32 v93, v93
	v_exp_f32_e32 v94, v94
	v_exp_f32_e32 v95, v95
	s_waitcnt lgkmcnt(14)
; #define SBAR() __builtin_amdgcn_sched_barrier(0)
;   #define RESC() do{ if(!NOMAX&&resc){ asm volatile("s_waitcnt lgkmcnt(0)":::"memory"); \
;       _Pragma("unroll") for(int d_=0;d_<2*VM;++d_) _Pragma("unroll") for(int r=0;r<16;++r)o[d_][r]*=wsf[crow(r,hi)]; } }while(0)
;   #define PKW(P,B) cvtpk_s(P[B],P[B+1])
; __device__ __forceinline__ void pv(f32x16*o,int vb,bf16x8 pa0,bf16x8 pa1,bf16x8 pa2,bf16x8 pa3){
;   #pragma unroll
;   for(int d0=0;d0<2;++d0){s16x4 lo[4],hi[4];
;     #pragma unroll
;     for(int ks=0;ks<4;++ks){
;       asm volatile("ds_read_b64_tr_b16 %0,%1 offset:%c2":"=&v"(lo[ks]):"v"(vb),"i"(d0*4096+ks*1024):"memory");
;       asm volatile("ds_read_b64_tr_b16 %0,%1 offset:%c2":"=&v"(hi[ks]):"v"(vb),"i"(d0*4096+ks*1024+512):"memory");}
;     asm volatile("s_waitcnt lgkmcnt(0)":::"memory");SBAR();
;     ...
;     o[d0]=__builtin_amdgcn_mfma_f32_32x32x16_bf16(pa0,PK(0),o[d0],0,0,0);
;     o[d0]=__builtin_amdgcn_mfma_f32_32x32x16_bf16(pa1,PK(1),o[d0],0,0,0);
;     o[d0]=__builtin_amdgcn_mfma_f32_32x32x16_bf16(pa2,PK(2),o[d0],0,0,0);
;     o[d0]=__builtin_amdgcn_mfma_f32_32x32x16_bf16(pa3,PK(3),o[d0],0,0,0);
;     ...
;   }
; }
; template<int THRL,int VM,bool NOMAX> __device__ __forceinline__ void attn_unit(const bf16*Qb,const bf16*__restrict__ Kh,const bf16*__restrict__ Vh,bf16*Ob,const int NT,const int sp,float*wscr,char*shm){
;     ...
;   STEP(pB0,pB1,pA0,pA1,NT-1,false,false,false); RESC();
;   { float sacc=pB0[0]+pB0[1]; _Pragma("unroll") for(int r=2;r<16;++r)sacc+=pB0[r]; _Pragma("unroll") for(int r=0;r<16;++r)sacc+=pB1[r]; l_reg+=sacc;
;     pw0=(u32x4){PKW(pB0,0),PKW(pB0,2),PKW(pB0,4),PKW(pB0,6)};pw1=(u32x4){PKW(pB0,8),PKW(pB0,10),PKW(pB0,12),PKW(pB0,14)};pw2=(u32x4){PKW(pB1,0),PKW(pB1,2),PKW(pB1,4),PKW(pB1,6)};pw3=(u32x4){PKW(pB1,8),PKW(pB1,10),PKW(pB1,12),PKW(pB1,14)};
;     SBAR(); pv(o,vb0+VM*sl_cur,PAF(0),PAF(1),PAF(2),PAF(3)); if constexpr(VM==2) pv(o+2,vb0+VM*sl_cur+8192,PAF(0),PAF(1),PAF(2),PAF(3)); }
;     ...
;   {auto rr=__builtin_amdgcn_permlane32_swap(__float_as_uint(l_reg),__float_as_uint(l_reg),false,false);l_reg=__uint_as_float(rr[0])+__uint_as_float(rr[1]);}
;   if(hi==0)wsf[32+r32]=l_reg;asm volatile("s_waitcnt lgkmcnt(0)":::"memory");
	v_mfma_f32_32x32x16_bf16 v[16:31], v[140:143], v[112:115], v[16:31]
	v_add_f32_e32 v57, v64, v65
	v_add_f32_e32 v57, v66, v57
	v_add_f32_e32 v57, v67, v57
	v_add_f32_e32 v57, v68, v57
	v_add_f32_e32 v57, v69, v57
	v_add_f32_e32 v57, v70, v57
	v_add_f32_e32 v57, v71, v57
	s_waitcnt lgkmcnt(12)
	v_mfma_f32_32x32x16_bf16 v[32:47], v[140:143], v[96:99], v[32:47]
	v_add_f32_e32 v57, v72, v57
	v_add_f32_e32 v57, v73, v57
	v_add_f32_e32 v57, v74, v57
	v_add_f32_e32 v57, v75, v57
	v_add_f32_e32 v57, v76, v57
	v_add_f32_e32 v57, v77, v57
	v_add_f32_e32 v57, v78, v57
	s_waitcnt lgkmcnt(10)
	v_mfma_f32_32x32x16_bf16 v[16:31], v[136:139], v[116:119], v[16:31]
	v_add_f32_e32 v57, v79, v57
	v_add_f32_e32 v57, v80, v57
	v_add_f32_e32 v57, v81, v57
	v_add_f32_e32 v57, v82, v57
	v_add_f32_e32 v57, v83, v57
	v_add_f32_e32 v57, v84, v57
	v_add_f32_e32 v57, v85, v57
	s_waitcnt lgkmcnt(8)
	v_mfma_f32_32x32x16_bf16 v[32:47], v[136:139], v[100:103], v[32:47]
	v_add_f32_e32 v57, v86, v57
	v_add_f32_e32 v57, v87, v57
	v_add_f32_e32 v57, v88, v57
	v_add_f32_e32 v57, v89, v57
	v_add_f32_e32 v57, v90, v57
	v_add_f32_e32 v57, v91, v57
	v_add_f32_e32 v57, v92, v57
	s_waitcnt lgkmcnt(6)
	v_mfma_f32_32x32x16_bf16 v[16:31], v[132:135], v[104:107], v[16:31]
	v_add_f32_e32 v57, v93, v57
	v_add_f32_e32 v57, v94, v57
	v_add_f32_e32 v57, v95, v57
	v_add_f32_e32 v56, v120, v56
	v_add_f32_e32 v56, v56, v57
	v_cvt_pk_bf16_f32 v58, v64, v65
	v_cvt_pk_bf16_f32 v59, v66, v67
	s_waitcnt lgkmcnt(4)
	v_mfma_f32_32x32x16_bf16 v[32:47], v[132:135], v[48:51], v[32:47]
	v_cvt_pk_bf16_f32 v48, v80, v81
	v_cvt_pk_bf16_f32 v60, v68, v69
	v_cvt_pk_bf16_f32 v61, v70, v71
	v_cvt_pk_bf16_f32 v62, v72, v73
	v_cvt_pk_bf16_f32 v63, v74, v75
	v_cvt_pk_bf16_f32 v64, v76, v77
	v_cvt_pk_bf16_f32 v65, v78, v79
	s_waitcnt lgkmcnt(2)
	v_mfma_f32_32x32x16_bf16 v[16:31], v[128:131], v[108:111], v[16:31]
	v_cvt_pk_bf16_f32 v49, v82, v83
	v_cvt_pk_bf16_f32 v50, v84, v85
	v_cvt_pk_bf16_f32 v51, v86, v87
	v_cvt_pk_bf16_f32 v66, v88, v89
	v_cvt_pk_bf16_f32 v67, v90, v91
	v_cvt_pk_bf16_f32 v68, v92, v93
	v_cvt_pk_bf16_f32 v69, v94, v95
	s_waitcnt lgkmcnt(0)
	v_mfma_f32_32x32x16_bf16 v[32:47], v[128:131], v[52:55], v[32:47]
	v_add3_u32 v57, v174, v168, s18
	ds_read_b64_tr_b16 v[52:53],v57 offset:0
	ds_read_b64_tr_b16 v[54:55],v57 offset:512
	ds_read_b64_tr_b16 v[70:71],v57 offset:1024
	ds_read_b64_tr_b16 v[72:73],v57 offset:1536
	ds_read_b64_tr_b16 v[74:75],v57 offset:2048
	ds_read_b64_tr_b16 v[76:77],v57 offset:2560
	ds_read_b64_tr_b16 v[78:79],v57 offset:3072
	ds_read_b64_tr_b16 v[80:81],v57 offset:3584
	s_waitcnt lgkmcnt(0)
	s_nop 0
	v_mfma_f32_32x32x16_bf16 v[16:31], v[58:61], v[52:55], v[16:31]
	ds_read_b64_tr_b16 v[52:53],v57 offset:4096
	ds_read_b64_tr_b16 v[54:55],v57 offset:4608
	v_mfma_f32_32x32x16_bf16 v[16:31], v[62:65], v[70:73], v[16:31]
	ds_read_b64_tr_b16 v[70:71],v57 offset:5120
	ds_read_b64_tr_b16 v[72:73],v57 offset:5632
	v_mfma_f32_32x32x16_bf16 v[16:31], v[48:51], v[74:77], v[16:31]
	ds_read_b64_tr_b16 v[74:75],v57 offset:6144
	ds_read_b64_tr_b16 v[76:77],v57 offset:6656
	ds_read_b64_tr_b16 v[82:83],v57 offset:7168
	ds_read_b64_tr_b16 v[84:85],v57 offset:7680
	s_waitcnt lgkmcnt(0)
	v_mfma_f32_32x32x16_bf16 v[16:31], v[66:69], v[78:81], v[16:31]
	v_mfma_f32_32x32x16_bf16 v[32:47], v[58:61], v[52:55], v[32:47]
	v_cmp_gt_u32_e32 vcc, 32, v178
	v_mfma_f32_32x32x16_bf16 v[32:47], v[62:65], v[70:73], v[32:47]
	v_mfma_f32_32x32x16_bf16 v[32:47], v[48:51], v[74:77], v[32:47]
	v_mov_b32_e32 v48, v56
	s_nop 1
	v_permlane32_swap_b32_e32 v56, v48
	v_mfma_f32_32x32x16_bf16 v[32:47], v[66:69], v[82:85], v[32:47]
	s_and_saveexec_b64 s[16:17], vcc
	s_cbranch_execz .LBB0_878
	v_add_f32_e32 v48, v56, v48
	v_lshl_add_u32 v49, v180, 2, s29
	ds_write_b32 v49, v48 offset:49280
	s_branch .LBB0_878

; #define WAIT_BAR(N) asm volatile("s_waitcnt vmcnt(" #N ") lgkmcnt(0)\n\ts_barrier":::"memory")
;   #define RESC() do{ if(!NOMAX&&resc){ asm volatile("s_waitcnt lgkmcnt(0)":::"memory"); \
;       _Pragma("unroll") for(int d_=0;d_<2*VM;++d_) _Pragma("unroll") for(int r=0;r<16;++r)o[d_][r]*=wsf[crow(r,hi)]; } }while(0)
;   #define ROT() do{sl_prev=sl_cur;sl_cur=sl_next;sl_next=(sl_next==(NSLOT-1)*SLOTB)?0:sl_next+SLOTB;}while(0)
; template<int THRL,int VM,bool NOMAX> __device__ __forceinline__ void attn_unit(const bf16*Qb,const bf16*__restrict__ Kh,const bf16*__restrict__ Vh,bf16*Ob,const int NT,const int sp,float*wscr,char*shm){
;     ...
;   int t=1;
;   for(;t+5<NT;t+=2){
;     STEP(pB0,pB1,pA0,pA1,t,true,true,true);     if constexpr(VM==2){WAIT_BAR(3);}else{WAIT_BAR(2);} RESC(); ROT();
;     STEP(pA0,pA1,pB0,pB1,t+1,true,true,true);   if constexpr(VM==2){WAIT_BAR(3);}else{WAIT_BAR(2);} RESC(); ROT();
.LBB0_891:
	v_mfma_f32_32x32x16_bf16 v[96:111], v[84:87], v[156:159], 0
	v_add_u32_e32 v187, s52, v168
	ds_read_b64_tr_b16 v[188:189], v187 offset:24576
	ds_read_b64_tr_b16 v[190:191], v187 offset:25088
	v_add_f32_e32 v88, v64, v65
	v_add_f32_e32 v88, v66, v88
	v_add_f32_e32 v88, v67, v88
	v_add_f32_e32 v88, v68, v88
	v_add_f32_e32 v88, v69, v88
	v_cvt_pk_bf16_f32 v140, v64, v65
	v_cvt_pk_bf16_f32 v141, v66, v67
	ds_read_b64_tr_b16 v[64:65], v187 offset:28672
	ds_read_b64_tr_b16 v[66:67], v187 offset:29184
	v_add_f32_e32 v84, v70, v88
	v_add_f32_e32 v84, v71, v84
	v_add_f32_e32 v84, v72, v84
	v_add_f32_e32 v128, v73, v84
	s_waitcnt lgkmcnt(10)
	v_mfma_f32_32x32x16_bf16 v[80:95], v[80:83], v[156:159], 0
	v_cvt_pk_bf16_f32 v142, v68, v69
	v_cvt_pk_bf16_f32 v143, v70, v71
	ds_read_b64_tr_b16 v[68:69], v187 offset:25600
	ds_read_b64_tr_b16 v[70:71], v187 offset:26112
	v_add_f32_e32 v128, v74, v128
	v_add_f32_e32 v128, v75, v128
	v_add_f32_e32 v128, v76, v128
	v_add_f32_e32 v128, v77, v128
	v_cvt_pk_bf16_f32 v136, v72, v73
	v_cvt_pk_bf16_f32 v137, v74, v75
	s_waitcnt lgkmcnt(11)
	v_mfma_f32_32x32x16_bf16 v[96:111], v[164:167], v[152:155], v[96:111]
	ds_read_b64_tr_b16 v[72:73], v187 offset:29696
	ds_read_b64_tr_b16 v[74:75], v187 offset:30208
	s_waitcnt lgkmcnt(12)
	v_mfma_f32_32x32x16_bf16 v[80:95], v[160:163], v[152:155], v[80:95]
	v_add_f32_e32 v128, v78, v128
	v_add_f32_e32 v128, v79, v128
	v_add_f32_e32 v128, v48, v128
	v_add_f32_e32 v128, v49, v128
	v_cvt_pk_bf16_f32 v138, v76, v77
	v_cvt_pk_bf16_f32 v139, v78, v79
	ds_read_b64_tr_b16 v[76:77], v187 offset:26624
	ds_read_b64_tr_b16 v[78:79], v187 offset:27136
	v_add_f32_e32 v128, v50, v128
	v_add_f32_e32 v128, v51, v128
	v_add_f32_e32 v128, v52, v128
	v_add_f32_e32 v128, v53, v128
	v_cvt_pk_bf16_f32 v132, v48, v49
	v_cvt_pk_bf16_f32 v133, v50, v51
	s_waitcnt lgkmcnt(13)
	v_mfma_f32_32x32x16_bf16 v[96:111], v[124:127], v[148:151], v[96:111]
	ds_read_b64_tr_b16 v[48:49], v187 offset:30720
	ds_read_b64_tr_b16 v[50:51], v187 offset:31232
	s_waitcnt lgkmcnt(14)
	v_mfma_f32_32x32x16_bf16 v[80:95], v[120:123], v[148:151], v[80:95]
	v_add_f32_e32 v124, v54, v128
	v_add_f32_e32 v124, v55, v124
	v_add_f32_e32 v124, v56, v124
	v_add_f32_e32 v124, v57, v124
	v_cvt_pk_bf16_f32 v134, v52, v53
	v_cvt_pk_bf16_f32 v135, v54, v55
	ds_read_b64_tr_b16 v[52:53], v187 offset:27648
	ds_read_b64_tr_b16 v[54:55], v187 offset:28160
	v_add_f32_e32 v120, v58, v124
	v_add_f32_e32 v120, v59, v120
	v_add_f32_e32 v120, v60, v120
	v_add_f32_e32 v120, v61, v120
	v_cvt_pk_bf16_f32 v128, v56, v57
	v_cvt_pk_bf16_f32 v129, v58, v59
	s_waitcnt lgkmcnt(14)
	v_mfma_f32_32x32x16_bf16 v[96:111], v[116:119], v[144:147], v[96:111]
	ds_read_b64_tr_b16 v[56:57], v187 offset:31744
	ds_read_b64_tr_b16 v[58:59], v187 offset:32256
	v_mfma_f32_32x32x16_bf16 v[80:95], v[112:115], v[144:147], v[80:95]
	v_add_f32_e32 v116, v62, v120
	v_add_f32_e32 v116, v63, v116
	v_add_f32_e32 v116, 0, v116
	v_cvt_pk_bf16_f32 v130, v60, v61
	v_cvt_pk_bf16_f32 v131, v62, v63
	v_add_f32_e32 v202, v186, v116
	s_waitcnt lgkmcnt(14)
	v_mfma_f32_32x32x16_bf16 v[16:31], v[140:143], v[188:191], v[16:31]
	v_exp_f32_e32 v96, v96
	v_exp_f32_e32 v97, v97
	v_exp_f32_e32 v98, v98
	v_exp_f32_e32 v99, v99
	s_waitcnt lgkmcnt(12)
	v_mfma_f32_32x32x16_bf16 v[32:47], v[140:143], v[64:67], v[32:47]
	v_exp_f32_e32 v100, v100
	v_exp_f32_e32 v101, v101
	v_exp_f32_e32 v102, v102
	v_exp_f32_e32 v103, v103
	v_add_u32_e32 v242, s33, v234
	v_add_u32_e32 v243, s33, v235
	v_add_u32_e32 v244, s33, v236
	v_add_u32_e32 v245, s33, v237
	ds_read_b128 v[60:63], v242
	ds_read_b128 v[112:115], v242 offset:4096
	s_waitcnt lgkmcnt(12)
	v_mfma_f32_32x32x16_bf16 v[16:31], v[136:139], v[68:71], v[16:31]
	v_exp_f32_e32 v104, v104
	v_exp_f32_e32 v105, v105
	v_exp_f32_e32 v106, v106
	v_exp_f32_e32 v107, v107
	ds_read_b128 v[116:119], v243
	ds_read_b128 v[120:123], v243 offset:4096
	s_waitcnt lgkmcnt(12)
	v_mfma_f32_32x32x16_bf16 v[32:47], v[136:139], v[72:75], v[32:47]
	v_exp_f32_e32 v108, v108
	v_exp_f32_e32 v109, v109
	v_exp_f32_e32 v110, v110
	v_exp_f32_e32 v111, v111
	ds_read_b128 v[124:127], v244
	ds_read_b128 v[160:163], v244 offset:4096
	s_waitcnt lgkmcnt(12)
	v_mfma_f32_32x32x16_bf16 v[16:31], v[132:135], v[76:79], v[16:31]
	v_exp_f32_e32 v80, v80
	v_exp_f32_e32 v81, v81
	v_exp_f32_e32 v82, v82
	v_exp_f32_e32 v83, v83
	ds_read_b128 v[164:167], v245
	ds_read_b128 v[186:189], v245 offset:4096
	s_waitcnt lgkmcnt(12)
	v_mfma_f32_32x32x16_bf16 v[32:47], v[132:135], v[48:51], v[32:47]
	v_lshl_add_u64 v[238:239], v[176:177], 0, s[38:39]
	s_add_i32 s35, s34, s17
	s_mov_b32 s52, m0
	s_mov_b32 m0, s35
	s_nop 0
	global_load_lds_dwordx4 v[238:239], off
	s_mov_b32 m0, s52
	v_exp_f32_e32 v84, v84
	v_exp_f32_e32 v85, v85
	v_exp_f32_e32 v86, v86
	v_exp_f32_e32 v87, v87
	s_waitcnt lgkmcnt(10)
	v_mfma_f32_32x32x16_bf16 v[16:31], v[128:131], v[52:55], v[16:31]
	v_lshl_add_u64 v[238:239], v[174:175], 0, s[38:39]
	s_add_i32 s35, s33, s16
	s_mov_b32 s52, m0
	s_mov_b32 m0, s35
	s_nop 0
	global_load_lds_dwordx4 v[238:239], off
	s_mov_b32 m0, s52
	v_exp_f32_e32 v88, v88
	v_exp_f32_e32 v89, v89
	v_exp_f32_e32 v90, v90
	v_exp_f32_e32 v91, v91
	s_waitcnt lgkmcnt(8)
	v_mfma_f32_32x32x16_bf16 v[32:47], v[128:131], v[56:59], v[32:47]
	v_exp_f32_e32 v92, v92
	v_exp_f32_e32 v93, v93
	v_exp_f32_e32 v94, v94
	v_exp_f32_e32 v95, v95
	s_waitcnt vmcnt(2) lgkmcnt(0)
	s_barrier
; #define WAIT_BAR(N) asm volatile("s_waitcnt vmcnt(" #N ") lgkmcnt(0)\n\ts_barrier":::"memory")
;   #define RESC() do{ if(!NOMAX&&resc){ asm volatile("s_waitcnt lgkmcnt(0)":::"memory"); \
;       _Pragma("unroll") for(int d_=0;d_<2*VM;++d_) _Pragma("unroll") for(int r=0;r<16;++r)o[d_][r]*=wsf[crow(r,hi)]; } }while(0)
;   #define ROT() do{sl_prev=sl_cur;sl_cur=sl_next;sl_next=(sl_next==(NSLOT-1)*SLOTB)?0:sl_next+SLOTB;}while(0)
; template<int THRL,int VM,bool NOMAX> __device__ __forceinline__ void attn_unit(const bf16*Qb,const bf16*__restrict__ Kh,const bf16*__restrict__ Vh,bf16*Ob,const int NT,const int sp,float*wscr,char*shm){
;     ...
;   int t=1;
;   for(;t+5<NT;t+=2){
;     STEP(pB0,pB1,pA0,pA1,t,true,true,true);     if constexpr(VM==2){WAIT_BAR(3);}else{WAIT_BAR(2);} RESC(); ROT();
;     STEP(pA0,pA1,pB0,pB1,t+1,true,true,true);   if constexpr(VM==2){WAIT_BAR(3);}else{WAIT_BAR(2);} RESC(); ROT();
	v_mfma_f32_32x32x16_bf16 v[64:79], v[60:63], v[156:159], 0
	s_add_i32 s35, s33, 0x2000
	s_cmpk_lg_i32 s33, 0x4000
	s_cselect_b32 s35, s35, 0
	v_add_u32_e32 v203, s34, v168
	ds_read_b64_tr_b16 v[190:191], v203 offset:24576
	ds_read_b64_tr_b16 v[192:193], v203 offset:25088
	v_add_f32_e32 v48, v96, v97
	v_add_f32_e32 v48, v98, v48
	v_add_f32_e32 v48, v99, v48
	v_add_f32_e32 v48, v100, v48
	v_add_f32_e32 v48, v101, v48
	v_cvt_pk_bf16_f32 v140, v96, v97
	v_cvt_pk_bf16_f32 v141, v98, v99
	ds_read_b64_tr_b16 v[96:97], v203 offset:28672
	ds_read_b64_tr_b16 v[98:99], v203 offset:29184
	v_add_f32_e32 v48, v102, v48
	v_add_f32_e32 v48, v103, v48
	v_add_f32_e32 v48, v104, v48
	v_add_f32_e32 v128, v105, v48
	s_waitcnt lgkmcnt(10)
	v_mfma_f32_32x32x16_bf16 v[48:63], v[112:115], v[156:159], 0
	v_cvt_pk_bf16_f32 v142, v100, v101
	v_cvt_pk_bf16_f32 v143, v102, v103
	ds_read_b64_tr_b16 v[100:101], v203 offset:25600
	ds_read_b64_tr_b16 v[102:103], v203 offset:26112
	s_waitcnt lgkmcnt(11)
	v_mfma_f32_32x32x16_bf16 v[64:79], v[116:119], v[152:155], v[64:79]
	v_add_f32_e32 v112, v106, v128
	v_add_f32_e32 v112, v107, v112
	v_add_f32_e32 v112, v108, v112
	v_add_f32_e32 v112, v109, v112
	v_cvt_pk_bf16_f32 v136, v104, v105
	v_cvt_pk_bf16_f32 v137, v106, v107
	ds_read_b64_tr_b16 v[104:105], v203 offset:29696
	ds_read_b64_tr_b16 v[106:107], v203 offset:30208
	s_waitcnt lgkmcnt(12)
	v_mfma_f32_32x32x16_bf16 v[48:63], v[120:123], v[152:155], v[48:63]
	v_add_f32_e32 v112, v110, v112
	v_add_f32_e32 v112, v111, v112
	v_add_f32_e32 v112, v80, v112
	v_add_f32_e32 v112, v81, v112
	v_cvt_pk_bf16_f32 v138, v108, v109
	v_cvt_pk_bf16_f32 v139, v110, v111
	ds_read_b64_tr_b16 v[108:109], v203 offset:26624
	ds_read_b64_tr_b16 v[110:111], v203 offset:27136
	s_waitcnt lgkmcnt(13)
	v_mfma_f32_32x32x16_bf16 v[64:79], v[124:127], v[148:151], v[64:79]
	v_add_f32_e32 v112, v82, v112
	v_add_f32_e32 v112, v83, v112
	v_add_f32_e32 v112, v84, v112
	v_add_f32_e32 v112, v85, v112
	v_cvt_pk_bf16_f32 v132, v80, v81
	v_cvt_pk_bf16_f32 v133, v82, v83
	ds_read_b64_tr_b16 v[194:195], v203 offset:30720
	ds_read_b64_tr_b16 v[196:197], v203 offset:31232
	s_waitcnt lgkmcnt(14)
	v_mfma_f32_32x32x16_bf16 v[48:63], v[160:163], v[148:151], v[48:63]
	v_add_f32_e32 v80, v86, v112
	v_add_f32_e32 v80, v87, v80
	v_add_f32_e32 v80, v88, v80
	v_add_f32_e32 v80, v89, v80
	v_cvt_pk_bf16_f32 v134, v84, v85
	v_cvt_pk_bf16_f32 v135, v86, v87
	ds_read_b64_tr_b16 v[198:199], v203 offset:27648
	ds_read_b64_tr_b16 v[200:201], v203 offset:28160
	s_waitcnt lgkmcnt(14)
	v_mfma_f32_32x32x16_bf16 v[64:79], v[164:167], v[144:147], v[64:79]
	v_add_f32_e32 v80, v90, v80
	v_add_f32_e32 v80, v91, v80
	v_add_f32_e32 v80, v92, v80
	v_add_f32_e32 v80, v93, v80
	v_cvt_pk_bf16_f32 v128, v88, v89
	v_cvt_pk_bf16_f32 v129, v90, v91
	ds_read_b64_tr_b16 v[88:89], v203 offset:31744
	ds_read_b64_tr_b16 v[90:91], v203 offset:32256
	v_mfma_f32_32x32x16_bf16 v[48:63], v[186:189], v[144:147], v[48:63]
	v_add_f32_e32 v80, v94, v80
	v_add_f32_e32 v80, v95, v80
	v_add_f32_e32 v80, 0, v80
	v_cvt_pk_bf16_f32 v130, v92, v93
	v_cvt_pk_bf16_f32 v131, v94, v95
	v_add_f32_e32 v186, v202, v80
	s_waitcnt lgkmcnt(14)
	v_mfma_f32_32x32x16_bf16 v[16:31], v[140:143], v[190:193], v[16:31]
	v_exp_f32_e32 v64, v64
	v_exp_f32_e32 v65, v65
	v_exp_f32_e32 v66, v66
	v_exp_f32_e32 v67, v67
	s_waitcnt lgkmcnt(12)
	v_mfma_f32_32x32x16_bf16 v[32:47], v[140:143], v[96:99], v[32:47]
	v_exp_f32_e32 v68, v68
	v_exp_f32_e32 v69, v69
	v_exp_f32_e32 v70, v70
	v_exp_f32_e32 v71, v71
	v_add_u32_e32 v242, s35, v234
	v_add_u32_e32 v243, s35, v235
	v_add_u32_e32 v244, s35, v236
	v_add_u32_e32 v245, s35, v237
	ds_read_b128 v[84:87], v242
	ds_read_b128 v[80:83], v242 offset:4096
	s_waitcnt lgkmcnt(12)
	v_mfma_f32_32x32x16_bf16 v[16:31], v[136:139], v[100:103], v[16:31]
	v_exp_f32_e32 v72, v72
	v_exp_f32_e32 v73, v73
	v_exp_f32_e32 v74, v74
	v_exp_f32_e32 v75, v75
	ds_read_b128 v[164:167], v243
	ds_read_b128 v[160:163], v243 offset:4096
	s_waitcnt lgkmcnt(12)
	v_mfma_f32_32x32x16_bf16 v[32:47], v[136:139], v[104:107], v[32:47]
	v_exp_f32_e32 v76, v76
	v_exp_f32_e32 v77, v77
	v_exp_f32_e32 v78, v78
	v_exp_f32_e32 v79, v79
	ds_read_b128 v[124:127], v244
	ds_read_b128 v[120:123], v244 offset:4096
	s_waitcnt lgkmcnt(12)
	v_mfma_f32_32x32x16_bf16 v[16:31], v[132:135], v[108:111], v[16:31]
	v_exp_f32_e32 v48, v48
	v_exp_f32_e32 v49, v49
	v_exp_f32_e32 v50, v50
	v_exp_f32_e32 v51, v51
	ds_read_b128 v[116:119], v245
	ds_read_b128 v[112:115], v245 offset:4096
	s_waitcnt lgkmcnt(12)
	v_mfma_f32_32x32x16_bf16 v[32:47], v[132:135], v[194:197], v[32:47]
	s_add_i32 s34, s33, s17
	s_mov_b32 s52, m0
	s_mov_b32 m0, s34
	s_nop 0
	global_load_lds_dwordx4 v[176:177], off
	s_mov_b32 m0, s52
	v_exp_f32_e32 v52, v52
	v_exp_f32_e32 v53, v53
	v_exp_f32_e32 v54, v54
	v_exp_f32_e32 v55, v55
	s_waitcnt lgkmcnt(10)
	v_mfma_f32_32x32x16_bf16 v[16:31], v[128:131], v[198:201], v[16:31]
	s_add_i32 s34, s35, s16
	s_mov_b32 s52, m0
	s_mov_b32 m0, s34
	s_nop 0
	global_load_lds_dwordx4 v[174:175], off
	s_mov_b32 m0, s52
	v_exp_f32_e32 v56, v56
	v_exp_f32_e32 v57, v57
	v_exp_f32_e32 v58, v58
	v_exp_f32_e32 v59, v59
	s_waitcnt lgkmcnt(8)
	v_mfma_f32_32x32x16_bf16 v[32:47], v[128:131], v[88:91], v[32:47]
	v_exp_f32_e32 v60, v60
	v_exp_f32_e32 v61, v61
	v_exp_f32_e32 v62, v62
	v_exp_f32_e32 v63, v63
	s_add_i32 s53, s35, 0x2000
	s_waitcnt vmcnt(2) lgkmcnt(0)
	s_barrier
	s_cmpk_lg_i32 s35, 0x4000
	s_mov_b32 s52, s33
	s_cselect_b32 s33, s53, 0
	s_add_i32 s29, s29, 2
	v_lshl_add_u64 v[174:175], v[174:175], 0, s[8:9]
	v_lshl_add_u64 v[176:177], v[176:177], 0, s[8:9]
	s_mov_b32 s34, s35
	s_cmp_lt_u32 s29, 57
	s_cbranch_scc1 .LBB0_891
;   #define RESC() do{ if(!NOMAX&&resc){ asm volatile("s_waitcnt lgkmcnt(0)":::"memory"); \
;       _Pragma("unroll") for(int d_=0;d_<2*VM;++d_) _Pragma("unroll") for(int r=0;r<16;++r)o[d_][r]*=wsf[crow(r,hi)]; } }while(0)
;   #define ROT() do{sl_prev=sl_cur;sl_cur=sl_next;sl_next=(sl_next==(NSLOT-1)*SLOTB)?0:sl_next+SLOTB;}while(0)
;   #define ENDW(tt) do{ if((tt)+3<NT){ if constexpr(VM==2){WAIT_BAR(3);}else{WAIT_BAR(2);} } else if((tt)+2<NT){ if constexpr(VM==2){WAIT_BAR(2);}else{WAIT_BAR(1);} } else {WAIT_BAR(0);} }while(0)
; template<int THRL,int VM,bool NOMAX> __device__ __forceinline__ void attn_unit(const bf16*Qb,const bf16*__restrict__ Kh,const bf16*__restrict__ Vh,bf16*Ob,const int NT,const int sp,float*wscr,char*shm){
;     ...
;   for(;t+1<NT;t+=2){
;     STEP(pB0,pB1,pA0,pA1,t,(t+3<NT),(t+1<NT),(t+1<NT));       ENDW(t);   RESC(); ROT();
	s_and_b32 s19, s19, 0x3fffffc0
	s_lshl_b32 s19, s19, 2
	s_add_i32 s19, s19, 0
	s_cmp_lg_u32 0, -1
	s_cselect_b32 s29, 0, 0
	s_add_i32 s33, s29, 0x6000
	v_add_u32_e32 v88, s33, v184
	v_add3_u32 v174, v88, v183, v185
	ds_read_b64_tr_b16 v[188:189], v168 offset:32768
	ds_read_b64_tr_b16 v[190:191], v168 offset:33280
	v_add_f32_e32 v88, v64, v65
	v_add_f32_e32 v88, v66, v88
	v_add_f32_e32 v88, v67, v88
	v_add_f32_e32 v88, v68, v88
	v_add_f32_e32 v88, v69, v88
	v_cvt_pk_bf16_f32 v140, v64, v65
	v_cvt_pk_bf16_f32 v141, v66, v67
	s_waitcnt lgkmcnt(9)
	v_mfma_f32_32x32x16_bf16 v[96:111], v[84:87], v[156:159], 0
	ds_read_b64_tr_b16 v[64:65], v168 offset:36864
	ds_read_b64_tr_b16 v[66:67], v168 offset:37376
	v_add_f32_e32 v84, v70, v88
	v_add_f32_e32 v84, v71, v84
	v_add_f32_e32 v84, v72, v84
	v_add_f32_e32 v128, v73, v84
	v_cvt_pk_bf16_f32 v142, v68, v69
	v_cvt_pk_bf16_f32 v143, v70, v71
	s_waitcnt lgkmcnt(10)
	v_mfma_f32_32x32x16_bf16 v[80:95], v[80:83], v[156:159], 0
	ds_read_b64_tr_b16 v[68:69], v168 offset:33792
	ds_read_b64_tr_b16 v[70:71], v168 offset:34304
	v_add_f32_e32 v128, v74, v128
	v_add_f32_e32 v128, v75, v128
	v_add_f32_e32 v128, v76, v128
	v_add_f32_e32 v128, v77, v128
	v_cvt_pk_bf16_f32 v136, v72, v73
	v_cvt_pk_bf16_f32 v137, v74, v75
	s_waitcnt lgkmcnt(11)
	v_mfma_f32_32x32x16_bf16 v[96:111], v[164:167], v[152:155], v[96:111]
	ds_read_b64_tr_b16 v[72:73], v168 offset:37888
	ds_read_b64_tr_b16 v[74:75], v168 offset:38400
	v_add_f32_e32 v128, v78, v128
	v_add_f32_e32 v128, v79, v128
	v_add_f32_e32 v128, v48, v128
	v_add_f32_e32 v128, v49, v128
	v_cvt_pk_bf16_f32 v138, v76, v77
	v_cvt_pk_bf16_f32 v139, v78, v79
	s_waitcnt lgkmcnt(12)
	v_mfma_f32_32x32x16_bf16 v[80:95], v[160:163], v[152:155], v[80:95]
	ds_read_b64_tr_b16 v[76:77], v168 offset:34816
	ds_read_b64_tr_b16 v[78:79], v168 offset:35328
	v_add_f32_e32 v128, v50, v128
	v_add_f32_e32 v128, v51, v128
	v_add_f32_e32 v128, v52, v128
	v_add_f32_e32 v128, v53, v128
	v_cvt_pk_bf16_f32 v132, v48, v49
	v_cvt_pk_bf16_f32 v133, v50, v51
	s_waitcnt lgkmcnt(13)
	v_mfma_f32_32x32x16_bf16 v[96:111], v[124:127], v[148:151], v[96:111]
	ds_read_b64_tr_b16 v[48:49], v168 offset:38912
	ds_read_b64_tr_b16 v[50:51], v168 offset:39424
	v_add_f32_e32 v124, v54, v128
	v_add_f32_e32 v124, v55, v124
	v_add_f32_e32 v124, v56, v124
	v_add_f32_e32 v124, v57, v124
	v_cvt_pk_bf16_f32 v134, v52, v53
	v_cvt_pk_bf16_f32 v135, v54, v55
	s_waitcnt lgkmcnt(14)
	v_mfma_f32_32x32x16_bf16 v[80:95], v[120:123], v[148:151], v[80:95]
	ds_read_b64_tr_b16 v[52:53], v168 offset:35840
	ds_read_b64_tr_b16 v[54:55], v168 offset:36352
	v_add_f32_e32 v120, v58, v124
	v_add_f32_e32 v120, v59, v120
	v_add_f32_e32 v120, v60, v120
	v_add_f32_e32 v120, v61, v120
	v_cvt_pk_bf16_f32 v128, v56, v57
	v_cvt_pk_bf16_f32 v129, v58, v59
	s_waitcnt lgkmcnt(14)
	v_mfma_f32_32x32x16_bf16 v[96:111], v[116:119], v[144:147], v[96:111]
	ds_read_b64_tr_b16 v[56:57], v168 offset:39936
	ds_read_b64_tr_b16 v[58:59], v168 offset:40448
	v_add_f32_e32 v116, v62, v120
	v_add_f32_e32 v116, v63, v116
	v_add_f32_e32 v116, 0, v116
	v_cvt_pk_bf16_f32 v130, v60, v61
	v_cvt_pk_bf16_f32 v131, v62, v63
	v_mfma_f32_32x32x16_bf16 v[80:95], v[112:115], v[144:147], v[80:95]
	s_add_i32 s28, s29, s28
	v_lshl_add_u64 v[60:61], v[172:173], 0, s[40:41]
	s_add_i32 s29, s28, 0x4000
	s_mov_b32 s33, m0
	s_mov_b32 m0, s29
	s_nop 0
	global_load_lds_dwordx4 v[60:61], off
	s_mov_b32 m0, s33
	v_lshl_add_u64 v[60:61], v[170:171], 0, s[42:43]
	s_mov_b32 s29, m0
	s_mov_b32 m0, s16
	s_nop 0
	global_load_lds_dwordx4 v[60:61], off
	s_mov_b32 m0, s29
	v_add_f32_e32 v175, v186, v116
	s_waitcnt lgkmcnt(14)
	v_mfma_f32_32x32x16_bf16 v[16:31], v[140:143], v[188:191], v[16:31]
	v_exp_f32_e32 v96, v96
	v_exp_f32_e32 v97, v97
	v_exp_f32_e32 v98, v98
	v_exp_f32_e32 v99, v99
	s_waitcnt lgkmcnt(12)
	v_mfma_f32_32x32x16_bf16 v[32:47], v[140:143], v[64:67], v[32:47]
	v_exp_f32_e32 v100, v100
	v_exp_f32_e32 v101, v101
	v_exp_f32_e32 v102, v102
	v_exp_f32_e32 v103, v103
	ds_read_b128 v[60:63], v234
	ds_read_b128 v[64:67], v234 offset:4096
	s_waitcnt lgkmcnt(12)
	v_mfma_f32_32x32x16_bf16 v[16:31], v[136:139], v[68:71], v[16:31]
	v_exp_f32_e32 v104, v104
	v_exp_f32_e32 v105, v105
	v_exp_f32_e32 v106, v106
	v_exp_f32_e32 v107, v107
	ds_read_b128 v[68:71], v235
	ds_read_b128 v[160:163], v235 offset:4096
	s_waitcnt lgkmcnt(12)
	v_mfma_f32_32x32x16_bf16 v[32:47], v[136:139], v[72:75], v[32:47]
	v_exp_f32_e32 v108, v108
	v_exp_f32_e32 v109, v109
	v_exp_f32_e32 v110, v110
	v_exp_f32_e32 v111, v111
	ds_read_b128 v[72:75], v236
	ds_read_b128 v[164:167], v236 offset:4096
	s_waitcnt lgkmcnt(12)
	v_mfma_f32_32x32x16_bf16 v[16:31], v[132:135], v[76:79], v[16:31]
	v_exp_f32_e32 v80, v80
	v_exp_f32_e32 v81, v81
	v_exp_f32_e32 v82, v82
	v_exp_f32_e32 v83, v83
	ds_read_b128 v[76:79], v237
	ds_read_b128 v[184:187], v237 offset:4096
	s_waitcnt lgkmcnt(12)
	v_mfma_f32_32x32x16_bf16 v[32:47], v[132:135], v[48:51], v[32:47]
	v_exp_f32_e32 v84, v84
	v_exp_f32_e32 v85, v85
	v_exp_f32_e32 v86, v86
	v_exp_f32_e32 v87, v87
	s_waitcnt lgkmcnt(10)
	v_mfma_f32_32x32x16_bf16 v[16:31], v[128:131], v[52:55], v[16:31]
	v_exp_f32_e32 v88, v88
	v_exp_f32_e32 v89, v89
	v_exp_f32_e32 v90, v90
	v_exp_f32_e32 v91, v91
	s_waitcnt lgkmcnt(8)
	v_mfma_f32_32x32x16_bf16 v[32:47], v[128:131], v[56:59], v[32:47]
	v_exp_f32_e32 v92, v92
	v_exp_f32_e32 v93, v93
	v_exp_f32_e32 v94, v94
	v_exp_f32_e32 v95, v95
	s_waitcnt vmcnt(2) lgkmcnt(0)
	s_barrier
;   #define RESC() do{ if(!NOMAX&&resc){ asm volatile("s_waitcnt lgkmcnt(0)":::"memory"); \
;       _Pragma("unroll") for(int d_=0;d_<2*VM;++d_) _Pragma("unroll") for(int r=0;r<16;++r)o[d_][r]*=wsf[crow(r,hi)]; } }while(0)
;   #define ROT() do{sl_prev=sl_cur;sl_cur=sl_next;sl_next=(sl_next==(NSLOT-1)*SLOTB)?0:sl_next+SLOTB;}while(0)
;   #define ENDW(tt) do{ if((tt)+3<NT){ if constexpr(VM==2){WAIT_BAR(3);}else{WAIT_BAR(2);} } else if((tt)+2<NT){ if constexpr(VM==2){WAIT_BAR(2);}else{WAIT_BAR(1);} } else {WAIT_BAR(0);} }while(0)
; template<int THRL,int VM,bool NOMAX> __device__ __forceinline__ void attn_unit(const bf16*Qb,const bf16*__restrict__ Kh,const bf16*__restrict__ Vh,bf16*Ob,const int NT,const int sp,float*wscr,char*shm){
;     ...
;   for(;t+1<NT;t+=2){
;     STEP(pB0,pB1,pA0,pA1,t,(t+3<NT),(t+1<NT),(t+1<NT));       ENDW(t);   RESC(); ROT();
;     STEP(pA0,pA1,pB0,pB1,t+1,(t+4<NT),(t+2<NT),(t+2<NT));     ENDW(t+1); RESC(); ROT();
	ds_read_b64_tr_b16 v[188:189], v168 offset:40960
	ds_read_b64_tr_b16 v[190:191], v168 offset:41472
	v_add_f32_e32 v48, v96, v97
	v_add_f32_e32 v48, v98, v48
	v_add_f32_e32 v48, v99, v48
	v_add_f32_e32 v48, v100, v48
	v_add_f32_e32 v48, v101, v48
	v_cvt_pk_bf16_f32 v140, v96, v97
	v_cvt_pk_bf16_f32 v141, v98, v99
	s_waitcnt lgkmcnt(9)
	v_mfma_f32_32x32x16_bf16 v[112:127], v[60:63], v[156:159], 0
	ds_read_b64_tr_b16 v[96:97], v168 offset:45056
	ds_read_b64_tr_b16 v[98:99], v168 offset:45568
	v_add_f32_e32 v48, v102, v48
	v_add_f32_e32 v48, v103, v48
	v_add_f32_e32 v48, v104, v48
	v_add_f32_e32 v128, v105, v48
	s_waitcnt lgkmcnt(10)
	v_mfma_f32_32x32x16_bf16 v[48:63], v[64:67], v[156:159], 0
	v_cvt_pk_bf16_f32 v142, v100, v101
	v_cvt_pk_bf16_f32 v143, v102, v103
	ds_read_b64_tr_b16 v[64:65], v168 offset:41984
	ds_read_b64_tr_b16 v[66:67], v168 offset:42496
	v_add_f32_e32 v100, v106, v128
	v_add_f32_e32 v100, v107, v100
	v_add_f32_e32 v100, v108, v100
	v_add_f32_e32 v100, v109, v100
	v_cvt_pk_bf16_f32 v136, v104, v105
	v_cvt_pk_bf16_f32 v137, v106, v107
	s_waitcnt lgkmcnt(11)
	v_mfma_f32_32x32x16_bf16 v[112:127], v[68:71], v[152:155], v[112:127]
	ds_read_b64_tr_b16 v[68:69], v168 offset:46080
	ds_read_b64_tr_b16 v[70:71], v168 offset:46592
	s_waitcnt lgkmcnt(12)
	v_mfma_f32_32x32x16_bf16 v[48:63], v[160:163], v[152:155], v[48:63]
	v_add_f32_e32 v100, v110, v100
	v_add_f32_e32 v100, v111, v100
	v_add_f32_e32 v100, v80, v100
	v_add_f32_e32 v104, v81, v100
	v_cvt_pk_bf16_f32 v138, v108, v109
	v_cvt_pk_bf16_f32 v139, v110, v111
	ds_read_b64_tr_b16 v[100:101], v168 offset:43008
	ds_read_b64_tr_b16 v[102:103], v168 offset:43520
	v_add_f32_e32 v104, v82, v104
	v_add_f32_e32 v104, v83, v104
	v_add_f32_e32 v104, v84, v104
	v_add_f32_e32 v104, v85, v104
	v_cvt_pk_bf16_f32 v132, v80, v81
	v_cvt_pk_bf16_f32 v133, v82, v83
	s_waitcnt lgkmcnt(13)
	v_mfma_f32_32x32x16_bf16 v[112:127], v[72:75], v[148:151], v[112:127]
	ds_read_b64_tr_b16 v[72:73], v168 offset:47104
	ds_read_b64_tr_b16 v[74:75], v168 offset:47616
	s_waitcnt lgkmcnt(14)
	v_mfma_f32_32x32x16_bf16 v[48:63], v[164:167], v[148:151], v[48:63]
	v_add_f32_e32 v80, v86, v104
	v_add_f32_e32 v80, v87, v80
	v_add_f32_e32 v80, v88, v80
	v_add_f32_e32 v104, v89, v80
	v_cvt_pk_bf16_f32 v134, v84, v85
	v_cvt_pk_bf16_f32 v135, v86, v87
	ds_read_b64_tr_b16 v[80:81], v168 offset:44032
	ds_read_b64_tr_b16 v[82:83], v168 offset:44544
	v_add_f32_e32 v84, v90, v104
	v_add_f32_e32 v84, v91, v84
	v_add_f32_e32 v84, v92, v84
	v_add_f32_e32 v84, v93, v84
	v_cvt_pk_bf16_f32 v128, v88, v89
	v_cvt_pk_bf16_f32 v129, v90, v91
	s_waitcnt lgkmcnt(14)
	v_mfma_f32_32x32x16_bf16 v[112:127], v[76:79], v[144:147], v[112:127]
	ds_read_b64_tr_b16 v[76:77], v168 offset:48128
	ds_read_b64_tr_b16 v[78:79], v168 offset:48640
	v_mfma_f32_32x32x16_bf16 v[48:63], v[184:187], v[144:147], v[48:63]
	v_add_f32_e32 v84, v94, v84
	v_add_f32_e32 v84, v95, v84
	v_add_f32_e32 v84, 0, v84
	v_cvt_pk_bf16_f32 v130, v92, v93
	v_cvt_pk_bf16_f32 v131, v94, v95
	s_nop 0
	v_add_f32_e32 v175, v175, v84
	v_lshl_add_u64 v[84:85], v[172:173], 0, s[44:45]
	s_mov_b32 s29, m0
	s_mov_b32 m0, s17
	s_nop 0
	global_load_lds_dwordx4 v[84:85], off
	s_mov_b32 m0, s29
	v_lshl_add_u64 v[84:85], v[170:171], 0, s[48:49]
	s_add_i32 s17, s28, 0x8000
	s_mov_b32 s29, m0
	s_mov_b32 m0, s17
	s_nop 0
	global_load_lds_dwordx4 v[84:85], off
	s_mov_b32 m0, s29
	s_waitcnt lgkmcnt(14)
	v_mfma_f32_32x32x16_bf16 v[16:31], v[140:143], v[188:191], v[16:31]
	v_exp_f32_e32 v112, v112
	v_exp_f32_e32 v113, v113
	v_exp_f32_e32 v114, v114
	v_exp_f32_e32 v115, v115
	s_waitcnt lgkmcnt(12)
	v_mfma_f32_32x32x16_bf16 v[32:47], v[140:143], v[96:99], v[32:47]
	v_exp_f32_e32 v116, v116
	v_exp_f32_e32 v117, v117
	v_exp_f32_e32 v118, v118
	v_exp_f32_e32 v119, v119
	ds_read_b128 v[84:87], v234 offset:8192
	ds_read_b128 v[96:99], v234 offset:12288
	s_waitcnt lgkmcnt(12)
	v_mfma_f32_32x32x16_bf16 v[16:31], v[136:139], v[64:67], v[16:31]
	v_exp_f32_e32 v120, v120
	v_exp_f32_e32 v121, v121
	v_exp_f32_e32 v122, v122
	v_exp_f32_e32 v123, v123
	ds_read_b128 v[104:107], v235 offset:8192
	ds_read_b128 v[108:111], v235 offset:12288
	s_waitcnt lgkmcnt(12)
	v_mfma_f32_32x32x16_bf16 v[32:47], v[136:139], v[68:71], v[32:47]
	v_exp_f32_e32 v124, v124
	v_exp_f32_e32 v125, v125
	v_exp_f32_e32 v126, v126
	v_exp_f32_e32 v127, v127
	ds_read_b128 v[160:163], v236 offset:8192
	ds_read_b128 v[164:167], v236 offset:12288
	s_waitcnt lgkmcnt(12)
	v_mfma_f32_32x32x16_bf16 v[16:31], v[132:135], v[100:103], v[16:31]
	v_exp_f32_e32 v48, v48
	v_exp_f32_e32 v49, v49
	v_exp_f32_e32 v50, v50
	v_exp_f32_e32 v51, v51
	ds_read_b128 v[100:103], v237 offset:8192
	ds_read_b128 v[184:187], v237 offset:12288
	s_waitcnt lgkmcnt(12)
	v_mfma_f32_32x32x16_bf16 v[32:47], v[132:135], v[72:75], v[32:47]
	v_exp_f32_e32 v52, v52
	v_exp_f32_e32 v53, v53
	v_exp_f32_e32 v54, v54
	v_exp_f32_e32 v55, v55
	s_waitcnt lgkmcnt(10)
	v_mfma_f32_32x32x16_bf16 v[16:31], v[128:131], v[80:83], v[16:31]
	v_exp_f32_e32 v56, v56
	v_exp_f32_e32 v57, v57
	v_exp_f32_e32 v58, v58
	v_exp_f32_e32 v59, v59
	s_waitcnt lgkmcnt(8)
	v_mfma_f32_32x32x16_bf16 v[32:47], v[128:131], v[76:79], v[32:47]
	v_exp_f32_e32 v60, v60
	v_exp_f32_e32 v61, v61
	v_exp_f32_e32 v62, v62
	v_exp_f32_e32 v63, v63
	s_waitcnt vmcnt(2) lgkmcnt(0)
	s_barrier
;   #define RESC() do{ if(!NOMAX&&resc){ asm volatile("s_waitcnt lgkmcnt(0)":::"memory"); \
;       _Pragma("unroll") for(int d_=0;d_<2*VM;++d_) _Pragma("unroll") for(int r=0;r<16;++r)o[d_][r]*=wsf[crow(r,hi)]; } }while(0)
;   #define ROT() do{sl_prev=sl_cur;sl_cur=sl_next;sl_next=(sl_next==(NSLOT-1)*SLOTB)?0:sl_next+SLOTB;}while(0)
;   #define ENDW(tt) do{ if((tt)+3<NT){ if constexpr(VM==2){WAIT_BAR(3);}else{WAIT_BAR(2);} } else if((tt)+2<NT){ if constexpr(VM==2){WAIT_BAR(2);}else{WAIT_BAR(1);} } else {WAIT_BAR(0);} }while(0)
; template<int THRL,int VM,bool NOMAX> __device__ __forceinline__ void attn_unit(const bf16*Qb,const bf16*__restrict__ Kh,const bf16*__restrict__ Vh,bf16*Ob,const int NT,const int sp,float*wscr,char*shm){
;     ...
;     STEP(pB0,pB1,pA0,pA1,t,(t+3<NT),(t+1<NT),(t+1<NT));       ENDW(t);   RESC(); ROT();
;     STEP(pA0,pA1,pB0,pB1,t+1,(t+4<NT),(t+2<NT),(t+2<NT));     ENDW(t+1); RESC(); ROT();
	ds_read_b64_tr_b16 v[188:189], v168 offset:24576
	ds_read_b64_tr_b16 v[190:191], v168 offset:25088
	v_add_f32_e32 v64, v112, v113
	v_add_f32_e32 v64, v114, v64
	v_add_f32_e32 v64, v115, v64
	v_add_f32_e32 v64, v116, v64
	v_add_f32_e32 v64, v117, v64
	v_cvt_pk_bf16_f32 v140, v112, v113
	v_cvt_pk_bf16_f32 v141, v114, v115
	s_waitcnt lgkmcnt(9)
	v_mfma_f32_32x32x16_bf16 v[80:95], v[84:87], v[156:159], 0
	ds_read_b64_tr_b16 v[112:113], v168 offset:28672
	ds_read_b64_tr_b16 v[114:115], v168 offset:29184
	v_add_f32_e32 v64, v118, v64
	v_add_f32_e32 v64, v119, v64
	v_add_f32_e32 v64, v120, v64
	v_add_f32_e32 v128, v121, v64
	v_cvt_pk_bf16_f32 v142, v116, v117
	v_cvt_pk_bf16_f32 v143, v118, v119
	s_waitcnt lgkmcnt(10)
	v_mfma_f32_32x32x16_bf16 v[64:79], v[96:99], v[156:159], 0
	ds_read_b64_tr_b16 v[96:97], v168 offset:25600
	ds_read_b64_tr_b16 v[98:99], v168 offset:26112
	v_add_f32_e32 v116, v122, v128
	v_add_f32_e32 v116, v123, v116
	v_add_f32_e32 v116, v124, v116
	v_add_f32_e32 v116, v125, v116
	v_cvt_pk_bf16_f32 v136, v120, v121
	v_cvt_pk_bf16_f32 v137, v122, v123
	s_waitcnt lgkmcnt(11)
	v_mfma_f32_32x32x16_bf16 v[80:95], v[104:107], v[152:155], v[80:95]
	ds_read_b64_tr_b16 v[104:105], v168 offset:29696
	ds_read_b64_tr_b16 v[106:107], v168 offset:30208
	v_add_f32_e32 v116, v126, v116
	v_add_f32_e32 v116, v127, v116
	v_add_f32_e32 v116, v48, v116
	v_add_f32_e32 v116, v49, v116
	v_cvt_pk_bf16_f32 v138, v124, v125
	v_cvt_pk_bf16_f32 v139, v126, v127
	s_waitcnt lgkmcnt(12)
	v_mfma_f32_32x32x16_bf16 v[64:79], v[108:111], v[152:155], v[64:79]
	ds_read_b64_tr_b16 v[108:109], v168 offset:26624
	ds_read_b64_tr_b16 v[110:111], v168 offset:27136
	v_add_f32_e32 v116, v50, v116
	v_add_f32_e32 v116, v51, v116
	v_add_f32_e32 v116, v52, v116
	v_add_f32_e32 v116, v53, v116
	v_cvt_pk_bf16_f32 v132, v48, v49
	v_cvt_pk_bf16_f32 v133, v50, v51
	s_waitcnt lgkmcnt(13)
	v_mfma_f32_32x32x16_bf16 v[80:95], v[160:163], v[148:151], v[80:95]
	ds_read_b64_tr_b16 v[48:49], v168 offset:30720
	ds_read_b64_tr_b16 v[50:51], v168 offset:31232
	v_add_f32_e32 v116, v54, v116
	v_add_f32_e32 v116, v55, v116
	v_add_f32_e32 v116, v56, v116
	v_add_f32_e32 v116, v57, v116
	v_cvt_pk_bf16_f32 v134, v52, v53
	v_cvt_pk_bf16_f32 v135, v54, v55
	s_waitcnt lgkmcnt(14)
	v_mfma_f32_32x32x16_bf16 v[64:79], v[164:167], v[148:151], v[64:79]
	ds_read_b64_tr_b16 v[52:53], v168 offset:27648
	ds_read_b64_tr_b16 v[54:55], v168 offset:28160
	v_add_f32_e32 v116, v58, v116
	v_add_f32_e32 v116, v59, v116
	v_add_f32_e32 v116, v60, v116
	v_add_f32_e32 v116, v61, v116
	v_cvt_pk_bf16_f32 v128, v56, v57
	v_cvt_pk_bf16_f32 v129, v58, v59
	s_waitcnt lgkmcnt(14)
	v_mfma_f32_32x32x16_bf16 v[80:95], v[100:103], v[144:147], v[80:95]
	ds_read_b64_tr_b16 v[56:57], v168 offset:31744
	ds_read_b64_tr_b16 v[58:59], v168 offset:32256
	v_add_f32_e32 v100, v62, v116
	v_add_f32_e32 v100, v63, v100
	v_add_f32_e32 v100, 0, v100
	v_cvt_pk_bf16_f32 v130, v60, v61
	v_cvt_pk_bf16_f32 v131, v62, v63
	v_mfma_f32_32x32x16_bf16 v[64:79], v[184:187], v[144:147], v[64:79]
	v_lshl_add_u64 v[60:61], v[170:171], 0, s[40:41]
	s_add_i32 s28, s28, 0xa000
	s_mov_b32 s17, m0
	s_mov_b32 m0, s28
	s_nop 0
	global_load_lds_dwordx4 v[60:61], off
	s_mov_b32 m0, s17
	v_add_f32_e32 v172, v175, v100
	s_waitcnt lgkmcnt(14)
	v_mfma_f32_32x32x16_bf16 v[16:31], v[140:143], v[188:191], v[16:31]
	v_exp_f32_e32 v80, v80
	v_exp_f32_e32 v81, v81
	v_exp_f32_e32 v82, v82
	v_exp_f32_e32 v83, v83
	s_waitcnt lgkmcnt(12)
	v_mfma_f32_32x32x16_bf16 v[32:47], v[140:143], v[112:115], v[32:47]
	v_exp_f32_e32 v84, v84
	v_exp_f32_e32 v85, v85
	v_exp_f32_e32 v86, v86
	v_exp_f32_e32 v87, v87
	ds_read_b128 v[60:63], v234 offset:16384
	ds_read_b128 v[112:115], v234 offset:20480
	s_waitcnt lgkmcnt(12)
	v_mfma_f32_32x32x16_bf16 v[16:31], v[136:139], v[96:99], v[16:31]
	v_exp_f32_e32 v88, v88
	v_exp_f32_e32 v89, v89
	v_exp_f32_e32 v90, v90
	v_exp_f32_e32 v91, v91
	ds_read_b128 v[116:119], v235 offset:16384
	ds_read_b128 v[120:123], v235 offset:20480
	s_waitcnt lgkmcnt(12)
	v_mfma_f32_32x32x16_bf16 v[32:47], v[136:139], v[104:107], v[32:47]
	v_exp_f32_e32 v92, v92
	v_exp_f32_e32 v93, v93
	v_exp_f32_e32 v94, v94
	v_exp_f32_e32 v95, v95
	ds_read_b128 v[124:127], v236 offset:16384
	ds_read_b128 v[160:163], v236 offset:20480
	s_waitcnt lgkmcnt(12)
	v_mfma_f32_32x32x16_bf16 v[16:31], v[132:135], v[108:111], v[16:31]
	v_exp_f32_e32 v64, v64
	v_exp_f32_e32 v65, v65
	v_exp_f32_e32 v66, v66
	v_exp_f32_e32 v67, v67
	ds_read_b128 v[164:167], v237 offset:16384
	ds_read_b128 v[184:187], v237 offset:20480
	s_waitcnt lgkmcnt(12)
	v_mfma_f32_32x32x16_bf16 v[32:47], v[132:135], v[48:51], v[32:47]
	v_exp_f32_e32 v68, v68
	v_exp_f32_e32 v69, v69
	v_exp_f32_e32 v70, v70
	v_exp_f32_e32 v71, v71
	s_waitcnt lgkmcnt(10)
	v_mfma_f32_32x32x16_bf16 v[16:31], v[128:131], v[52:55], v[16:31]
	v_exp_f32_e32 v72, v72
	v_exp_f32_e32 v73, v73
	v_exp_f32_e32 v74, v74
	v_exp_f32_e32 v75, v75
	s_waitcnt lgkmcnt(8)
	v_mfma_f32_32x32x16_bf16 v[32:47], v[128:131], v[56:59], v[32:47]
	v_exp_f32_e32 v76, v76
	v_exp_f32_e32 v77, v77
	v_exp_f32_e32 v78, v78
	v_exp_f32_e32 v79, v79
	s_waitcnt vmcnt(1) lgkmcnt(0)
	s_barrier
;   #define RESC() do{ if(!NOMAX&&resc){ asm volatile("s_waitcnt lgkmcnt(0)":::"memory"); \
;       _Pragma("unroll") for(int d_=0;d_<2*VM;++d_) _Pragma("unroll") for(int r=0;r<16;++r)o[d_][r]*=wsf[crow(r,hi)]; } }while(0)
;   #define ROT() do{sl_prev=sl_cur;sl_cur=sl_next;sl_next=(sl_next==(NSLOT-1)*SLOTB)?0:sl_next+SLOTB;}while(0)
;   #define ENDW(tt) do{ if((tt)+3<NT){ if constexpr(VM==2){WAIT_BAR(3);}else{WAIT_BAR(2);} } else if((tt)+2<NT){ if constexpr(VM==2){WAIT_BAR(2);}else{WAIT_BAR(1);} } else {WAIT_BAR(0);} }while(0)
; template<int THRL,int VM,bool NOMAX> __device__ __forceinline__ void attn_unit(const bf16*Qb,const bf16*__restrict__ Kh,const bf16*__restrict__ Vh,bf16*Ob,const int NT,const int sp,float*wscr,char*shm){
;     ...
;     STEP(pA0,pA1,pB0,pB1,t+1,(t+4<NT),(t+2<NT),(t+2<NT));     ENDW(t+1); RESC(); ROT();
	ds_read_b64_tr_b16 v[188:189], v168 offset:32768
	ds_read_b64_tr_b16 v[190:191], v168 offset:33280
	v_add_f32_e32 v48, v80, v81
	v_add_f32_e32 v48, v82, v48
	v_add_f32_e32 v48, v83, v48
	v_add_f32_e32 v48, v84, v48
	v_add_f32_e32 v48, v85, v48
	v_cvt_pk_bf16_f32 v140, v80, v81
	v_cvt_pk_bf16_f32 v141, v82, v83
	s_waitcnt lgkmcnt(9)
	v_mfma_f32_32x32x16_bf16 v[96:111], v[60:63], v[156:159], 0
	ds_read_b64_tr_b16 v[80:81], v168 offset:36864
	ds_read_b64_tr_b16 v[82:83], v168 offset:37376
	v_add_f32_e32 v48, v86, v48
	v_add_f32_e32 v48, v87, v48
	v_add_f32_e32 v48, v88, v48
	v_add_f32_e32 v128, v89, v48
	s_waitcnt lgkmcnt(10)
	v_mfma_f32_32x32x16_bf16 v[48:63], v[112:115], v[156:159], 0
	v_cvt_pk_bf16_f32 v142, v84, v85
	v_cvt_pk_bf16_f32 v143, v86, v87
	ds_read_b64_tr_b16 v[84:85], v168 offset:33792
	ds_read_b64_tr_b16 v[86:87], v168 offset:34304
	v_add_f32_e32 v112, v90, v128
	v_add_f32_e32 v112, v91, v112
	v_add_f32_e32 v112, v92, v112
	v_add_f32_e32 v112, v93, v112
	v_cvt_pk_bf16_f32 v136, v88, v89
	v_cvt_pk_bf16_f32 v137, v90, v91
	s_waitcnt lgkmcnt(11)
	v_mfma_f32_32x32x16_bf16 v[96:111], v[116:119], v[152:155], v[96:111]
	ds_read_b64_tr_b16 v[88:89], v168 offset:37888
	ds_read_b64_tr_b16 v[90:91], v168 offset:38400
	s_waitcnt lgkmcnt(12)
	v_mfma_f32_32x32x16_bf16 v[48:63], v[120:123], v[152:155], v[48:63]
	v_add_f32_e32 v112, v94, v112
	v_add_f32_e32 v112, v95, v112
	v_add_f32_e32 v112, v64, v112
	v_add_f32_e32 v112, v65, v112
	v_cvt_pk_bf16_f32 v138, v92, v93
	v_cvt_pk_bf16_f32 v139, v94, v95
	ds_read_b64_tr_b16 v[92:93], v168 offset:34816
	ds_read_b64_tr_b16 v[94:95], v168 offset:35328
	v_add_f32_e32 v112, v66, v112
	v_add_f32_e32 v112, v67, v112
	v_add_f32_e32 v112, v68, v112
	v_add_f32_e32 v112, v69, v112
	v_cvt_pk_bf16_f32 v132, v64, v65
	v_cvt_pk_bf16_f32 v133, v66, v67
	s_waitcnt lgkmcnt(13)
	v_mfma_f32_32x32x16_bf16 v[96:111], v[124:127], v[148:151], v[96:111]
	ds_read_b64_tr_b16 v[64:65], v168 offset:38912
	ds_read_b64_tr_b16 v[66:67], v168 offset:39424
	s_waitcnt lgkmcnt(14)
	v_mfma_f32_32x32x16_bf16 v[48:63], v[160:163], v[148:151], v[48:63]
	v_add_f32_e32 v112, v70, v112
	v_add_f32_e32 v112, v71, v112
	v_add_f32_e32 v112, v72, v112
	v_add_f32_e32 v112, v73, v112
	v_cvt_pk_bf16_f32 v134, v68, v69
	v_cvt_pk_bf16_f32 v135, v70, v71
	ds_read_b64_tr_b16 v[68:69], v168 offset:35840
	ds_read_b64_tr_b16 v[70:71], v168 offset:36352
	v_add_f32_e32 v112, v74, v112
	v_add_f32_e32 v112, v75, v112
	v_add_f32_e32 v112, v76, v112
	v_add_f32_e32 v112, v77, v112
	v_cvt_pk_bf16_f32 v128, v72, v73
	v_cvt_pk_bf16_f32 v129, v74, v75
	s_waitcnt lgkmcnt(14)
	v_mfma_f32_32x32x16_bf16 v[96:111], v[164:167], v[144:147], v[96:111]
	ds_read_b64_tr_b16 v[72:73], v168 offset:39936
	ds_read_b64_tr_b16 v[74:75], v168 offset:40448
	v_mfma_f32_32x32x16_bf16 v[48:63], v[184:187], v[144:147], v[48:63]
	v_add_f32_e32 v112, v78, v112
	v_add_f32_e32 v112, v79, v112
	v_add_f32_e32 v112, 0, v112
	v_cvt_pk_bf16_f32 v130, v76, v77
	v_cvt_pk_bf16_f32 v131, v78, v79
	v_lshl_add_u64 v[76:77], v[170:171], 0, s[44:45]
	s_mov_b32 s17, m0
	s_mov_b32 m0, s16
	s_nop 0
	global_load_lds_dwordx4 v[76:77], off
	s_mov_b32 m0, s17
	v_add_f32_e32 v120, v172, v112
	s_waitcnt lgkmcnt(14)
	v_mfma_f32_32x32x16_bf16 v[16:31], v[140:143], v[188:191], v[16:31]
	v_exp_f32_e32 v96, v96
	v_exp_f32_e32 v97, v97
	v_exp_f32_e32 v98, v98
	v_exp_f32_e32 v99, v99
	s_waitcnt lgkmcnt(12)
	v_mfma_f32_32x32x16_bf16 v[32:47], v[140:143], v[80:83], v[32:47]
	v_exp_f32_e32 v100, v100
	v_exp_f32_e32 v101, v101
	v_exp_f32_e32 v102, v102
	v_exp_f32_e32 v103, v103
	ds_read_b128 v[76:79], v234
	ds_read_b128 v[80:83], v234 offset:4096
	s_waitcnt lgkmcnt(12)
	v_mfma_f32_32x32x16_bf16 v[16:31], v[136:139], v[84:87], v[16:31]
	v_exp_f32_e32 v104, v104
	v_exp_f32_e32 v105, v105
	v_exp_f32_e32 v106, v106
	v_exp_f32_e32 v107, v107
	ds_read_b128 v[122:125], v235
	ds_read_b128 v[160:163], v235 offset:4096
	s_waitcnt lgkmcnt(12)
	v_mfma_f32_32x32x16_bf16 v[32:47], v[136:139], v[88:91], v[32:47]
	v_exp_f32_e32 v108, v108
	v_exp_f32_e32 v109, v109
	v_exp_f32_e32 v110, v110
	v_exp_f32_e32 v111, v111
	ds_read_b128 v[164:167], v236
	ds_read_b128 v[170:173], v236 offset:4096
	s_waitcnt lgkmcnt(12)
	v_mfma_f32_32x32x16_bf16 v[16:31], v[132:135], v[92:95], v[16:31]
	v_exp_f32_e32 v48, v48
	v_exp_f32_e32 v49, v49
	v_exp_f32_e32 v50, v50
	v_exp_f32_e32 v51, v51
	ds_read_b128 v[184:187], v237
	ds_read_b128 v[188:191], v237 offset:4096
	s_waitcnt lgkmcnt(12)
	v_mfma_f32_32x32x16_bf16 v[32:47], v[132:135], v[64:67], v[32:47]
	v_exp_f32_e32 v52, v52
	v_exp_f32_e32 v53, v53
	v_exp_f32_e32 v54, v54
	v_exp_f32_e32 v55, v55
	s_waitcnt lgkmcnt(10)
	v_mfma_f32_32x32x16_bf16 v[16:31], v[128:131], v[68:71], v[16:31]
	v_exp_f32_e32 v56, v56
	v_exp_f32_e32 v57, v57
	v_exp_f32_e32 v58, v58
	v_exp_f32_e32 v59, v59
	s_waitcnt lgkmcnt(8)
	v_mfma_f32_32x32x16_bf16 v[32:47], v[128:131], v[72:75], v[32:47]
	v_exp_f32_e32 v60, v60
	v_exp_f32_e32 v61, v61
	v_exp_f32_e32 v62, v62
	v_exp_f32_e32 v63, v63
	s_waitcnt vmcnt(0) lgkmcnt(0)
	s_barrier
;   #define RESC() do{ if(!NOMAX&&resc){ asm volatile("s_waitcnt lgkmcnt(0)":::"memory"); \
;       _Pragma("unroll") for(int d_=0;d_<2*VM;++d_) _Pragma("unroll") for(int r=0;r<16;++r)o[d_][r]*=wsf[crow(r,hi)]; } }while(0)
; template<int THRL,int VM,bool NOMAX> __device__ __forceinline__ void attn_unit(const bf16*Qb,const bf16*__restrict__ Kh,const bf16*__restrict__ Vh,bf16*Ob,const int NT,const int sp,float*wscr,char*shm){
;     ...
;   STEP(pB0,pB1,pA0,pA1,NT-1,false,false,false); RESC();
	ds_read_b64_tr_b16 v[112:113], v168 offset:40960
	ds_read_b64_tr_b16 v[114:115], v168 offset:41472
	v_add_f32_e32 v64, v96, v97
	v_add_f32_e32 v64, v98, v64
	v_add_f32_e32 v64, v99, v64
	v_add_f32_e32 v64, v100, v64
	v_add_f32_e32 v84, v101, v64
	v_cvt_pk_bf16_f32 v140, v96, v97
	v_cvt_pk_bf16_f32 v141, v98, v99
	s_waitcnt lgkmcnt(9)
	v_mfma_f32_32x32x16_bf16 v[64:79], v[76:79], v[156:159], 0
	ds_read_b64_tr_b16 v[96:97], v168 offset:45056
	ds_read_b64_tr_b16 v[98:99], v168 offset:45568
	v_add_f32_e32 v84, v102, v84
	v_add_f32_e32 v84, v103, v84
	v_add_f32_e32 v84, v104, v84
	v_add_f32_e32 v121, v105, v84
	v_cvt_pk_bf16_f32 v142, v100, v101
	v_cvt_pk_bf16_f32 v143, v102, v103
	s_waitcnt lgkmcnt(10)
	v_mfma_f32_32x32x16_bf16 v[80:95], v[80:83], v[156:159], 0
	ds_read_b64_tr_b16 v[116:117], v168 offset:41984
	ds_read_b64_tr_b16 v[118:119], v168 offset:42496
	v_add_f32_e32 v100, v106, v121
	v_add_f32_e32 v100, v107, v100
	v_add_f32_e32 v100, v108, v100
	v_add_f32_e32 v121, v109, v100
	v_cvt_pk_bf16_f32 v136, v104, v105
	v_cvt_pk_bf16_f32 v137, v106, v107
	s_waitcnt lgkmcnt(11)
	v_mfma_f32_32x32x16_bf16 v[64:79], v[122:125], v[152:155], v[64:79]
	ds_read_b64_tr_b16 v[100:101], v168 offset:46080
	ds_read_b64_tr_b16 v[102:103], v168 offset:46592
	v_add_f32_e32 v104, v110, v121
	v_add_f32_e32 v104, v111, v104
	v_add_f32_e32 v104, v48, v104
	v_add_f32_e32 v121, v49, v104
	v_cvt_pk_bf16_f32 v138, v108, v109
	v_cvt_pk_bf16_f32 v139, v110, v111
	s_waitcnt lgkmcnt(12)
	v_mfma_f32_32x32x16_bf16 v[80:95], v[160:163], v[152:155], v[80:95]
	ds_read_b64_tr_b16 v[104:105], v168 offset:43008
	ds_read_b64_tr_b16 v[106:107], v168 offset:43520
	v_add_f32_e32 v108, v50, v121
	v_add_f32_e32 v108, v51, v108
	v_add_f32_e32 v108, v52, v108
	v_add_f32_e32 v108, v53, v108
	v_cvt_pk_bf16_f32 v132, v48, v49
	v_cvt_pk_bf16_f32 v133, v50, v51
	s_waitcnt lgkmcnt(13)
	v_mfma_f32_32x32x16_bf16 v[64:79], v[164:167], v[148:151], v[64:79]
	ds_read_b64_tr_b16 v[48:49], v168 offset:47104
	ds_read_b64_tr_b16 v[50:51], v168 offset:47616
	v_add_f32_e32 v108, v54, v108
	v_add_f32_e32 v108, v55, v108
	v_add_f32_e32 v108, v56, v108
	v_add_f32_e32 v121, v57, v108
	v_cvt_pk_bf16_f32 v134, v52, v53
	v_cvt_pk_bf16_f32 v135, v54, v55
	s_waitcnt lgkmcnt(14)
	v_mfma_f32_32x32x16_bf16 v[80:95], v[170:173], v[148:151], v[80:95]
	ds_read_b64_tr_b16 v[108:109], v168 offset:44032
	ds_read_b64_tr_b16 v[110:111], v168 offset:44544
	v_add_f32_e32 v52, v58, v121
	v_add_f32_e32 v52, v59, v52
	v_add_f32_e32 v52, v60, v52
	v_add_f32_e32 v121, v61, v52
	v_cvt_pk_bf16_f32 v128, v56, v57
	v_cvt_pk_bf16_f32 v129, v58, v59
	s_waitcnt lgkmcnt(14)
	v_mfma_f32_32x32x16_bf16 v[64:79], v[184:187], v[144:147], v[64:79]
	ds_read_b64_tr_b16 v[52:53], v168 offset:48128
	ds_read_b64_tr_b16 v[54:55], v168 offset:48640
	v_add_f32_e32 v56, v62, v121
	v_add_f32_e32 v56, v63, v56
	v_add_f32_e32 v56, 0, v56
	v_cvt_pk_bf16_f32 v130, v60, v61
	v_cvt_pk_bf16_f32 v131, v62, v63
	v_mfma_f32_32x32x16_bf16 v[80:95], v[188:191], v[144:147], v[80:95]
	s_nop 3
	v_exp_f32_e32 v64, v64
	v_exp_f32_e32 v65, v65
	v_exp_f32_e32 v66, v66
	v_exp_f32_e32 v67, v67
	s_nop 0
	v_exp_f32_e32 v68, v68
	v_exp_f32_e32 v69, v69
	v_exp_f32_e32 v70, v70
	v_exp_f32_e32 v71, v71
	s_nop 0
	v_exp_f32_e32 v72, v72
	v_exp_f32_e32 v73, v73
	v_exp_f32_e32 v74, v74
	v_exp_f32_e32 v75, v75
	s_nop 0
	v_exp_f32_e32 v76, v76
	v_exp_f32_e32 v77, v77
	v_exp_f32_e32 v78, v78
	v_exp_f32_e32 v79, v79
	v_exp_f32_e32 v80, v80
	v_exp_f32_e32 v81, v81
	v_exp_f32_e32 v82, v82
	v_exp_f32_e32 v83, v83
	s_nop 0
	v_exp_f32_e32 v84, v84
	v_exp_f32_e32 v85, v85
	v_exp_f32_e32 v86, v86
	v_exp_f32_e32 v87, v87
	s_nop 0
	v_exp_f32_e32 v88, v88
	v_exp_f32_e32 v89, v89
	v_exp_f32_e32 v90, v90
	v_exp_f32_e32 v91, v91
	s_nop 0
	v_exp_f32_e32 v92, v92
	v_exp_f32_e32 v93, v93
	v_exp_f32_e32 v94, v94
	v_exp_f32_e32 v95, v95
	s_waitcnt lgkmcnt(14)
; #define SBAR() __builtin_amdgcn_sched_barrier(0)
;   #define PKW(P,B) cvtpk_s(P[B],P[B+1])
; __device__ __forceinline__ void pv(f32x16*o,int vb,bf16x8 pa0,bf16x8 pa1,bf16x8 pa2,bf16x8 pa3){
;   #pragma unroll
;   for(int d0=0;d0<2;++d0){s16x4 lo[4],hi[4];
;     #pragma unroll
;     for(int ks=0;ks<4;++ks){
;       asm volatile("ds_read_b64_tr_b16 %0,%1 offset:%c2":"=&v"(lo[ks]):"v"(vb),"i"(d0*4096+ks*1024):"memory");
;       asm volatile("ds_read_b64_tr_b16 %0,%1 offset:%c2":"=&v"(hi[ks]):"v"(vb),"i"(d0*4096+ks*1024+512):"memory");}
;     asm volatile("s_waitcnt lgkmcnt(0)":::"memory");SBAR();
;     ...
;     o[d0]=__builtin_amdgcn_mfma_f32_32x32x16_bf16(pa0,PK(0),o[d0],0,0,0);
;     o[d0]=__builtin_amdgcn_mfma_f32_32x32x16_bf16(pa1,PK(1),o[d0],0,0,0);
;     o[d0]=__builtin_amdgcn_mfma_f32_32x32x16_bf16(pa2,PK(2),o[d0],0,0,0);
;     o[d0]=__builtin_amdgcn_mfma_f32_32x32x16_bf16(pa3,PK(3),o[d0],0,0,0);
;     ...
;   }
; }
; template<int THRL,int VM,bool NOMAX> __device__ __forceinline__ void attn_unit(const bf16*Qb,const bf16*__restrict__ Kh,const bf16*__restrict__ Vh,bf16*Ob,const int NT,const int sp,float*wscr,char*shm){
;     ...
;   { float sacc=pB0[0]+pB0[1]; _Pragma("unroll") for(int r=2;r<16;++r)sacc+=pB0[r]; _Pragma("unroll") for(int r=0;r<16;++r)sacc+=pB1[r]; l_reg+=sacc;
;     pw0=(u32x4){PKW(pB0,0),PKW(pB0,2),PKW(pB0,4),PKW(pB0,6)};pw1=(u32x4){PKW(pB0,8),PKW(pB0,10),PKW(pB0,12),PKW(pB0,14)};pw2=(u32x4){PKW(pB1,0),PKW(pB1,2),PKW(pB1,4),PKW(pB1,6)};pw3=(u32x4){PKW(pB1,8),PKW(pB1,10),PKW(pB1,12),PKW(pB1,14)};
;     SBAR(); pv(o,vb0+VM*sl_cur,PAF(0),PAF(1),PAF(2),PAF(3)); if constexpr(VM==2) pv(o+2,vb0+VM*sl_cur+8192,PAF(0),PAF(1),PAF(2),PAF(3)); }
;     ...
;   {auto rr=__builtin_amdgcn_permlane32_swap(__float_as_uint(l_reg),__float_as_uint(l_reg),false,false);l_reg=__uint_as_float(rr[0])+__uint_as_float(rr[1]);}
;   if(hi==0)wsf[32+r32]=l_reg;asm volatile("s_waitcnt lgkmcnt(0)":::"memory");
	v_mfma_f32_32x32x16_bf16 v[16:31], v[140:143], v[112:115], v[16:31]
	v_add_f32_e32 v57, v64, v65
	v_add_f32_e32 v57, v66, v57
	v_add_f32_e32 v57, v67, v57
	v_add_f32_e32 v57, v68, v57
	v_add_f32_e32 v57, v69, v57
	v_add_f32_e32 v57, v70, v57
	v_add_f32_e32 v57, v71, v57
	s_waitcnt lgkmcnt(12)
	v_mfma_f32_32x32x16_bf16 v[32:47], v[140:143], v[96:99], v[32:47]
	v_add_f32_e32 v57, v72, v57
	v_add_f32_e32 v57, v73, v57
	v_add_f32_e32 v57, v74, v57
	v_add_f32_e32 v57, v75, v57
	v_add_f32_e32 v57, v76, v57
	v_add_f32_e32 v57, v77, v57
	v_add_f32_e32 v57, v78, v57
	s_waitcnt lgkmcnt(10)
	v_mfma_f32_32x32x16_bf16 v[16:31], v[136:139], v[116:119], v[16:31]
	v_add_f32_e32 v57, v79, v57
	v_add_f32_e32 v57, v80, v57
	v_add_f32_e32 v57, v81, v57
	v_add_f32_e32 v57, v82, v57
	v_add_f32_e32 v57, v83, v57
	v_add_f32_e32 v57, v84, v57
	v_add_f32_e32 v57, v85, v57
	s_waitcnt lgkmcnt(8)
	v_mfma_f32_32x32x16_bf16 v[32:47], v[136:139], v[100:103], v[32:47]
	v_add_f32_e32 v57, v86, v57
	v_add_f32_e32 v57, v87, v57
	v_add_f32_e32 v57, v88, v57
	v_add_f32_e32 v57, v89, v57
	v_add_f32_e32 v57, v90, v57
	v_add_f32_e32 v57, v91, v57
	v_add_f32_e32 v57, v92, v57
	s_waitcnt lgkmcnt(6)
	v_mfma_f32_32x32x16_bf16 v[16:31], v[132:135], v[104:107], v[16:31]
	v_add_f32_e32 v57, v93, v57
	v_add_f32_e32 v57, v94, v57
	v_add_f32_e32 v57, v95, v57
	v_add_f32_e32 v56, v120, v56
	v_add_f32_e32 v56, v56, v57
	v_cvt_pk_bf16_f32 v58, v64, v65
	v_cvt_pk_bf16_f32 v59, v66, v67
	s_waitcnt lgkmcnt(4)
	v_mfma_f32_32x32x16_bf16 v[32:47], v[132:135], v[48:51], v[32:47]
	v_cvt_pk_bf16_f32 v48, v80, v81
	v_cvt_pk_bf16_f32 v60, v68, v69
	v_cvt_pk_bf16_f32 v61, v70, v71
	v_cvt_pk_bf16_f32 v62, v72, v73
	v_cvt_pk_bf16_f32 v63, v74, v75
	v_cvt_pk_bf16_f32 v64, v76, v77
	v_cvt_pk_bf16_f32 v65, v78, v79
	s_waitcnt lgkmcnt(2)
	v_mfma_f32_32x32x16_bf16 v[16:31], v[128:131], v[108:111], v[16:31]
	v_cvt_pk_bf16_f32 v49, v82, v83
	v_cvt_pk_bf16_f32 v50, v84, v85
	v_cvt_pk_bf16_f32 v51, v86, v87
	v_cvt_pk_bf16_f32 v66, v88, v89
	v_cvt_pk_bf16_f32 v67, v90, v91
	v_cvt_pk_bf16_f32 v68, v92, v93
	v_cvt_pk_bf16_f32 v69, v94, v95
	s_waitcnt lgkmcnt(0)
	v_mfma_f32_32x32x16_bf16 v[32:47], v[128:131], v[52:55], v[32:47]
	ds_read_b64_tr_b16 v[52:53],v174 offset:0
	ds_read_b64_tr_b16 v[54:55],v174 offset:512
	ds_read_b64_tr_b16 v[70:71],v174 offset:1024
	ds_read_b64_tr_b16 v[72:73],v174 offset:1536
	ds_read_b64_tr_b16 v[74:75],v174 offset:2048
	ds_read_b64_tr_b16 v[76:77],v174 offset:2560
	ds_read_b64_tr_b16 v[78:79],v174 offset:3072
	ds_read_b64_tr_b16 v[80:81],v174 offset:3584
	s_waitcnt lgkmcnt(0)
	s_nop 0
	v_mfma_f32_32x32x16_bf16 v[16:31], v[58:61], v[52:55], v[16:31]
	ds_read_b64_tr_b16 v[52:53],v174 offset:4096
	ds_read_b64_tr_b16 v[54:55],v174 offset:4608
	v_mfma_f32_32x32x16_bf16 v[16:31], v[62:65], v[70:73], v[16:31]
	ds_read_b64_tr_b16 v[70:71],v174 offset:5120
	ds_read_b64_tr_b16 v[72:73],v174 offset:5632
	v_mfma_f32_32x32x16_bf16 v[16:31], v[48:51], v[74:77], v[16:31]
	ds_read_b64_tr_b16 v[74:75],v174 offset:6144
	ds_read_b64_tr_b16 v[76:77],v174 offset:6656
	ds_read_b64_tr_b16 v[82:83],v174 offset:7168
	ds_read_b64_tr_b16 v[84:85],v174 offset:7680
	s_waitcnt lgkmcnt(0)
	v_mfma_f32_32x32x16_bf16 v[16:31], v[66:69], v[78:81], v[16:31]
	v_mfma_f32_32x32x16_bf16 v[32:47], v[58:61], v[52:55], v[32:47]
	v_cmp_gt_u32_e32 vcc, 32, v178
	v_mfma_f32_32x32x16_bf16 v[32:47], v[62:65], v[70:73], v[32:47]
	v_mfma_f32_32x32x16_bf16 v[32:47], v[48:51], v[74:77], v[32:47]
	v_mov_b32_e32 v48, v56
	s_nop 1
	v_permlane32_swap_b32_e32 v56, v48
	v_mfma_f32_32x32x16_bf16 v[32:47], v[66:69], v[82:85], v[32:47]
	s_and_saveexec_b64 s[16:17], vcc
	s_cbranch_execz .LBB0_887
	v_add_f32_e32 v48, v56, v48
	v_lshl_add_u32 v49, v180, 2, s19
	ds_write_b32 v49, v48 offset:49280
	s_branch .LBB0_887
